# widen norm-tail dwordx2 write-through stores to dwordx4 via DPP lane-pair exchange (section 7.3 lever), bit-identical
# speedup vs baseline: 1.0008x; 1.0008x over previous
.LBB0_793:
	s_lshl_b64 s[18:19], s[38:39], 12
	s_add_u32 s18, s36, s18
	s_addc_u32 s19, s37, s19
	s_lshl_b64 s[0:1], s[0:1], 12
	s_add_u32 s0, s6, s0
	s_addc_u32 s1, s7, s1
	s_lshl_b64 s[6:7], s[8:9], 12
	s_add_u32 s6, s40, s6
	s_addc_u32 s7, s41, s7
	v_lshl_add_u64 v[66:67], v[48:49], 3, s[6:7]
	v_lshl_add_u64 v[68:69], v[64:65], 0, s[88:89]
	s_mov_b32 s6, 0xda00000
	v_add_co_u32_e32 v70, vcc, s6, v68
	s_mov_b32 s6, 0xdb80000
	s_nop 0
	v_addc_co_u32_e32 v71, vcc, 0, v69, vcc
	v_add_co_u32_e32 v72, vcc, s6, v68
	s_mov_b32 s6, 0xdd00000
	s_nop 0
	v_addc_co_u32_e32 v73, vcc, 0, v69, vcc
	v_lshl_add_u64 v[32:33], s[18:19], 0, v[50:51]
	v_add_co_u32_e32 v74, vcc, s6, v68
	global_load_dwordx4 v[44:47], v[32:33], off
	global_load_dwordx4 v[40:43], v[32:33], off offset:1024
	global_load_dwordx4 v[36:39], v[32:33], off offset:2048
	s_nop 0
	global_load_dwordx4 v[32:35], v[32:33], off offset:3072
	s_nop 0
	global_load_dwordx2 v[84:85], v[70:71], off
	global_load_dwordx2 v[96:97], v[70:71], off offset:512
	global_load_dwordx2 v[82:83], v[70:71], off offset:1024
	global_load_dwordx2 v[76:77], v[70:71], off offset:1536
	v_addc_co_u32_e32 v75, vcc, 0, v69, vcc
	s_mov_b32 s6, 0xde80000
	global_load_dwordx2 v[92:93], v[72:73], off
	global_load_dwordx2 v[100:101], v[72:73], off offset:512
	global_load_dwordx2 v[88:89], v[72:73], off offset:1024
	global_load_dwordx2 v[78:79], v[72:73], off offset:1536
	v_add_co_u32_e32 v68, vcc, s6, v68
	global_load_dwordx2 v[106:107], v[74:75], off
	global_load_dwordx2 v[108:109], v[74:75], off offset:512
	global_load_dwordx2 v[90:91], v[74:75], off offset:1024
	global_load_dwordx2 v[80:81], v[74:75], off offset:1536
	v_addc_co_u32_e32 v69, vcc, 0, v69, vcc
	global_load_dwordx2 v[110:111], v[68:69], off
	global_load_dwordx2 v[112:113], v[68:69], off offset:512
	global_load_dwordx2 v[98:99], v[68:69], off offset:1024
	global_load_dwordx2 v[94:95], v[68:69], off offset:1536
	s_waitcnt vmcnt(15)
	v_lshlrev_b32_e32 v86, 16, v84
	v_and_b32_e32 v87, 0xffff0000, v84
	v_lshlrev_b32_e32 v84, 16, v85
	v_and_b32_e32 v85, 0xffff0000, v85
	s_waitcnt vmcnt(11)
	v_lshlrev_b32_e32 v114, 16, v92
	v_and_b32_e32 v115, 0xffff0000, v92
	v_pk_add_f32 v[84:85], v[84:85], 0 op_sel_hi:[1,0]
	v_lshlrev_b32_e32 v92, 16, v93
	v_and_b32_e32 v93, 0xffff0000, v93
	v_pk_add_f32 v[84:85], v[84:85], v[92:93]
	s_waitcnt vmcnt(7)
	v_lshlrev_b32_e32 v92, 16, v107
	v_and_b32_e32 v93, 0xffff0000, v107
	v_pk_add_f32 v[84:85], v[84:85], v[92:93]
	s_waitcnt vmcnt(3)
	v_lshlrev_b32_e32 v92, 16, v111
	v_and_b32_e32 v93, 0xffff0000, v111
	v_pk_add_f32 v[86:87], v[86:87], 0 op_sel_hi:[1,0]
	v_pk_add_f32 v[92:93], v[84:85], v[92:93]
	v_lshlrev_b32_e32 v84, 16, v96
	v_and_b32_e32 v85, 0xffff0000, v96
	v_lshlrev_b32_e32 v96, 16, v97
	v_and_b32_e32 v97, 0xffff0000, v97
	v_pk_add_f32 v[86:87], v[86:87], v[114:115]
	v_lshlrev_b32_e32 v114, 16, v106
	v_and_b32_e32 v115, 0xffff0000, v106
	v_lshlrev_b32_e32 v106, 16, v100
	v_and_b32_e32 v107, 0xffff0000, v100
	v_pk_add_f32 v[96:97], v[96:97], 0 op_sel_hi:[1,0]
	v_lshlrev_b32_e32 v100, 16, v101
	v_and_b32_e32 v101, 0xffff0000, v101
	v_pk_add_f32 v[84:85], v[84:85], 0 op_sel_hi:[1,0]
	v_pk_add_f32 v[96:97], v[96:97], v[100:101]
	v_lshlrev_b32_e32 v100, 16, v109
	v_and_b32_e32 v101, 0xffff0000, v109
	v_pk_add_f32 v[84:85], v[84:85], v[106:107]
	v_lshlrev_b32_e32 v106, 16, v108
	v_and_b32_e32 v107, 0xffff0000, v108
	v_pk_add_f32 v[96:97], v[96:97], v[100:101]
	s_waitcnt vmcnt(2)
	v_lshlrev_b32_e32 v100, 16, v113
	v_and_b32_e32 v101, 0xffff0000, v113
	v_pk_add_f32 v[84:85], v[84:85], v[106:107]
	v_lshlrev_b32_e32 v106, 16, v112
	v_and_b32_e32 v107, 0xffff0000, v112
	v_pk_add_f32 v[100:101], v[96:97], v[100:101]
	v_lshlrev_b32_e32 v96, 16, v82
	v_and_b32_e32 v97, 0xffff0000, v82
	v_lshlrev_b32_e32 v82, 16, v83
	v_and_b32_e32 v83, 0xffff0000, v83
	v_pk_add_f32 v[84:85], v[84:85], v[106:107]
	v_lshlrev_b32_e32 v106, 16, v88
	v_and_b32_e32 v107, 0xffff0000, v88
	v_pk_add_f32 v[82:83], v[82:83], 0 op_sel_hi:[1,0]
	v_lshlrev_b32_e32 v88, 16, v89
	v_and_b32_e32 v89, 0xffff0000, v89
	v_pk_add_f32 v[82:83], v[82:83], v[88:89]
	v_lshlrev_b32_e32 v88, 16, v91
	v_and_b32_e32 v89, 0xffff0000, v91
	v_pk_add_f32 v[82:83], v[82:83], v[88:89]
	s_waitcnt vmcnt(1)
	v_lshlrev_b32_e32 v88, 16, v99
	v_and_b32_e32 v89, 0xffff0000, v99
	v_pk_add_f32 v[96:97], v[96:97], 0 op_sel_hi:[1,0]
	v_pk_add_f32 v[88:89], v[82:83], v[88:89]
	v_lshlrev_b32_e32 v82, 16, v76
	v_and_b32_e32 v83, 0xffff0000, v76
	v_lshlrev_b32_e32 v76, 16, v77
	v_and_b32_e32 v77, 0xffff0000, v77
	v_pk_add_f32 v[86:87], v[86:87], v[114:115]
	v_lshlrev_b32_e32 v114, 16, v110
	v_and_b32_e32 v115, 0xffff0000, v110
	v_pk_add_f32 v[96:97], v[96:97], v[106:107]
	v_lshlrev_b32_e32 v106, 16, v90
	v_and_b32_e32 v107, 0xffff0000, v90
	v_pk_add_f32 v[82:83], v[82:83], 0 op_sel_hi:[1,0]
	v_lshlrev_b32_e32 v90, 16, v78
	v_and_b32_e32 v91, 0xffff0000, v78
	v_pk_add_f32 v[76:77], v[76:77], 0 op_sel_hi:[1,0]
	v_lshlrev_b32_e32 v78, 16, v79
	v_and_b32_e32 v79, 0xffff0000, v79
	v_pk_add_f32 v[86:87], v[86:87], v[114:115]
	v_pk_add_f32 v[82:83], v[82:83], v[90:91]
	v_lshlrev_b32_e32 v90, 16, v80
	v_and_b32_e32 v91, 0xffff0000, v80
	v_pk_add_f32 v[76:77], v[76:77], v[78:79]
	v_lshlrev_b32_e32 v78, 16, v81
	v_and_b32_e32 v79, 0xffff0000, v81
	v_pk_add_f32 v[96:97], v[96:97], v[106:107]
	v_lshlrev_b32_e32 v106, 16, v98
	v_and_b32_e32 v107, 0xffff0000, v98
	v_pk_add_f32 v[82:83], v[82:83], v[90:91]
	s_waitcnt vmcnt(0)
	v_lshlrev_b32_e32 v90, 16, v94
	v_and_b32_e32 v91, 0xffff0000, v94
	v_pk_add_f32 v[76:77], v[76:77], v[78:79]
	v_lshlrev_b32_e32 v78, 16, v95
	v_and_b32_e32 v79, 0xffff0000, v95
	v_mov_b32_e32 v80, v87
	v_mov_b32_e32 v81, v93
	v_pk_add_f32 v[96:97], v[96:97], v[106:107]
	v_pk_add_f32 v[82:83], v[82:83], v[90:91]
	v_pk_add_f32 v[76:77], v[76:77], v[78:79]
	v_mov_b32_e32 v78, v86
	v_mov_b32_e32 v79, v92
	v_pk_mul_f32 v[80:81], v[80:81], v[80:81]
	v_mov_b32_e32 v90, v85
	v_mov_b32_e32 v91, v101
	v_pk_fma_f32 v[78:79], v[78:79], v[78:79], v[80:81]
	v_mov_b32_e32 v80, v84
	v_mov_b32_e32 v81, v100
	v_pk_mul_f32 v[90:91], v[90:91], v[90:91]
	v_mul_f32_e32 v60, v97, v97
	v_pk_fma_f32 v[80:81], v[80:81], v[80:81], v[90:91]
	v_pk_fma_f32 v[90:91], v[96:97], v[96:97], v[60:61] op_sel_hi:[1,1,0]
	v_mul_f32_e32 v60, v89, v89
	v_pk_add_f32 v[78:79], v[78:79], v[78:79] op_sel:[0,1] op_sel_hi:[1,0]
	v_pk_add_f32 v[80:81], v[80:81], v[80:81] op_sel:[0,1] op_sel_hi:[1,0]
	v_pk_fma_f32 v[94:95], v[88:89], v[88:89], v[60:61] op_sel_hi:[1,1,0]
	v_pk_mul_f32 v[98:99], v[82:83], v[82:83]
	v_pk_mul_f32 v[106:107], v[76:77], v[76:77]
	v_mov_b32_e32 v79, v98
	v_mov_b32_e32 v81, v99
	v_mov_b32_e32 v91, v106
	v_mov_b32_e32 v95, v107
	v_pk_add_f32 v[78:79], v[78:79], v[80:81]
	v_pk_add_f32 v[80:81], v[90:91], v[94:95]
	s_nop 0
	v_pk_add_f32 v[78:79], v[78:79], v[80:81]
	s_nop 0
	v_add_f32_e32 v60, v78, v79
	s_nop 1
	v_mov_b32_dpp v78, v60 quad_perm:[1,0,3,2] row_mask:0xf bank_mask:0xf
	s_waitcnt lgkmcnt(0)
	v_add_f32_e32 v60, v60, v78
	s_nop 1
	v_mov_b32_dpp v78, v60 quad_perm:[2,3,0,1] row_mask:0xf bank_mask:0xf
	s_waitcnt lgkmcnt(0)
	v_add_f32_e32 v60, v60, v78
	s_nop 1
	v_mov_b32_dpp v78, v60 row_half_mirror row_mask:0xf bank_mask:0xf
	s_waitcnt lgkmcnt(0)
	v_add_f32_e32 v60, v60, v78
	s_nop 1
	v_mov_b32_dpp v78, v60 row_mirror row_mask:0xf bank_mask:0xf
	s_waitcnt lgkmcnt(0)
	v_add_f32_e32 v60, v60, v78
	v_mov_b32_e32 v78, v60
	s_nop 1
	v_permlane16_swap_b32 v60, v78
	s_waitcnt lgkmcnt(0)
	v_add_f32_e32 v60, v60, v78
	v_mov_b32_e32 v78, v60
	s_nop 1
	v_permlane32_swap_b32 v60, v78
	s_waitcnt lgkmcnt(0)
	v_add_f32_e32 v60, v60, v78
	v_fmamk_f32 v60, v60, 0x3a800000, v102
	v_cmp_gt_f32_e32 vcc, s84, v60
	v_mul_f32_e32 v78, 0x4b800000, v60
	s_nop 0
	v_cndmask_b32_e32 v60, v60, v78, vcc
	v_rsq_f32_e32 v60, v60
	s_nop 0
	v_mul_f32_e32 v78, 0x45800000, v60
	v_cndmask_b32_e32 v78, v60, v78, vcc
	v_pk_mul_f32 v[80:81], v[92:93], v[78:79] op_sel_hi:[1,0]
	v_pk_mul_f32 v[86:87], v[86:87], v[78:79] op_sel_hi:[1,0]
	v_pk_fma_f32 v[46:47], v[2:3], v[80:81], v[46:47]
	v_pk_fma_f32 v[44:45], v[0:1], v[86:87], v[44:45]
	s_and_b64 vcc, exec, s[10:11]
	s_cbranch_vccnz .LBB0_819
	v_lshl_add_u64 v[80:81], v[66:67], 0, s[70:71]
	v_cvt_pk_bf16_f32 v86, v44, v45
	v_cvt_pk_bf16_f32 v87, v46, v47
	s_nop 0
	v_mov_b32_e32 v208, v86
	v_mov_b32_e32 v209, v87
	s_nop 1
	v_lshl_add_u64 v[80:81], s[0:1], 0, v[50:51]
	s_cbranch_execnz .LBB0_796

.LBB0_796:
	v_mov_b32_e32 v79, v78
	v_mov_b32_e32 v86, v78
	v_mov_b32_e32 v87, v78
	v_pk_mul_f32 v[84:85], v[84:85], v[78:79]
	v_pk_mul_f32 v[86:87], v[100:101], v[86:87]
	s_and_b64 vcc, exec, s[10:11]
	v_pk_fma_f32 v[42:43], v[14:15], v[86:87], v[42:43]
	v_pk_fma_f32 v[40:41], v[12:13], v[84:85], v[40:41]
	s_cbranch_vccnz .LBB0_820
	v_cvt_pk_bf16_f32 v84, v40, v41
	v_cvt_pk_bf16_f32 v85, v42, v43
	v_lshl_add_u64 v[86:87], v[66:67], 0, s[72:73]
	v_mov_b32_e32 v210, v84
	v_mov_b32_e32 v211, v85
	s_nop 1
	s_cbranch_execnz .LBB0_799

.LBB0_799:
	v_mov_b32_e32 v86, v78
	v_mov_b32_e32 v87, v78
	v_pk_mul_f32 v[84:85], v[96:97], v[78:79]
	v_pk_mul_f32 v[86:87], v[88:89], v[86:87]
	s_and_b64 vcc, exec, s[10:11]
	v_pk_fma_f32 v[38:39], v[18:19], v[86:87], v[38:39]
	v_pk_fma_f32 v[36:37], v[16:17], v[84:85], v[36:37]
	s_cbranch_vccnz .LBB0_821
	v_cvt_pk_bf16_f32 v84, v36, v37
	v_cvt_pk_bf16_f32 v85, v38, v39
	v_lshl_add_u64 v[86:87], v[66:67], 0, s[74:75]
	v_mov_b32_e32 v212, v84
	v_mov_b32_e32 v213, v85
	s_nop 1
	s_cbranch_execnz .LBB0_802

.LBB0_802:
	v_pk_mul_f32 v[82:83], v[82:83], v[78:79]
	v_mov_b32_e32 v79, v78
	v_pk_mul_f32 v[76:77], v[76:77], v[78:79]
	s_and_b64 vcc, exec, s[10:11]
	v_pk_fma_f32 v[34:35], v[30:31], v[76:77], v[34:35]
	v_pk_fma_f32 v[32:33], v[28:29], v[82:83], v[32:33]
	s_cbranch_vccnz .LBB0_822
	v_cvt_pk_bf16_f32 v76, v32, v33
	v_cvt_pk_bf16_f32 v77, v34, v35
	v_lshl_add_u64 v[66:67], v[66:67], 0, s[78:79]
	v_and_b32_e32 v232, 1, v152
	v_cmp_eq_u32_e64 s[98:99], 1, v232
	v_mul_u32_u24_e32 v230, 0x1f8, v232
	v_mov_b32_e32 v231, 0
	v_lshl_add_u64 v[228:229], v[66:67], 0, v[230:231]
	v_cndmask_b32_e64 v216, v210, v208, s[98:99]
	v_cndmask_b32_e64 v217, v211, v209, s[98:99]
	s_nop 1
	v_mov_b32_dpp v218, v216 quad_perm:[1,0,3,2] row_mask:0xf bank_mask:0xf
	v_mov_b32_dpp v219, v217 quad_perm:[1,0,3,2] row_mask:0xf bank_mask:0xf
	v_cndmask_b32_e64 v220, v208, v218, s[98:99]
	v_cndmask_b32_e64 v221, v209, v219, s[98:99]
	v_cndmask_b32_e64 v222, v218, v210, s[98:99]
	v_cndmask_b32_e64 v223, v219, v211, s[98:99]
	global_store_dwordx4 v[228:229], v[220:223], off offset:-1536 sc0 sc1
	s_nop 1
	v_cndmask_b32_e64 v216, v76, v212, s[98:99]
	v_cndmask_b32_e64 v217, v77, v213, s[98:99]
	s_nop 1
	v_mov_b32_dpp v218, v216 quad_perm:[1,0,3,2] row_mask:0xf bank_mask:0xf
	v_mov_b32_dpp v219, v217 quad_perm:[1,0,3,2] row_mask:0xf bank_mask:0xf
	v_cndmask_b32_e64 v224, v212, v218, s[98:99]
	v_cndmask_b32_e64 v225, v213, v219, s[98:99]
	v_cndmask_b32_e64 v226, v218, v76, s[98:99]
	v_cndmask_b32_e64 v227, v219, v77, s[98:99]
	global_store_dwordx4 v[228:229], v[224:227], off offset:-512 sc0 sc1
	s_nop 1
	s_mov_b32 s99, 0
	s_nop 1
	s_cbranch_execnz .LBB0_805

.LBB0_805:
	s_and_b64 vcc, exec, s[10:11]
	v_lshl_add_u64 v[66:67], v[62:63], 0, s[88:89]
	s_cbranch_vccnz .LBB0_807
	v_mul_f32_e32 v60, v44, v44
	v_mul_f32_e32 v76, v46, v46
	v_fmac_f32_e32 v60, v45, v45
	v_fmac_f32_e32 v76, v47, v47
	v_add_f32_e32 v60, v76, v60
	v_mul_f32_e32 v76, v40, v40
	v_mul_f32_e32 v77, v43, v43
	v_fmac_f32_e32 v76, v41, v41
	v_fmac_f32_e32 v77, v42, v42
	v_add_f32_e32 v76, v77, v76
	v_add_f32_e32 v60, v60, v76
	v_mul_f32_e32 v76, v36, v36
	v_mul_f32_e32 v77, v39, v39
	v_fmac_f32_e32 v76, v37, v37
	v_fmac_f32_e32 v77, v38, v38
	v_add_f32_e32 v76, v77, v76
	v_add_f32_e32 v60, v60, v76
	v_mov_b32_e32 v76, v35
	v_mov_b32_e32 v77, v32
	v_pk_mul_f32 v[76:77], v[76:77], v[76:77]
	v_mov_b32_e32 v78, v34
	v_mov_b32_e32 v79, v33
	v_pk_fma_f32 v[76:77], v[78:79], v[78:79], v[76:77]
	s_mov_b64 s[0:1], 0x3800000
	v_add_f32_e32 v76, v76, v77
	v_add_f32_e32 v60, v60, v76
	s_nop 1
	v_mov_b32_dpp v76, v60 quad_perm:[1,0,3,2] row_mask:0xf bank_mask:0xf
	s_waitcnt lgkmcnt(0)
	v_add_f32_e32 v60, v60, v76
	s_nop 1
	v_mov_b32_dpp v76, v60 quad_perm:[2,3,0,1] row_mask:0xf bank_mask:0xf
	s_waitcnt lgkmcnt(0)
	v_add_f32_e32 v60, v60, v76
	s_nop 1
	v_mov_b32_dpp v76, v60 row_half_mirror row_mask:0xf bank_mask:0xf
	s_waitcnt lgkmcnt(0)
	v_add_f32_e32 v60, v60, v76
	s_nop 1
	v_mov_b32_dpp v76, v60 row_mirror row_mask:0xf bank_mask:0xf
	s_waitcnt lgkmcnt(0)
	v_add_f32_e32 v60, v60, v76
	v_mov_b32_e32 v76, v60
	s_nop 1
	v_permlane16_swap_b32 v60, v76
	s_waitcnt lgkmcnt(0)
	v_add_f32_e32 v60, v60, v76
	v_mov_b32_e32 v76, v60
	s_nop 1
	v_permlane32_swap_b32 v60, v76
	s_waitcnt lgkmcnt(0)
	v_add_f32_e32 v60, v60, v76
	v_fmamk_f32 v60, v60, 0x3a800000, v102
	v_mul_f32_e32 v76, 0x4b800000, v60
	v_cmp_gt_f32_e32 vcc, s84, v60
	s_nop 1
	v_cndmask_b32_e32 v60, v60, v76, vcc
	v_rsq_f32_e32 v60, v60
	v_lshl_add_u64 v[76:77], v[66:67], 0, s[0:1]
	s_mov_b64 s[0:1], 0x3800200
	v_mul_f32_e32 v78, 0x45800000, v60
	v_cndmask_b32_e32 v60, v60, v78, vcc
	v_pk_mul_f32 v[44:45], v[44:45], v[60:61] op_sel_hi:[1,0]
	v_pk_mul_f32 v[40:41], v[40:41], v[60:61] op_sel_hi:[1,0]
	v_pk_mul_f32 v[42:43], v[42:43], v[60:61] op_sel_hi:[1,0]
	v_pk_mul_f32 v[46:47], v[46:47], v[60:61] op_sel_hi:[1,0]
	v_pk_mul_f32 v[44:45], v[8:9], v[44:45]
	v_pk_mul_f32 v[42:43], v[6:7], v[42:43]
	v_pk_mul_f32 v[40:41], v[4:5], v[40:41]
	v_pk_mul_f32 v[36:37], v[36:37], v[60:61] op_sel_hi:[1,0]
	v_pk_mul_f32 v[38:39], v[38:39], v[60:61] op_sel_hi:[1,0]
	v_pk_mul_f32 v[46:47], v[10:11], v[46:47]
	v_cvt_pk_bf16_f32 v44, v44, v45
	v_pk_mul_f32 v[38:39], v[26:27], v[38:39]
	v_cvt_pk_bf16_f32 v45, v46, v47
	v_pk_mul_f32 v[36:37], v[24:25], v[36:37]
	v_mov_b32_e32 v208, v44
	v_mov_b32_e32 v209, v45
	s_nop 1
	v_cvt_pk_bf16_f32 v40, v40, v41
	v_cvt_pk_bf16_f32 v41, v42, v43
	v_lshl_add_u64 v[42:43], v[66:67], 0, s[0:1]
	s_mov_b64 s[0:1], 0x3800400
	v_pk_mul_f32 v[32:33], v[32:33], v[60:61] op_sel_hi:[1,0]
	v_pk_mul_f32 v[34:35], v[34:35], v[60:61] op_sel_hi:[1,0]
	v_mov_b32_e32 v210, v40
	v_mov_b32_e32 v211, v41
	s_nop 1
	v_cvt_pk_bf16_f32 v36, v36, v37
	v_cvt_pk_bf16_f32 v37, v38, v39
	v_lshl_add_u64 v[38:39], v[66:67], 0, s[0:1]
	v_pk_mul_f32 v[34:35], v[22:23], v[34:35]
	v_pk_mul_f32 v[32:33], v[20:21], v[32:33]
	s_mov_b64 s[0:1], 0x3800600
	v_mov_b32_e32 v212, v36
	v_mov_b32_e32 v213, v37
	s_nop 1
	v_cvt_pk_bf16_f32 v32, v32, v33
	v_cvt_pk_bf16_f32 v33, v34, v35
	v_lshl_add_u64 v[34:35], v[66:67], 0, s[0:1]
	v_and_b32_e32 v232, 1, v152
	v_cmp_eq_u32_e64 s[98:99], 1, v232
	v_mul_u32_u24_e32 v230, 0x1f8, v232
	v_mov_b32_e32 v231, 0
	v_lshl_add_u64 v[228:229], v[34:35], 0, v[230:231]
	v_cndmask_b32_e64 v216, v210, v208, s[98:99]
	v_cndmask_b32_e64 v217, v211, v209, s[98:99]
	s_nop 1
	v_mov_b32_dpp v218, v216 quad_perm:[1,0,3,2] row_mask:0xf bank_mask:0xf
	v_mov_b32_dpp v219, v217 quad_perm:[1,0,3,2] row_mask:0xf bank_mask:0xf
	v_cndmask_b32_e64 v220, v208, v218, s[98:99]
	v_cndmask_b32_e64 v221, v209, v219, s[98:99]
	v_cndmask_b32_e64 v222, v218, v210, s[98:99]
	v_cndmask_b32_e64 v223, v219, v211, s[98:99]
	global_store_dwordx4 v[228:229], v[220:223], off offset:-1536 sc0 sc1
	s_nop 1
	v_cndmask_b32_e64 v216, v32, v212, s[98:99]
	v_cndmask_b32_e64 v217, v33, v213, s[98:99]
	s_nop 1
	v_mov_b32_dpp v218, v216 quad_perm:[1,0,3,2] row_mask:0xf bank_mask:0xf
	v_mov_b32_dpp v219, v217 quad_perm:[1,0,3,2] row_mask:0xf bank_mask:0xf
	v_cndmask_b32_e64 v224, v212, v218, s[98:99]
	v_cndmask_b32_e64 v225, v213, v219, s[98:99]
	v_cndmask_b32_e64 v226, v218, v32, s[98:99]
	v_cndmask_b32_e64 v227, v219, v33, s[98:99]
	global_store_dwordx4 v[228:229], v[224:227], off offset:-512 sc0 sc1
	s_nop 1
	s_mov_b32 s99, 0
	s_nop 1

.LBB0_832:
	s_lshl_b64 s[0:1], s[38:39], 12
	s_add_u32 s0, s36, s0
	s_addc_u32 s1, s37, s1
	v_lshl_add_u64 v[32:33], s[0:1], 0, v[50:51]
	global_load_dwordx4 v[44:47], v[32:33], off
	global_load_dwordx4 v[40:43], v[32:33], off offset:1024
	global_load_dwordx4 v[36:39], v[32:33], off offset:2048
	s_nop 0
	global_load_dwordx4 v[32:35], v[32:33], off offset:3072
	s_nop 0
	global_load_dwordx2 v[82:83], v[70:71], off offset:2048
	global_load_dwordx2 v[88:89], v[70:71], off offset:2560
	global_load_dwordx2 v[80:81], v[70:71], off offset:3072
	s_nop 0
	global_load_dwordx2 v[70:71], v[70:71], off offset:3584
	s_nop 0
	global_load_dwordx2 v[90:91], v[72:73], off offset:2048
	global_load_dwordx2 v[96:97], v[72:73], off offset:2560
	global_load_dwordx2 v[84:85], v[72:73], off offset:3072
	s_nop 0
	global_load_dwordx2 v[72:73], v[72:73], off offset:3584
	s_nop 0
	global_load_dwordx2 v[98:99], v[74:75], off offset:2048
	global_load_dwordx2 v[100:101], v[74:75], off offset:2560
	global_load_dwordx2 v[86:87], v[74:75], off offset:3072
	s_nop 0
	global_load_dwordx2 v[74:75], v[74:75], off offset:3584
	s_nop 0
	global_load_dwordx2 v[106:107], v[68:69], off offset:2048
	global_load_dwordx2 v[108:109], v[68:69], off offset:2560
	global_load_dwordx2 v[94:95], v[68:69], off offset:3072
	global_load_dwordx2 v[92:93], v[68:69], off offset:3584
	s_lshl_b64 s[0:1], s[6:7], 12
	s_add_u32 s0, s8, s0
	s_addc_u32 s1, s9, s1
	s_lshl_b64 s[6:7], s[50:51], 12
	s_add_u32 s6, s40, s6
	s_addc_u32 s7, s41, s7
	v_lshl_add_u64 v[76:77], v[48:49], 3, s[6:7]
	s_waitcnt vmcnt(15)
	v_lshlrev_b32_e32 v68, 16, v82
	v_and_b32_e32 v69, 0xffff0000, v82
	v_pk_add_f32 v[68:69], v[68:69], 0 op_sel_hi:[1,0]
	s_waitcnt vmcnt(11)
	v_lshlrev_b32_e32 v78, 16, v90
	v_and_b32_e32 v79, 0xffff0000, v90
	v_pk_add_f32 v[68:69], v[68:69], v[78:79]
	v_lshlrev_b32_e32 v82, 16, v91
	s_waitcnt vmcnt(7)
	v_lshlrev_b32_e32 v78, 16, v98
	v_and_b32_e32 v79, 0xffff0000, v98
	v_pk_add_f32 v[68:69], v[68:69], v[78:79]
	s_waitcnt vmcnt(3)
	v_lshlrev_b32_e32 v78, 16, v106
	v_and_b32_e32 v79, 0xffff0000, v106
	v_pk_add_f32 v[78:79], v[68:69], v[78:79]
	v_lshlrev_b32_e32 v68, 16, v83
	v_and_b32_e32 v69, 0xffff0000, v83
	v_pk_add_f32 v[68:69], v[68:69], 0 op_sel_hi:[1,0]
	v_and_b32_e32 v83, 0xffff0000, v91
	v_pk_add_f32 v[68:69], v[68:69], v[82:83]
	v_lshlrev_b32_e32 v82, 16, v99
	v_and_b32_e32 v83, 0xffff0000, v99
	v_pk_add_f32 v[68:69], v[68:69], v[82:83]
	v_lshlrev_b32_e32 v82, 16, v107
	v_and_b32_e32 v83, 0xffff0000, v107
	v_pk_add_f32 v[90:91], v[68:69], v[82:83]
	v_lshlrev_b32_e32 v68, 16, v88
	v_and_b32_e32 v69, 0xffff0000, v88
	v_pk_add_f32 v[68:69], v[68:69], 0 op_sel_hi:[1,0]
	v_lshlrev_b32_e32 v82, 16, v96
	v_and_b32_e32 v83, 0xffff0000, v96
	v_pk_add_f32 v[68:69], v[68:69], v[82:83]
	v_lshlrev_b32_e32 v82, 16, v100
	v_and_b32_e32 v83, 0xffff0000, v100
	v_pk_add_f32 v[68:69], v[68:69], v[82:83]
	s_waitcnt vmcnt(2)
	v_lshlrev_b32_e32 v82, 16, v108
	v_and_b32_e32 v83, 0xffff0000, v108
	v_pk_add_f32 v[68:69], v[68:69], v[82:83]
	v_lshlrev_b32_e32 v82, 16, v89
	v_and_b32_e32 v83, 0xffff0000, v89
	v_pk_add_f32 v[82:83], v[82:83], 0 op_sel_hi:[1,0]
	v_lshlrev_b32_e32 v88, 16, v97
	v_and_b32_e32 v89, 0xffff0000, v97
	v_pk_add_f32 v[82:83], v[82:83], v[88:89]
	v_lshlrev_b32_e32 v88, 16, v101
	v_and_b32_e32 v89, 0xffff0000, v101
	v_pk_add_f32 v[82:83], v[82:83], v[88:89]
	v_lshlrev_b32_e32 v88, 16, v109
	v_and_b32_e32 v89, 0xffff0000, v109
	v_pk_add_f32 v[88:89], v[82:83], v[88:89]
	v_lshlrev_b32_e32 v82, 16, v80
	v_and_b32_e32 v83, 0xffff0000, v80
	v_lshlrev_b32_e32 v80, 16, v81
	v_and_b32_e32 v81, 0xffff0000, v81
	v_lshlrev_b32_e32 v96, 16, v84
	v_and_b32_e32 v97, 0xffff0000, v84
	v_pk_add_f32 v[80:81], v[80:81], 0 op_sel_hi:[1,0]
	v_lshlrev_b32_e32 v84, 16, v85
	v_and_b32_e32 v85, 0xffff0000, v85
	v_pk_add_f32 v[80:81], v[80:81], v[84:85]
	v_lshlrev_b32_e32 v84, 16, v87
	v_and_b32_e32 v85, 0xffff0000, v87
	v_pk_add_f32 v[80:81], v[80:81], v[84:85]
	s_waitcnt vmcnt(1)
	v_lshlrev_b32_e32 v84, 16, v95
	v_and_b32_e32 v85, 0xffff0000, v95
	v_pk_add_f32 v[82:83], v[82:83], 0 op_sel_hi:[1,0]
	v_pk_add_f32 v[84:85], v[80:81], v[84:85]
	v_lshlrev_b32_e32 v80, 16, v70
	v_and_b32_e32 v81, 0xffff0000, v70
	v_lshlrev_b32_e32 v70, 16, v71
	v_and_b32_e32 v71, 0xffff0000, v71
	v_pk_add_f32 v[82:83], v[82:83], v[96:97]
	v_lshlrev_b32_e32 v96, 16, v86
	v_and_b32_e32 v97, 0xffff0000, v86
	v_pk_add_f32 v[80:81], v[80:81], 0 op_sel_hi:[1,0]
	v_lshlrev_b32_e32 v86, 16, v72
	v_and_b32_e32 v87, 0xffff0000, v72
	v_pk_add_f32 v[70:71], v[70:71], 0 op_sel_hi:[1,0]
	v_lshlrev_b32_e32 v72, 16, v73
	v_and_b32_e32 v73, 0xffff0000, v73
	v_pk_add_f32 v[80:81], v[80:81], v[86:87]
	v_lshlrev_b32_e32 v86, 16, v74
	v_and_b32_e32 v87, 0xffff0000, v74
	v_pk_add_f32 v[70:71], v[70:71], v[72:73]
	v_lshlrev_b32_e32 v72, 16, v75
	v_and_b32_e32 v73, 0xffff0000, v75
	v_pk_add_f32 v[82:83], v[82:83], v[96:97]
	v_lshlrev_b32_e32 v96, 16, v94
	v_and_b32_e32 v97, 0xffff0000, v94
	v_pk_add_f32 v[80:81], v[80:81], v[86:87]
	s_waitcnt vmcnt(0)
	v_lshlrev_b32_e32 v86, 16, v92
	v_and_b32_e32 v87, 0xffff0000, v92
	v_pk_add_f32 v[70:71], v[70:71], v[72:73]
	v_lshlrev_b32_e32 v72, 16, v93
	v_and_b32_e32 v73, 0xffff0000, v93
	v_mov_b32_e32 v74, v79
	v_mov_b32_e32 v75, v91
	v_pk_add_f32 v[82:83], v[82:83], v[96:97]
	v_pk_add_f32 v[80:81], v[80:81], v[86:87]
	v_pk_add_f32 v[70:71], v[70:71], v[72:73]
	v_mov_b32_e32 v72, v78
	v_mov_b32_e32 v73, v90
	v_pk_mul_f32 v[74:75], v[74:75], v[74:75]
	v_mov_b32_e32 v86, v69
	v_mov_b32_e32 v87, v89
	v_pk_fma_f32 v[72:73], v[72:73], v[72:73], v[74:75]
	v_mov_b32_e32 v74, v68
	v_mov_b32_e32 v75, v88
	v_pk_mul_f32 v[86:87], v[86:87], v[86:87]
	v_mul_f32_e32 v60, v83, v83
	v_pk_fma_f32 v[74:75], v[74:75], v[74:75], v[86:87]
	v_pk_fma_f32 v[86:87], v[82:83], v[82:83], v[60:61] op_sel_hi:[1,1,0]
	v_mul_f32_e32 v60, v85, v85
	v_pk_add_f32 v[72:73], v[72:73], v[72:73] op_sel:[0,1] op_sel_hi:[1,0]
	v_pk_add_f32 v[74:75], v[74:75], v[74:75] op_sel:[0,1] op_sel_hi:[1,0]
	v_pk_fma_f32 v[92:93], v[84:85], v[84:85], v[60:61] op_sel_hi:[1,1,0]
	v_pk_mul_f32 v[94:95], v[80:81], v[80:81]
	v_pk_mul_f32 v[96:97], v[70:71], v[70:71]
	v_mov_b32_e32 v73, v94
	v_mov_b32_e32 v75, v95
	v_mov_b32_e32 v87, v96
	v_mov_b32_e32 v93, v97
	v_pk_add_f32 v[72:73], v[72:73], v[74:75]
	v_pk_add_f32 v[74:75], v[86:87], v[92:93]
	s_nop 0
	v_pk_add_f32 v[72:73], v[72:73], v[74:75]
	s_nop 0
	v_add_f32_e32 v60, v72, v73
	s_nop 1
	v_mov_b32_dpp v72, v60 quad_perm:[1,0,3,2] row_mask:0xf bank_mask:0xf
	s_waitcnt lgkmcnt(0)
	v_add_f32_e32 v60, v60, v72
	s_nop 1
	v_mov_b32_dpp v72, v60 quad_perm:[2,3,0,1] row_mask:0xf bank_mask:0xf
	s_waitcnt lgkmcnt(0)
	v_add_f32_e32 v60, v60, v72
	s_nop 1
	v_mov_b32_dpp v72, v60 row_half_mirror row_mask:0xf bank_mask:0xf
	s_waitcnt lgkmcnt(0)
	v_add_f32_e32 v60, v60, v72
	s_nop 1
	v_mov_b32_dpp v72, v60 row_mirror row_mask:0xf bank_mask:0xf
	s_waitcnt lgkmcnt(0)
	v_add_f32_e32 v60, v60, v72
	v_mov_b32_e32 v72, v60
	s_nop 1
	v_permlane16_swap_b32 v60, v72
	s_waitcnt lgkmcnt(0)
	v_add_f32_e32 v60, v60, v72
	v_mov_b32_e32 v72, v60
	s_nop 1
	v_permlane32_swap_b32 v60, v72
	s_waitcnt lgkmcnt(0)
	v_add_f32_e32 v60, v60, v72
	v_fmamk_f32 v60, v60, 0x3a800000, v102
	v_cmp_gt_f32_e32 vcc, s84, v60
	v_mul_f32_e32 v72, 0x4b800000, v60
	s_nop 0
	v_cndmask_b32_e32 v60, v60, v72, vcc
	v_rsq_f32_e32 v60, v60
	s_nop 0
	v_mul_f32_e32 v72, 0x45800000, v60
	v_cndmask_b32_e32 v72, v60, v72, vcc
	v_pk_mul_f32 v[74:75], v[90:91], v[72:73] op_sel_hi:[1,0]
	v_pk_mul_f32 v[78:79], v[78:79], v[72:73] op_sel_hi:[1,0]
	v_pk_fma_f32 v[46:47], v[2:3], v[74:75], v[46:47]
	v_pk_fma_f32 v[44:45], v[0:1], v[78:79], v[44:45]
	s_and_b64 vcc, exec, s[10:11]
	s_cbranch_vccnz .LBB0_846
	v_lshl_add_u64 v[74:75], v[76:77], 0, s[70:71]
	v_cvt_pk_bf16_f32 v78, v44, v45
	v_cvt_pk_bf16_f32 v79, v46, v47
	s_nop 0
	v_mov_b32_e32 v208, v78
	v_mov_b32_e32 v209, v79
	s_nop 1
	v_lshl_add_u64 v[74:75], s[0:1], 0, v[50:51]
	s_cbranch_execnz .LBB0_835

.LBB0_835:
	v_mov_b32_e32 v73, v72
	v_mov_b32_e32 v78, v72
	v_mov_b32_e32 v79, v72
	v_pk_mul_f32 v[68:69], v[68:69], v[72:73]
	v_pk_mul_f32 v[78:79], v[88:89], v[78:79]
	s_and_b64 vcc, exec, s[10:11]
	v_pk_fma_f32 v[42:43], v[14:15], v[78:79], v[42:43]
	v_pk_fma_f32 v[40:41], v[12:13], v[68:69], v[40:41]
	s_cbranch_vccnz .LBB0_847
	v_cvt_pk_bf16_f32 v68, v40, v41
	v_cvt_pk_bf16_f32 v69, v42, v43
	v_lshl_add_u64 v[78:79], v[76:77], 0, s[72:73]
	v_mov_b32_e32 v210, v68
	v_mov_b32_e32 v211, v69
	s_nop 1
	s_cbranch_execnz .LBB0_838

.LBB0_838:
	v_mov_b32_e32 v78, v72
	v_mov_b32_e32 v79, v72
	v_pk_mul_f32 v[68:69], v[82:83], v[72:73]
	v_pk_mul_f32 v[78:79], v[84:85], v[78:79]
	s_and_b64 vcc, exec, s[10:11]
	v_pk_fma_f32 v[38:39], v[18:19], v[78:79], v[38:39]
	v_pk_fma_f32 v[36:37], v[16:17], v[68:69], v[36:37]
	s_cbranch_vccnz .LBB0_848
	v_cvt_pk_bf16_f32 v68, v36, v37
	v_cvt_pk_bf16_f32 v69, v38, v39
	v_lshl_add_u64 v[78:79], v[76:77], 0, s[74:75]
	v_mov_b32_e32 v212, v68
	v_mov_b32_e32 v213, v69
	s_nop 1
	s_cbranch_execnz .LBB0_841

.LBB0_841:
	v_pk_mul_f32 v[68:69], v[80:81], v[72:73]
	v_mov_b32_e32 v73, v72
	v_pk_mul_f32 v[70:71], v[70:71], v[72:73]
	s_and_b64 vcc, exec, s[10:11]
	v_pk_fma_f32 v[34:35], v[30:31], v[70:71], v[34:35]
	v_pk_fma_f32 v[32:33], v[28:29], v[68:69], v[32:33]
	s_cbranch_vccnz .LBB0_849
	v_cvt_pk_bf16_f32 v68, v32, v33
	v_cvt_pk_bf16_f32 v69, v34, v35
	v_lshl_add_u64 v[70:71], v[76:77], 0, s[78:79]
	v_and_b32_e32 v232, 1, v152
	v_cmp_eq_u32_e64 s[98:99], 1, v232
	v_mul_u32_u24_e32 v230, 0x1f8, v232
	v_mov_b32_e32 v231, 0
	v_lshl_add_u64 v[228:229], v[70:71], 0, v[230:231]
	v_cndmask_b32_e64 v216, v210, v208, s[98:99]
	v_cndmask_b32_e64 v217, v211, v209, s[98:99]
	s_nop 1
	v_mov_b32_dpp v218, v216 quad_perm:[1,0,3,2] row_mask:0xf bank_mask:0xf
	v_mov_b32_dpp v219, v217 quad_perm:[1,0,3,2] row_mask:0xf bank_mask:0xf
	v_cndmask_b32_e64 v220, v208, v218, s[98:99]
	v_cndmask_b32_e64 v221, v209, v219, s[98:99]
	v_cndmask_b32_e64 v222, v218, v210, s[98:99]
	v_cndmask_b32_e64 v223, v219, v211, s[98:99]
	global_store_dwordx4 v[228:229], v[220:223], off offset:-1536 sc0 sc1
	s_nop 1
	v_cndmask_b32_e64 v216, v68, v212, s[98:99]
	v_cndmask_b32_e64 v217, v69, v213, s[98:99]
	s_nop 1
	v_mov_b32_dpp v218, v216 quad_perm:[1,0,3,2] row_mask:0xf bank_mask:0xf
	v_mov_b32_dpp v219, v217 quad_perm:[1,0,3,2] row_mask:0xf bank_mask:0xf
	v_cndmask_b32_e64 v224, v212, v218, s[98:99]
	v_cndmask_b32_e64 v225, v213, v219, s[98:99]
	v_cndmask_b32_e64 v226, v218, v68, s[98:99]
	v_cndmask_b32_e64 v227, v219, v69, s[98:99]
	global_store_dwordx4 v[228:229], v[224:227], off offset:-512 sc0 sc1
	s_nop 1
	s_mov_b32 s99, 0
	s_nop 1
	s_cbranch_execnz .LBB0_844

.LBB0_844:
	s_and_b64 vcc, exec, s[10:11]
	s_cbranch_vccnz .LBB0_771
	v_mul_f32_e32 v60, v44, v44
	v_mul_f32_e32 v68, v46, v46
	v_fmac_f32_e32 v60, v45, v45
	v_fmac_f32_e32 v68, v47, v47
	v_add_f32_e32 v60, v68, v60
	v_mul_f32_e32 v68, v40, v40
	v_mul_f32_e32 v69, v43, v43
	v_fmac_f32_e32 v68, v41, v41
	v_fmac_f32_e32 v69, v42, v42
	v_add_f32_e32 v68, v69, v68
	v_add_f32_e32 v60, v60, v68
	v_mul_f32_e32 v68, v36, v36
	v_mul_f32_e32 v69, v39, v39
	v_fmac_f32_e32 v68, v37, v37
	v_fmac_f32_e32 v69, v38, v38
	v_add_f32_e32 v68, v69, v68
	v_add_f32_e32 v60, v60, v68
	v_mov_b32_e32 v68, v35
	v_mov_b32_e32 v69, v32
	v_pk_mul_f32 v[68:69], v[68:69], v[68:69]
	v_mov_b32_e32 v70, v34
	v_mov_b32_e32 v71, v33
	v_pk_fma_f32 v[68:69], v[70:71], v[70:71], v[68:69]
	s_mov_b64 s[0:1], 0x3800800
	v_add_f32_e32 v68, v68, v69
	v_add_f32_e32 v60, v60, v68
	s_nop 1
	v_mov_b32_dpp v68, v60 quad_perm:[1,0,3,2] row_mask:0xf bank_mask:0xf
	s_waitcnt lgkmcnt(0)
	v_add_f32_e32 v60, v60, v68
	s_nop 1
	v_mov_b32_dpp v68, v60 quad_perm:[2,3,0,1] row_mask:0xf bank_mask:0xf
	s_waitcnt lgkmcnt(0)
	v_add_f32_e32 v60, v60, v68
	s_nop 1
	v_mov_b32_dpp v68, v60 row_half_mirror row_mask:0xf bank_mask:0xf
	s_waitcnt lgkmcnt(0)
	v_add_f32_e32 v60, v60, v68
	s_nop 1
	v_mov_b32_dpp v68, v60 row_mirror row_mask:0xf bank_mask:0xf
	s_waitcnt lgkmcnt(0)
	v_add_f32_e32 v60, v60, v68
	v_mov_b32_e32 v68, v60
	s_nop 1
	v_permlane16_swap_b32 v60, v68
	s_waitcnt lgkmcnt(0)
	v_add_f32_e32 v60, v60, v68
	v_mov_b32_e32 v68, v60
	s_nop 1
	v_permlane32_swap_b32 v60, v68
	s_waitcnt lgkmcnt(0)
	v_add_f32_e32 v60, v60, v68
	v_fmamk_f32 v60, v60, 0x3a800000, v102
	v_mul_f32_e32 v68, 0x4b800000, v60
	v_cmp_gt_f32_e32 vcc, s84, v60
	s_nop 1
	v_cndmask_b32_e32 v60, v60, v68, vcc
	v_rsq_f32_e32 v60, v60
	v_lshl_add_u64 v[68:69], v[66:67], 0, s[0:1]
	s_mov_b64 s[0:1], 0x3800a00
	v_mul_f32_e32 v70, 0x45800000, v60
	v_cndmask_b32_e32 v60, v60, v70, vcc
	v_pk_mul_f32 v[44:45], v[44:45], v[60:61] op_sel_hi:[1,0]
	v_pk_mul_f32 v[40:41], v[40:41], v[60:61] op_sel_hi:[1,0]
	v_pk_mul_f32 v[42:43], v[42:43], v[60:61] op_sel_hi:[1,0]
	v_pk_mul_f32 v[46:47], v[46:47], v[60:61] op_sel_hi:[1,0]
	v_pk_mul_f32 v[44:45], v[8:9], v[44:45]
	v_pk_mul_f32 v[42:43], v[6:7], v[42:43]
	v_pk_mul_f32 v[40:41], v[4:5], v[40:41]
	v_pk_mul_f32 v[36:37], v[36:37], v[60:61] op_sel_hi:[1,0]
	v_pk_mul_f32 v[38:39], v[38:39], v[60:61] op_sel_hi:[1,0]
	v_pk_mul_f32 v[46:47], v[10:11], v[46:47]
	v_cvt_pk_bf16_f32 v44, v44, v45
	v_pk_mul_f32 v[38:39], v[26:27], v[38:39]
	v_cvt_pk_bf16_f32 v45, v46, v47
	v_pk_mul_f32 v[36:37], v[24:25], v[36:37]
	v_mov_b32_e32 v208, v44
	v_mov_b32_e32 v209, v45
	s_nop 1
	v_cvt_pk_bf16_f32 v40, v40, v41
	v_cvt_pk_bf16_f32 v41, v42, v43
	v_lshl_add_u64 v[42:43], v[66:67], 0, s[0:1]
	s_mov_b64 s[0:1], 0x3800c00
	v_pk_mul_f32 v[32:33], v[32:33], v[60:61] op_sel_hi:[1,0]
	v_pk_mul_f32 v[34:35], v[34:35], v[60:61] op_sel_hi:[1,0]
	v_mov_b32_e32 v210, v40
	v_mov_b32_e32 v211, v41
	s_nop 1
	v_cvt_pk_bf16_f32 v36, v36, v37
	v_cvt_pk_bf16_f32 v37, v38, v39
	v_lshl_add_u64 v[38:39], v[66:67], 0, s[0:1]
	v_pk_mul_f32 v[34:35], v[22:23], v[34:35]
	v_pk_mul_f32 v[32:33], v[20:21], v[32:33]
	s_mov_b64 s[0:1], 0x3800e00
	v_mov_b32_e32 v212, v36
	v_mov_b32_e32 v213, v37
	s_nop 1
	v_cvt_pk_bf16_f32 v32, v32, v33
	v_cvt_pk_bf16_f32 v33, v34, v35
	v_lshl_add_u64 v[34:35], v[66:67], 0, s[0:1]
	v_and_b32_e32 v232, 1, v152
	v_cmp_eq_u32_e64 s[98:99], 1, v232
	v_mul_u32_u24_e32 v230, 0x1f8, v232
	v_mov_b32_e32 v231, 0
	v_lshl_add_u64 v[228:229], v[34:35], 0, v[230:231]
	v_cndmask_b32_e64 v216, v210, v208, s[98:99]
	v_cndmask_b32_e64 v217, v211, v209, s[98:99]
	s_nop 1
	v_mov_b32_dpp v218, v216 quad_perm:[1,0,3,2] row_mask:0xf bank_mask:0xf
	v_mov_b32_dpp v219, v217 quad_perm:[1,0,3,2] row_mask:0xf bank_mask:0xf
	v_cndmask_b32_e64 v220, v208, v218, s[98:99]
	v_cndmask_b32_e64 v221, v209, v219, s[98:99]
	v_cndmask_b32_e64 v222, v218, v210, s[98:99]
	v_cndmask_b32_e64 v223, v219, v211, s[98:99]
	global_store_dwordx4 v[228:229], v[220:223], off offset:-1536 sc0 sc1
	s_nop 1
	v_cndmask_b32_e64 v216, v32, v212, s[98:99]
	v_cndmask_b32_e64 v217, v33, v213, s[98:99]
	s_nop 1
	v_mov_b32_dpp v218, v216 quad_perm:[1,0,3,2] row_mask:0xf bank_mask:0xf
	v_mov_b32_dpp v219, v217 quad_perm:[1,0,3,2] row_mask:0xf bank_mask:0xf
	v_cndmask_b32_e64 v224, v212, v218, s[98:99]
	v_cndmask_b32_e64 v225, v213, v219, s[98:99]
	v_cndmask_b32_e64 v226, v218, v32, s[98:99]
	v_cndmask_b32_e64 v227, v219, v33, s[98:99]
	global_store_dwordx4 v[228:229], v[224:227], off offset:-512 sc0 sc1
	s_nop 1
	s_mov_b32 s99, 0
	s_nop 1
	s_branch .LBB0_771

.LBB0_875:
	s_or_b64 exec, exec, s[48:49]
	s_lshl_b64 s[16:17], s[38:39], 12
	s_add_u32 s16, s40, s16
	s_addc_u32 s17, s41, s17
	s_lshl_b64 s[18:19], s[86:87], 11
	v_lshl_add_u64 v[34:35], v[56:57], 0, s[18:19]
	global_load_dwordx2 v[68:69], v[34:35], off
	s_lshl_b64 s[18:19], s[36:37], 12
	s_add_u32 s8, s8, s18
	s_addc_u32 s9, s9, s19
	v_lshl_add_u64 v[44:45], s[8:9], 0, v[50:51]
	global_load_dwordx4 v[74:77], v[44:45], off
	global_load_dwordx4 v[36:39], v[44:45], off offset:1024
	global_load_dwordx2 v[72:73], v[34:35], off offset:512
	global_load_dwordx2 v[70:71], v[34:35], off offset:1024
	global_load_dwordx2 v[64:65], v[34:35], off offset:1536
	global_load_dwordx4 v[40:43], v[44:45], off offset:2048
	s_nop 0
	global_load_dwordx4 v[44:47], v[44:45], off offset:3072
	s_waitcnt vmcnt(8)
	s_nop 1
	v_mov_b32_dpp v33, v32 quad_perm:[1,0,3,2] row_mask:0xf bank_mask:0xf
	s_lshl_b64 s[8:9], s[0:1], 12
	s_add_u32 s6, s6, s8
	v_lshl_add_u64 v[62:63], v[48:49], 3, s[16:17]
	s_addc_u32 s7, s7, s9
	s_waitcnt lgkmcnt(0)
	v_add_f32_e32 v32, v32, v33
	s_nop 1
	v_mov_b32_dpp v33, v32 quad_perm:[2,3,0,1] row_mask:0xf bank_mask:0xf
	s_and_b64 vcc, exec, s[10:11]
	s_waitcnt lgkmcnt(0)
	v_add_f32_e32 v32, v32, v33
	s_nop 1
	v_mov_b32_dpp v33, v32 row_half_mirror row_mask:0xf bank_mask:0xf
	s_waitcnt lgkmcnt(0)
	v_add_f32_e32 v32, v32, v33
	s_nop 1
	v_mov_b32_dpp v33, v32 row_mirror row_mask:0xf bank_mask:0xf
	s_waitcnt lgkmcnt(0)
	v_add_f32_e32 v32, v32, v33
	v_mov_b32_e32 v33, v32
	s_nop 1
	v_permlane16_swap_b32 v32, v33
	s_waitcnt lgkmcnt(0)
	v_add_f32_e32 v32, v32, v33
	v_mov_b32_e32 v33, v32
	s_nop 1
	v_permlane32_swap_b32 v32, v33
	s_waitcnt lgkmcnt(0)
	v_add_f32_e32 v32, v32, v33
	v_fmamk_f32 v32, v32, 0x3a800000, v102
	v_mul_f32_e32 v33, 0x4b800000, v32
	v_cmp_gt_f32_e64 s[0:1], s84, v32
	s_waitcnt vmcnt(7)
	v_lshlrev_b32_e32 v34, 16, v69
	v_cndmask_b32_e64 v32, v32, v33, s[0:1]
	v_rsq_f32_e32 v32, v32
	v_and_b32_e32 v35, 0xffff0000, v69
	v_mul_f32_e32 v33, 0x45800000, v32
	v_cndmask_b32_e64 v66, v32, v33, s[0:1]
	v_lshlrev_b32_e32 v32, 16, v68
	v_and_b32_e32 v33, 0xffff0000, v68
	v_pk_mul_f32 v[34:35], v[66:67], v[34:35] op_sel_hi:[0,1]
	v_pk_mul_f32 v[32:33], v[66:67], v[32:33] op_sel_hi:[0,1]
	s_waitcnt vmcnt(6)
	v_pk_fma_f32 v[32:33], v[0:1], v[32:33], v[74:75]
	v_pk_fma_f32 v[34:35], v[2:3], v[34:35], v[76:77]
	s_cbranch_vccnz .LBB0_901
	v_lshl_add_u64 v[68:69], v[62:63], 0, s[70:71]
	v_cvt_pk_bf16_f32 v74, v32, v33
	v_cvt_pk_bf16_f32 v75, v34, v35
	s_nop 0
	v_mov_b32_e32 v208, v74
	v_mov_b32_e32 v209, v75
	s_nop 1
	v_lshl_add_u64 v[68:69], s[6:7], 0, v[50:51]
	s_cbranch_execnz .LBB0_878

.LBB0_878:
	v_mov_b32_e32 v67, v66
	s_waitcnt vmcnt(4)
	v_lshlrev_b32_e32 v74, 16, v72
	v_and_b32_e32 v75, 0xffff0000, v72
	v_lshlrev_b32_e32 v72, 16, v73
	v_and_b32_e32 v73, 0xffff0000, v73
	v_mov_b32_e32 v76, v66
	v_mov_b32_e32 v77, v66
	v_pk_mul_f32 v[72:73], v[76:77], v[72:73]
	v_pk_mul_f32 v[74:75], v[66:67], v[74:75]
	s_and_b64 vcc, exec, s[10:11]
	v_pk_fma_f32 v[36:37], v[12:13], v[74:75], v[36:37]
	v_pk_fma_f32 v[38:39], v[14:15], v[72:73], v[38:39]
	s_cbranch_vccnz .LBB0_902
	v_cvt_pk_bf16_f32 v72, v36, v37
	v_cvt_pk_bf16_f32 v73, v38, v39
	v_lshl_add_u64 v[74:75], v[62:63], 0, s[72:73]
	v_mov_b32_e32 v210, v72
	v_mov_b32_e32 v211, v73
	s_nop 1
	s_cbranch_execnz .LBB0_881

.LBB0_881:
	s_waitcnt vmcnt(3)
	v_lshlrev_b32_e32 v72, 16, v70
	v_and_b32_e32 v73, 0xffff0000, v70
	v_lshlrev_b32_e32 v70, 16, v71
	v_and_b32_e32 v71, 0xffff0000, v71
	v_mov_b32_e32 v74, v66
	v_mov_b32_e32 v75, v66
	v_pk_mul_f32 v[70:71], v[74:75], v[70:71]
	v_pk_mul_f32 v[72:73], v[66:67], v[72:73]
	s_and_b64 vcc, exec, s[10:11]
	s_waitcnt vmcnt(1)
	v_pk_fma_f32 v[40:41], v[16:17], v[72:73], v[40:41]
	v_pk_fma_f32 v[42:43], v[18:19], v[70:71], v[42:43]
	s_cbranch_vccnz .LBB0_903
	v_cvt_pk_bf16_f32 v70, v40, v41
	v_cvt_pk_bf16_f32 v71, v42, v43
	v_lshl_add_u64 v[72:73], v[62:63], 0, s[74:75]
	v_mov_b32_e32 v212, v70
	v_mov_b32_e32 v213, v71
	s_nop 1
	s_cbranch_execnz .LBB0_884

.LBB0_884:
	v_lshlrev_b32_e32 v70, 16, v64
	v_and_b32_e32 v71, 0xffff0000, v64
	v_lshlrev_b32_e32 v64, 16, v65
	v_and_b32_e32 v65, 0xffff0000, v65
	v_pk_mul_f32 v[70:71], v[66:67], v[70:71]
	v_mov_b32_e32 v67, v66
	v_pk_mul_f32 v[64:65], v[66:67], v[64:65]
	s_and_b64 vcc, exec, s[10:11]
	s_waitcnt vmcnt(0)
	v_pk_fma_f32 v[46:47], v[30:31], v[64:65], v[46:47]
	v_pk_fma_f32 v[44:45], v[28:29], v[70:71], v[44:45]
	s_cbranch_vccnz .LBB0_904
	v_cvt_pk_bf16_f32 v64, v44, v45
	v_cvt_pk_bf16_f32 v65, v46, v47
	v_lshl_add_u64 v[62:63], v[62:63], 0, s[78:79]
	v_and_b32_e32 v232, 1, v152
	v_cmp_eq_u32_e64 s[98:99], 1, v232
	v_mul_u32_u24_e32 v230, 0x1f8, v232
	v_mov_b32_e32 v231, 0
	v_lshl_add_u64 v[228:229], v[62:63], 0, v[230:231]
	v_cndmask_b32_e64 v216, v210, v208, s[98:99]
	v_cndmask_b32_e64 v217, v211, v209, s[98:99]
	s_nop 1
	v_mov_b32_dpp v218, v216 quad_perm:[1,0,3,2] row_mask:0xf bank_mask:0xf
	v_mov_b32_dpp v219, v217 quad_perm:[1,0,3,2] row_mask:0xf bank_mask:0xf
	v_cndmask_b32_e64 v220, v208, v218, s[98:99]
	v_cndmask_b32_e64 v221, v209, v219, s[98:99]
	v_cndmask_b32_e64 v222, v218, v210, s[98:99]
	v_cndmask_b32_e64 v223, v219, v211, s[98:99]
	global_store_dwordx4 v[228:229], v[220:223], off offset:-1536 sc0 sc1
	s_nop 1
	v_cndmask_b32_e64 v216, v64, v212, s[98:99]
	v_cndmask_b32_e64 v217, v65, v213, s[98:99]
	s_nop 1
	v_mov_b32_dpp v218, v216 quad_perm:[1,0,3,2] row_mask:0xf bank_mask:0xf
	v_mov_b32_dpp v219, v217 quad_perm:[1,0,3,2] row_mask:0xf bank_mask:0xf
	v_cndmask_b32_e64 v224, v212, v218, s[98:99]
	v_cndmask_b32_e64 v225, v213, v219, s[98:99]
	v_cndmask_b32_e64 v226, v218, v64, s[98:99]
	v_cndmask_b32_e64 v227, v219, v65, s[98:99]
	global_store_dwordx4 v[228:229], v[224:227], off offset:-512 sc0 sc1
	s_nop 1
	s_mov_b32 s99, 0
	s_nop 1
	s_cbranch_execnz .LBB0_887

.LBB0_887:
	s_and_b64 vcc, exec, s[10:11]
	s_cbranch_vccnz .LBB0_889
	v_mul_f32_e32 v60, v32, v32
	v_mul_f32_e32 v62, v34, v34
	v_fmac_f32_e32 v60, v33, v33
	v_fmac_f32_e32 v62, v35, v35
	v_add_f32_e32 v60, v62, v60
	v_mul_f32_e32 v62, v36, v36
	v_mul_f32_e32 v63, v39, v39
	v_fmac_f32_e32 v62, v37, v37
	v_fmac_f32_e32 v63, v38, v38
	v_add_f32_e32 v62, v63, v62
	v_add_f32_e32 v60, v60, v62
	v_mul_f32_e32 v62, v40, v40
	v_mul_f32_e32 v63, v43, v43
	v_fmac_f32_e32 v62, v41, v41
	v_fmac_f32_e32 v63, v42, v42
	v_add_f32_e32 v62, v63, v62
	v_add_f32_e32 v60, v60, v62
	v_mov_b32_e32 v62, v47
	v_mov_b32_e32 v63, v44
	v_pk_mul_f32 v[62:63], v[62:63], v[62:63]
	v_mov_b32_e32 v64, v46
	v_mov_b32_e32 v65, v45
	v_pk_fma_f32 v[62:63], v[64:65], v[64:65], v[62:63]
	s_lshl_b64 s[0:1], s[86:87], 10
	v_add_f32_e32 v62, v62, v63
	v_add_f32_e32 v60, v60, v62
	s_nop 1
	v_mov_b32_dpp v62, v60 quad_perm:[1,0,3,2] row_mask:0xf bank_mask:0xf
	s_waitcnt lgkmcnt(0)
	v_add_f32_e32 v60, v60, v62
	s_nop 1
	v_mov_b32_dpp v62, v60 quad_perm:[2,3,0,1] row_mask:0xf bank_mask:0xf
	s_waitcnt lgkmcnt(0)
	v_add_f32_e32 v60, v60, v62
	s_nop 1
	v_mov_b32_dpp v62, v60 row_half_mirror row_mask:0xf bank_mask:0xf
	s_waitcnt lgkmcnt(0)
	v_add_f32_e32 v60, v60, v62
	s_nop 1
	v_mov_b32_dpp v62, v60 row_mirror row_mask:0xf bank_mask:0xf
	s_waitcnt lgkmcnt(0)
	v_add_f32_e32 v60, v60, v62
	v_mov_b32_e32 v62, v60
	s_nop 1
	v_permlane16_swap_b32 v60, v62
	s_waitcnt lgkmcnt(0)
	v_add_f32_e32 v60, v60, v62
	v_mov_b32_e32 v62, v60
	s_nop 1
	v_permlane32_swap_b32 v60, v62
	s_waitcnt lgkmcnt(0)
	v_add_f32_e32 v60, v60, v62
	v_fmamk_f32 v60, v60, 0x3a800000, v102
	v_cmp_gt_f32_e32 vcc, s84, v60
	v_mul_f32_e32 v62, 0x4b800000, v60
	s_nop 0
	v_cndmask_b32_e32 v60, v60, v62, vcc
	v_rsq_f32_e32 v60, v60
	s_nop 0
	v_mul_f32_e32 v62, 0x45800000, v60
	v_cndmask_b32_e32 v60, v60, v62, vcc
	v_pk_mul_f32 v[32:33], v[32:33], v[60:61] op_sel_hi:[1,0]
	v_pk_mul_f32 v[34:35], v[34:35], v[60:61] op_sel_hi:[1,0]
	v_pk_mul_f32 v[32:33], v[8:9], v[32:33]
	v_pk_mul_f32 v[34:35], v[10:11], v[34:35]
	v_cvt_pk_bf16_f32 v32, v32, v33
	v_lshl_add_u64 v[62:63], s[0:1], 1, v[54:55]
	v_cvt_pk_bf16_f32 v33, v34, v35
	v_pk_mul_f32 v[34:35], v[38:39], v[60:61] op_sel_hi:[1,0]
	v_mov_b32_e32 v208, v32
	v_mov_b32_e32 v209, v33
	s_nop 1
	v_pk_mul_f32 v[32:33], v[36:37], v[60:61] op_sel_hi:[1,0]
	v_pk_mul_f32 v[34:35], v[6:7], v[34:35]
	v_pk_mul_f32 v[32:33], v[4:5], v[32:33]
	s_mov_b64 s[0:1], 0x600
	v_cvt_pk_bf16_f32 v32, v32, v33
	v_cvt_pk_bf16_f32 v33, v34, v35
	v_lshl_add_u64 v[34:35], v[62:63], 0, s[42:43]
	v_mov_b32_e32 v210, v32
	v_mov_b32_e32 v211, v33
	s_nop 1
	v_pk_mul_f32 v[32:33], v[40:41], v[60:61] op_sel_hi:[1,0]
	v_pk_mul_f32 v[34:35], v[42:43], v[60:61] op_sel_hi:[1,0]
	v_pk_mul_f32 v[32:33], v[24:25], v[32:33]
	v_pk_mul_f32 v[34:35], v[26:27], v[34:35]
	v_cvt_pk_bf16_f32 v32, v32, v33
	s_nop 0
	v_cvt_pk_bf16_f32 v33, v34, v35
	v_lshl_add_u64 v[34:35], v[62:63], 0, s[28:29]
	v_mov_b32_e32 v212, v32
	v_mov_b32_e32 v213, v33
	s_nop 1
	v_pk_mul_f32 v[32:33], v[44:45], v[60:61] op_sel_hi:[1,0]
	v_pk_mul_f32 v[34:35], v[46:47], v[60:61] op_sel_hi:[1,0]
	v_pk_mul_f32 v[32:33], v[20:21], v[32:33]
	v_pk_mul_f32 v[34:35], v[22:23], v[34:35]
	v_cvt_pk_bf16_f32 v32, v32, v33
	s_nop 0
	v_cvt_pk_bf16_f32 v33, v34, v35
	v_lshl_add_u64 v[34:35], v[62:63], 0, s[0:1]
	v_and_b32_e32 v232, 1, v152
	v_cmp_eq_u32_e64 s[98:99], 1, v232
	v_mul_u32_u24_e32 v230, 0x1f8, v232
	v_mov_b32_e32 v231, 0
	v_lshl_add_u64 v[228:229], v[34:35], 0, v[230:231]
	v_cndmask_b32_e64 v216, v210, v208, s[98:99]
	v_cndmask_b32_e64 v217, v211, v209, s[98:99]
	s_nop 1
	v_mov_b32_dpp v218, v216 quad_perm:[1,0,3,2] row_mask:0xf bank_mask:0xf
	v_mov_b32_dpp v219, v217 quad_perm:[1,0,3,2] row_mask:0xf bank_mask:0xf
	v_cndmask_b32_e64 v220, v208, v218, s[98:99]
	v_cndmask_b32_e64 v221, v209, v219, s[98:99]
	v_cndmask_b32_e64 v222, v218, v210, s[98:99]
	v_cndmask_b32_e64 v223, v219, v211, s[98:99]
	global_store_dwordx4 v[228:229], v[220:223], off offset:-1536 sc0 sc1
	s_nop 1
	v_cndmask_b32_e64 v216, v32, v212, s[98:99]
	v_cndmask_b32_e64 v217, v33, v213, s[98:99]
	s_nop 1
	v_mov_b32_dpp v218, v216 quad_perm:[1,0,3,2] row_mask:0xf bank_mask:0xf
	v_mov_b32_dpp v219, v217 quad_perm:[1,0,3,2] row_mask:0xf bank_mask:0xf
	v_cndmask_b32_e64 v224, v212, v218, s[98:99]
	v_cndmask_b32_e64 v225, v213, v219, s[98:99]
	v_cndmask_b32_e64 v226, v218, v32, s[98:99]
	v_cndmask_b32_e64 v227, v219, v33, s[98:99]
	global_store_dwordx4 v[228:229], v[224:227], off offset:-512 sc0 sc1
	s_nop 1
	s_mov_b32 s99, 0
	s_nop 1

.LBB0_916:
	s_or_b64 exec, exec, s[48:49]
	s_lshl_b64 s[16:17], s[38:39], 12
	s_add_u32 s16, s40, s16
	s_addc_u32 s17, s41, s17
	s_lshl_b64 s[18:19], s[68:69], 11
	v_lshl_add_u64 v[34:35], v[56:57], 0, s[18:19]
	global_load_dwordx2 v[68:69], v[34:35], off
	s_lshl_b64 s[14:15], s[14:15], 12
	s_add_u32 s14, s36, s14
	s_addc_u32 s15, s37, s15
	v_lshl_add_u64 v[44:45], s[14:15], 0, v[50:51]
	global_load_dwordx4 v[74:77], v[44:45], off
	global_load_dwordx4 v[36:39], v[44:45], off offset:1024
	global_load_dwordx2 v[72:73], v[34:35], off offset:512
	global_load_dwordx2 v[70:71], v[34:35], off offset:1024
	global_load_dwordx2 v[64:65], v[34:35], off offset:1536
	global_load_dwordx4 v[40:43], v[44:45], off offset:2048
	s_nop 0
	global_load_dwordx4 v[44:47], v[44:45], off offset:3072
	s_waitcnt vmcnt(8)
	s_nop 1
	v_mov_b32_dpp v33, v32 quad_perm:[1,0,3,2] row_mask:0xf bank_mask:0xf
	s_lshl_b64 s[6:7], s[6:7], 12
	s_add_u32 s6, s8, s6
	v_lshl_add_u64 v[62:63], v[48:49], 3, s[16:17]
	s_addc_u32 s7, s9, s7
	s_waitcnt lgkmcnt(0)
	v_add_f32_e32 v32, v32, v33
	s_nop 1
	v_mov_b32_dpp v33, v32 quad_perm:[2,3,0,1] row_mask:0xf bank_mask:0xf
	s_and_b64 vcc, exec, s[10:11]
	s_waitcnt lgkmcnt(0)
	v_add_f32_e32 v32, v32, v33
	s_nop 1
	v_mov_b32_dpp v33, v32 row_half_mirror row_mask:0xf bank_mask:0xf
	s_waitcnt lgkmcnt(0)
	v_add_f32_e32 v32, v32, v33
	s_nop 1
	v_mov_b32_dpp v33, v32 row_mirror row_mask:0xf bank_mask:0xf
	s_waitcnt lgkmcnt(0)
	v_add_f32_e32 v32, v32, v33
	v_mov_b32_e32 v33, v32
	s_nop 1
	v_permlane16_swap_b32 v32, v33
	s_waitcnt lgkmcnt(0)
	v_add_f32_e32 v32, v32, v33
	v_mov_b32_e32 v33, v32
	s_nop 1
	v_permlane32_swap_b32 v32, v33
	s_waitcnt lgkmcnt(0)
	v_add_f32_e32 v32, v32, v33
	v_fmamk_f32 v32, v32, 0x3a800000, v102
	v_mul_f32_e32 v33, 0x4b800000, v32
	v_cmp_gt_f32_e64 s[14:15], s84, v32
	s_waitcnt vmcnt(7)
	v_lshlrev_b32_e32 v34, 16, v69
	v_cndmask_b32_e64 v32, v32, v33, s[14:15]
	v_rsq_f32_e32 v32, v32
	v_and_b32_e32 v35, 0xffff0000, v69
	v_mul_f32_e32 v33, 0x45800000, v32
	v_cndmask_b32_e64 v66, v32, v33, s[14:15]
	v_lshlrev_b32_e32 v32, 16, v68
	v_and_b32_e32 v33, 0xffff0000, v68
	v_pk_mul_f32 v[34:35], v[66:67], v[34:35] op_sel_hi:[0,1]
	v_pk_mul_f32 v[32:33], v[66:67], v[32:33] op_sel_hi:[0,1]
	s_waitcnt vmcnt(6)
	v_pk_fma_f32 v[32:33], v[0:1], v[32:33], v[74:75]
	v_pk_fma_f32 v[34:35], v[2:3], v[34:35], v[76:77]
	s_cbranch_vccnz .LBB0_942
	v_lshl_add_u64 v[68:69], v[62:63], 0, s[70:71]
	v_cvt_pk_bf16_f32 v74, v32, v33
	v_cvt_pk_bf16_f32 v75, v34, v35
	s_nop 0
	v_mov_b32_e32 v208, v74
	v_mov_b32_e32 v209, v75
	s_nop 1
	v_lshl_add_u64 v[68:69], s[6:7], 0, v[50:51]
	s_cbranch_execnz .LBB0_919

.LBB0_928:
	s_and_b64 vcc, exec, s[10:11]
	s_cbranch_vccnz .LBB0_930
	v_mul_f32_e32 v60, v32, v32
	v_mul_f32_e32 v62, v34, v34
	v_fmac_f32_e32 v60, v33, v33
	v_fmac_f32_e32 v62, v35, v35
	v_add_f32_e32 v60, v62, v60
	v_mul_f32_e32 v62, v36, v36
	v_mul_f32_e32 v63, v39, v39
	v_fmac_f32_e32 v62, v37, v37
	v_fmac_f32_e32 v63, v38, v38
	v_add_f32_e32 v62, v63, v62
	v_add_f32_e32 v60, v60, v62
	v_mul_f32_e32 v62, v40, v40
	v_mul_f32_e32 v63, v43, v43
	v_fmac_f32_e32 v62, v41, v41
	v_fmac_f32_e32 v63, v42, v42
	v_add_f32_e32 v62, v63, v62
	v_add_f32_e32 v60, v60, v62
	v_mov_b32_e32 v62, v47
	v_mov_b32_e32 v63, v44
	v_pk_mul_f32 v[62:63], v[62:63], v[62:63]
	v_mov_b32_e32 v64, v46
	v_mov_b32_e32 v65, v45
	v_pk_fma_f32 v[62:63], v[64:65], v[64:65], v[62:63]
	s_lshl_b64 s[6:7], s[68:69], 10
	v_add_f32_e32 v62, v62, v63
	v_add_f32_e32 v60, v60, v62
	s_nop 1
	v_mov_b32_dpp v62, v60 quad_perm:[1,0,3,2] row_mask:0xf bank_mask:0xf
	s_waitcnt lgkmcnt(0)
	v_add_f32_e32 v60, v60, v62
	s_nop 1
	v_mov_b32_dpp v62, v60 quad_perm:[2,3,0,1] row_mask:0xf bank_mask:0xf
	s_waitcnt lgkmcnt(0)
	v_add_f32_e32 v60, v60, v62
	s_nop 1
	v_mov_b32_dpp v62, v60 row_half_mirror row_mask:0xf bank_mask:0xf
	s_waitcnt lgkmcnt(0)
	v_add_f32_e32 v60, v60, v62
	s_nop 1
	v_mov_b32_dpp v62, v60 row_mirror row_mask:0xf bank_mask:0xf
	s_waitcnt lgkmcnt(0)
	v_add_f32_e32 v60, v60, v62
	v_mov_b32_e32 v62, v60
	s_nop 1
	v_permlane16_swap_b32 v60, v62
	s_waitcnt lgkmcnt(0)
	v_add_f32_e32 v60, v60, v62
	v_mov_b32_e32 v62, v60
	s_nop 1
	v_permlane32_swap_b32 v60, v62
	s_waitcnt lgkmcnt(0)
	v_add_f32_e32 v60, v60, v62
	v_fmamk_f32 v60, v60, 0x3a800000, v102
	v_cmp_gt_f32_e32 vcc, s84, v60
	v_mul_f32_e32 v62, 0x4b800000, v60
	s_nop 0
	v_cndmask_b32_e32 v60, v60, v62, vcc
	v_rsq_f32_e32 v60, v60
	s_nop 0
	v_mul_f32_e32 v62, 0x45800000, v60
	v_cndmask_b32_e32 v60, v60, v62, vcc
	v_pk_mul_f32 v[32:33], v[32:33], v[60:61] op_sel_hi:[1,0]
	v_pk_mul_f32 v[34:35], v[34:35], v[60:61] op_sel_hi:[1,0]
	v_pk_mul_f32 v[32:33], v[8:9], v[32:33]
	v_pk_mul_f32 v[34:35], v[10:11], v[34:35]
	v_cvt_pk_bf16_f32 v32, v32, v33
	v_lshl_add_u64 v[62:63], s[6:7], 1, v[54:55]
	v_cvt_pk_bf16_f32 v33, v34, v35
	v_pk_mul_f32 v[34:35], v[38:39], v[60:61] op_sel_hi:[1,0]
	v_mov_b32_e32 v208, v32
	v_mov_b32_e32 v209, v33
	s_nop 1
	v_pk_mul_f32 v[32:33], v[36:37], v[60:61] op_sel_hi:[1,0]
	v_pk_mul_f32 v[34:35], v[6:7], v[34:35]
	v_pk_mul_f32 v[32:33], v[4:5], v[32:33]
	s_mov_b64 s[6:7], 0x600
	v_cvt_pk_bf16_f32 v32, v32, v33
	v_cvt_pk_bf16_f32 v33, v34, v35
	v_lshl_add_u64 v[34:35], v[62:63], 0, s[42:43]
	v_mov_b32_e32 v210, v32
	v_mov_b32_e32 v211, v33
	s_nop 1
	v_pk_mul_f32 v[32:33], v[40:41], v[60:61] op_sel_hi:[1,0]
	v_pk_mul_f32 v[34:35], v[42:43], v[60:61] op_sel_hi:[1,0]
	v_pk_mul_f32 v[32:33], v[24:25], v[32:33]
	v_pk_mul_f32 v[34:35], v[26:27], v[34:35]
	v_cvt_pk_bf16_f32 v32, v32, v33
	s_nop 0
	v_cvt_pk_bf16_f32 v33, v34, v35
	v_lshl_add_u64 v[34:35], v[62:63], 0, s[28:29]
	v_mov_b32_e32 v212, v32
	v_mov_b32_e32 v213, v33
	s_nop 1
	v_pk_mul_f32 v[32:33], v[44:45], v[60:61] op_sel_hi:[1,0]
	v_pk_mul_f32 v[34:35], v[46:47], v[60:61] op_sel_hi:[1,0]
	v_pk_mul_f32 v[32:33], v[20:21], v[32:33]
	v_pk_mul_f32 v[34:35], v[22:23], v[34:35]
	v_cvt_pk_bf16_f32 v32, v32, v33
	s_nop 0
	v_cvt_pk_bf16_f32 v33, v34, v35
	v_lshl_add_u64 v[34:35], v[62:63], 0, s[6:7]
	v_and_b32_e32 v232, 1, v152
	v_cmp_eq_u32_e64 s[98:99], 1, v232
	v_mul_u32_u24_e32 v230, 0x1f8, v232
	v_mov_b32_e32 v231, 0
	v_lshl_add_u64 v[228:229], v[34:35], 0, v[230:231]
	v_cndmask_b32_e64 v216, v210, v208, s[98:99]
	v_cndmask_b32_e64 v217, v211, v209, s[98:99]
	s_nop 1
	v_mov_b32_dpp v218, v216 quad_perm:[1,0,3,2] row_mask:0xf bank_mask:0xf
	v_mov_b32_dpp v219, v217 quad_perm:[1,0,3,2] row_mask:0xf bank_mask:0xf
	v_cndmask_b32_e64 v220, v208, v218, s[98:99]
	v_cndmask_b32_e64 v221, v209, v219, s[98:99]
	v_cndmask_b32_e64 v222, v218, v210, s[98:99]
	v_cndmask_b32_e64 v223, v219, v211, s[98:99]
	global_store_dwordx4 v[228:229], v[220:223], off offset:-1536 sc0 sc1
	s_nop 1
	v_cndmask_b32_e64 v216, v32, v212, s[98:99]
	v_cndmask_b32_e64 v217, v33, v213, s[98:99]
	s_nop 1
	v_mov_b32_dpp v218, v216 quad_perm:[1,0,3,2] row_mask:0xf bank_mask:0xf
	v_mov_b32_dpp v219, v217 quad_perm:[1,0,3,2] row_mask:0xf bank_mask:0xf
	v_cndmask_b32_e64 v224, v212, v218, s[98:99]
	v_cndmask_b32_e64 v225, v213, v219, s[98:99]
	v_cndmask_b32_e64 v226, v218, v32, s[98:99]
	v_cndmask_b32_e64 v227, v219, v33, s[98:99]
	global_store_dwordx4 v[228:229], v[224:227], off offset:-512 sc0 sc1
	s_nop 1
	s_mov_b32 s99, 0
	s_nop 1

.LBB0_998:
	s_or_b64 exec, exec, s[40:41]
	s_lshl_b64 s[0:1], s[0:1], 12
	s_add_u32 s0, s38, s0
	s_addc_u32 s1, s39, s1
	s_lshl_b64 s[16:17], s[68:69], 11
	v_lshl_add_u64 v[34:35], v[56:57], 0, s[16:17]
	global_load_dwordx2 v[68:69], v[34:35], off
	s_lshl_b64 s[14:15], s[14:15], 12
	s_add_u32 s14, s36, s14
	s_addc_u32 s15, s37, s15
	v_lshl_add_u64 v[44:45], s[14:15], 0, v[50:51]
	global_load_dwordx4 v[74:77], v[44:45], off
	global_load_dwordx4 v[36:39], v[44:45], off offset:1024
	global_load_dwordx2 v[72:73], v[34:35], off offset:512
	global_load_dwordx2 v[70:71], v[34:35], off offset:1024
	global_load_dwordx2 v[64:65], v[34:35], off offset:1536
	global_load_dwordx4 v[40:43], v[44:45], off offset:2048
	s_nop 0
	global_load_dwordx4 v[44:47], v[44:45], off offset:3072
	s_waitcnt vmcnt(8)
	s_nop 1
	v_mov_b32_dpp v33, v32 quad_perm:[1,0,3,2] row_mask:0xf bank_mask:0xf
	v_lshl_add_u64 v[62:63], v[48:49], 3, s[0:1]
	s_lshl_b64 s[6:7], s[6:7], 12
	s_add_u32 s6, s8, s6
	s_addc_u32 s7, s9, s7
	s_waitcnt lgkmcnt(0)
	v_add_f32_e32 v32, v32, v33
	s_nop 1
	v_mov_b32_dpp v33, v32 quad_perm:[2,3,0,1] row_mask:0xf bank_mask:0xf
	s_and_b64 vcc, exec, s[10:11]
	s_waitcnt lgkmcnt(0)
	v_add_f32_e32 v32, v32, v33
	s_nop 1
	v_mov_b32_dpp v33, v32 row_half_mirror row_mask:0xf bank_mask:0xf
	s_waitcnt lgkmcnt(0)
	v_add_f32_e32 v32, v32, v33
	s_nop 1
	v_mov_b32_dpp v33, v32 row_mirror row_mask:0xf bank_mask:0xf
	s_waitcnt lgkmcnt(0)
	v_add_f32_e32 v32, v32, v33
	v_mov_b32_e32 v33, v32
	s_nop 1
	v_permlane16_swap_b32 v32, v33
	s_waitcnt lgkmcnt(0)
	v_add_f32_e32 v32, v32, v33
	v_mov_b32_e32 v33, v32
	s_nop 1
	v_permlane32_swap_b32 v32, v33
	s_waitcnt lgkmcnt(0)
	v_add_f32_e32 v32, v32, v33
	v_fmamk_f32 v32, v32, 0x3a800000, v102
	v_mul_f32_e32 v33, 0x4b800000, v32
	v_cmp_gt_f32_e64 s[0:1], s84, v32
	s_waitcnt vmcnt(7)
	v_lshlrev_b32_e32 v34, 16, v69
	v_cndmask_b32_e64 v32, v32, v33, s[0:1]
	v_rsq_f32_e32 v32, v32
	v_and_b32_e32 v35, 0xffff0000, v69
	v_mul_f32_e32 v33, 0x45800000, v32
	v_cndmask_b32_e64 v66, v32, v33, s[0:1]
	v_lshlrev_b32_e32 v32, 16, v68
	v_and_b32_e32 v33, 0xffff0000, v68
	v_pk_mul_f32 v[34:35], v[66:67], v[34:35] op_sel_hi:[0,1]
	v_pk_mul_f32 v[32:33], v[66:67], v[32:33] op_sel_hi:[0,1]
	s_waitcnt vmcnt(6)
	v_pk_fma_f32 v[32:33], v[0:1], v[32:33], v[74:75]
	v_pk_fma_f32 v[34:35], v[2:3], v[34:35], v[76:77]
	s_cbranch_vccnz .LBB0_1012
	v_lshl_add_u64 v[68:69], v[62:63], 0, s[70:71]
	v_cvt_pk_bf16_f32 v74, v32, v33
	v_cvt_pk_bf16_f32 v75, v34, v35
	s_nop 0
	v_mov_b32_e32 v208, v74
	v_mov_b32_e32 v209, v75
	s_nop 1
	v_lshl_add_u64 v[68:69], s[6:7], 0, v[50:51]
	s_cbranch_execnz .LBB0_1001

.LBB0_1010:
	s_and_b64 vcc, exec, s[10:11]
	s_cbranch_vccnz .LBB0_728
	v_mul_f32_e32 v60, v32, v32
	v_mul_f32_e32 v62, v34, v34
	v_fmac_f32_e32 v60, v33, v33
	v_fmac_f32_e32 v62, v35, v35
	v_add_f32_e32 v60, v62, v60
	v_mul_f32_e32 v62, v36, v36
	v_mul_f32_e32 v63, v39, v39
	v_fmac_f32_e32 v62, v37, v37
	v_fmac_f32_e32 v63, v38, v38
	v_add_f32_e32 v62, v63, v62
	v_add_f32_e32 v60, v60, v62
	v_mul_f32_e32 v62, v40, v40
	v_mul_f32_e32 v63, v43, v43
	v_fmac_f32_e32 v62, v41, v41
	v_fmac_f32_e32 v63, v42, v42
	v_add_f32_e32 v62, v63, v62
	v_add_f32_e32 v60, v60, v62
	v_mov_b32_e32 v62, v47
	v_mov_b32_e32 v63, v44
	v_pk_mul_f32 v[62:63], v[62:63], v[62:63]
	v_mov_b32_e32 v64, v46
	v_mov_b32_e32 v65, v45
	v_pk_fma_f32 v[62:63], v[64:65], v[64:65], v[62:63]
	s_lshl_b64 s[0:1], s[68:69], 10
	v_add_f32_e32 v62, v62, v63
	v_add_f32_e32 v60, v60, v62
	s_nop 1
	v_mov_b32_dpp v62, v60 quad_perm:[1,0,3,2] row_mask:0xf bank_mask:0xf
	s_waitcnt lgkmcnt(0)
	v_add_f32_e32 v60, v60, v62
	s_nop 1
	v_mov_b32_dpp v62, v60 quad_perm:[2,3,0,1] row_mask:0xf bank_mask:0xf
	s_waitcnt lgkmcnt(0)
	v_add_f32_e32 v60, v60, v62
	s_nop 1
	v_mov_b32_dpp v62, v60 row_half_mirror row_mask:0xf bank_mask:0xf
	s_waitcnt lgkmcnt(0)
	v_add_f32_e32 v60, v60, v62
	s_nop 1
	v_mov_b32_dpp v62, v60 row_mirror row_mask:0xf bank_mask:0xf
	s_waitcnt lgkmcnt(0)
	v_add_f32_e32 v60, v60, v62
	v_mov_b32_e32 v62, v60
	s_nop 1
	v_permlane16_swap_b32 v60, v62
	s_waitcnt lgkmcnt(0)
	v_add_f32_e32 v60, v60, v62
	v_mov_b32_e32 v62, v60
	s_nop 1
	v_permlane32_swap_b32 v60, v62
	s_waitcnt lgkmcnt(0)
	v_add_f32_e32 v60, v60, v62
	v_fmamk_f32 v60, v60, 0x3a800000, v102
	v_mul_f32_e32 v62, 0x4b800000, v60
	v_cmp_gt_f32_e32 vcc, s84, v60
	s_nop 1
	v_cndmask_b32_e32 v60, v60, v62, vcc
	v_rsq_f32_e32 v60, v60
	v_lshl_add_u64 v[62:63], s[0:1], 1, v[54:55]
	s_mov_b64 s[0:1], 0x600
	v_mul_f32_e32 v64, 0x45800000, v60
	v_cndmask_b32_e32 v60, v60, v64, vcc
	v_pk_mul_f32 v[32:33], v[32:33], v[60:61] op_sel_hi:[1,0]
	v_pk_mul_f32 v[34:35], v[34:35], v[60:61] op_sel_hi:[1,0]
	v_pk_mul_f32 v[32:33], v[8:9], v[32:33]
	v_pk_mul_f32 v[36:37], v[36:37], v[60:61] op_sel_hi:[1,0]
	v_pk_mul_f32 v[38:39], v[38:39], v[60:61] op_sel_hi:[1,0]
	v_pk_mul_f32 v[34:35], v[10:11], v[34:35]
	v_cvt_pk_bf16_f32 v32, v32, v33
	s_nop 0
	v_cvt_pk_bf16_f32 v33, v34, v35
	v_pk_mul_f32 v[34:35], v[4:5], v[36:37]
	v_mov_b32_e32 v208, v32
	v_mov_b32_e32 v209, v33
	s_nop 1
	v_pk_mul_f32 v[32:33], v[6:7], v[38:39]
	v_cvt_pk_bf16_f32 v34, v34, v35
	s_nop 0
	v_cvt_pk_bf16_f32 v35, v32, v33
	v_lshl_add_u64 v[32:33], v[62:63], 0, s[42:43]
	v_mov_b32_e32 v210, v34
	v_mov_b32_e32 v211, v35
	s_nop 1
	v_pk_mul_f32 v[32:33], v[40:41], v[60:61] op_sel_hi:[1,0]
	v_pk_mul_f32 v[34:35], v[42:43], v[60:61] op_sel_hi:[1,0]
	v_pk_mul_f32 v[32:33], v[24:25], v[32:33]
	v_pk_mul_f32 v[34:35], v[26:27], v[34:35]
	v_cvt_pk_bf16_f32 v32, v32, v33
	s_nop 0
	v_cvt_pk_bf16_f32 v33, v34, v35
	v_lshl_add_u64 v[34:35], v[62:63], 0, s[28:29]
	v_mov_b32_e32 v212, v32
	v_mov_b32_e32 v213, v33
	s_nop 1
	v_pk_mul_f32 v[32:33], v[44:45], v[60:61] op_sel_hi:[1,0]
	v_pk_mul_f32 v[34:35], v[46:47], v[60:61] op_sel_hi:[1,0]
	v_pk_mul_f32 v[32:33], v[20:21], v[32:33]
	v_pk_mul_f32 v[34:35], v[22:23], v[34:35]
	v_cvt_pk_bf16_f32 v32, v32, v33
	s_nop 0
	v_cvt_pk_bf16_f32 v33, v34, v35
	v_lshl_add_u64 v[34:35], v[62:63], 0, s[0:1]
	v_and_b32_e32 v232, 1, v152
	v_cmp_eq_u32_e64 s[98:99], 1, v232
	v_mul_u32_u24_e32 v230, 0x1f8, v232
	v_mov_b32_e32 v231, 0
	v_lshl_add_u64 v[228:229], v[34:35], 0, v[230:231]
	v_cndmask_b32_e64 v216, v210, v208, s[98:99]
	v_cndmask_b32_e64 v217, v211, v209, s[98:99]
	s_nop 1
	v_mov_b32_dpp v218, v216 quad_perm:[1,0,3,2] row_mask:0xf bank_mask:0xf
	v_mov_b32_dpp v219, v217 quad_perm:[1,0,3,2] row_mask:0xf bank_mask:0xf
	v_cndmask_b32_e64 v220, v208, v218, s[98:99]
	v_cndmask_b32_e64 v221, v209, v219, s[98:99]
	v_cndmask_b32_e64 v222, v218, v210, s[98:99]
	v_cndmask_b32_e64 v223, v219, v211, s[98:99]
	global_store_dwordx4 v[228:229], v[220:223], off offset:-1536 sc0 sc1
	s_nop 1
	v_cndmask_b32_e64 v216, v32, v212, s[98:99]
	v_cndmask_b32_e64 v217, v33, v213, s[98:99]
	s_nop 1
	v_mov_b32_dpp v218, v216 quad_perm:[1,0,3,2] row_mask:0xf bank_mask:0xf
	v_mov_b32_dpp v219, v217 quad_perm:[1,0,3,2] row_mask:0xf bank_mask:0xf
	v_cndmask_b32_e64 v224, v212, v218, s[98:99]
	v_cndmask_b32_e64 v225, v213, v219, s[98:99]
	v_cndmask_b32_e64 v226, v218, v32, s[98:99]
	v_cndmask_b32_e64 v227, v219, v33, s[98:99]
	global_store_dwordx4 v[228:229], v[224:227], off offset:-512 sc0 sc1
	s_nop 1
	s_mov_b32 s99, 0
	s_nop 1
	s_branch .LBB0_728

.LBB0_1351:
	s_or_b64 exec, exec, s[8:9]
	s_lshl_b64 s[0:1], s[0:1], 12
	s_add_u32 s0, s6, s0
	s_addc_u32 s1, s7, s1
	v_lshl_add_u64 v[44:45], v[32:33], 3, s[0:1]
	s_lshl_b64 s[0:1], s[56:57], 11
	v_lshl_add_u64 v[54:55], v[38:39], 0, s[0:1]
	global_load_dwordx2 v[46:47], v[44:45], off offset:2048
	global_load_dwordx2 v[48:49], v[44:45], off offset:2560
	global_load_dwordx2 v[50:51], v[44:45], off offset:3072
	global_load_dwordx2 v[52:53], v[44:45], off offset:3584
	global_load_dwordx2 v[56:57], v[54:55], off
	global_load_dwordx2 v[58:59], v[54:55], off offset:512
	global_load_dwordx2 v[60:61], v[54:55], off offset:1024
	s_nop 0
	global_load_dwordx2 v[54:55], v[54:55], off offset:1536
	s_waitcnt vmcnt(8)
	s_nop 1
	v_mov_b32_dpp v62, v42 quad_perm:[1,0,3,2] row_mask:0xf bank_mask:0xf
	s_waitcnt lgkmcnt(0)
	v_add_f32_e32 v42, v42, v62
	s_nop 1
	v_mov_b32_dpp v62, v42 quad_perm:[2,3,0,1] row_mask:0xf bank_mask:0xf
	s_waitcnt lgkmcnt(0)
	v_add_f32_e32 v42, v42, v62
	s_nop 1
	v_mov_b32_dpp v62, v42 row_half_mirror row_mask:0xf bank_mask:0xf
	s_waitcnt lgkmcnt(0)
	v_add_f32_e32 v42, v42, v62
	s_nop 1
	v_mov_b32_dpp v62, v42 row_mirror row_mask:0xf bank_mask:0xf
	s_waitcnt lgkmcnt(0)
	v_add_f32_e32 v42, v42, v62
	v_mov_b32_e32 v62, v42
	s_nop 1
	v_permlane16_swap_b32 v42, v62
	s_waitcnt lgkmcnt(0)
	v_add_f32_e32 v42, v42, v62
	v_mov_b32_e32 v62, v42
	s_nop 1
	v_permlane32_swap_b32 v42, v62
	s_waitcnt lgkmcnt(0)
	v_add_f32_e32 v42, v42, v62
	v_fmamk_f32 v42, v42, 0x3a800000, v146
	v_mul_f32_e32 v62, 0x4b800000, v42
	v_cmp_gt_f32_e32 vcc, s97, v42
	s_waitcnt vmcnt(7)
	v_and_b32_e32 v63, 0xffff0000, v46
	v_cndmask_b32_e32 v42, v42, v62, vcc
	v_rsq_f32_e32 v42, v42
	s_waitcnt vmcnt(3)
	v_lshlrev_b32_e32 v70, 16, v56
	v_and_b32_e32 v71, 0xffff0000, v56
	v_lshlrev_b32_e32 v56, 16, v57
	v_mul_f32_e32 v62, 0x45800000, v42
	v_cndmask_b32_e32 v42, v42, v62, vcc
	v_and_b32_e32 v57, 0xffff0000, v57
	s_waitcnt vmcnt(2)
	v_lshlrev_b32_e32 v72, 16, v58
	v_and_b32_e32 v73, 0xffff0000, v58
	v_lshlrev_b32_e32 v58, 16, v59
	v_and_b32_e32 v59, 0xffff0000, v59
	v_lshlrev_b32_e32 v62, 16, v46
	v_lshlrev_b32_e32 v46, 16, v47
	v_and_b32_e32 v47, 0xffff0000, v47
	v_lshlrev_b32_e32 v64, 16, v48
	v_and_b32_e32 v65, 0xffff0000, v48
	v_lshlrev_b32_e32 v48, 16, v49
	v_and_b32_e32 v49, 0xffff0000, v49
	s_waitcnt vmcnt(1)
	v_lshlrev_b32_e32 v74, 16, v60
	v_and_b32_e32 v75, 0xffff0000, v60
	v_lshlrev_b32_e32 v60, 16, v61
	v_and_b32_e32 v61, 0xffff0000, v61
	v_pk_mul_f32 v[70:71], v[42:43], v[70:71] op_sel_hi:[0,1]
	v_pk_mul_f32 v[56:57], v[42:43], v[56:57] op_sel_hi:[0,1]
	v_pk_mul_f32 v[58:59], v[42:43], v[58:59] op_sel_hi:[0,1]
	v_pk_mul_f32 v[72:73], v[42:43], v[72:73] op_sel_hi:[0,1]
	v_lshlrev_b32_e32 v66, 16, v50
	v_and_b32_e32 v67, 0xffff0000, v50
	v_lshlrev_b32_e32 v50, 16, v51
	v_and_b32_e32 v51, 0xffff0000, v51
	v_pk_mul_f32 v[60:61], v[42:43], v[60:61] op_sel_hi:[0,1]
	v_pk_mul_f32 v[74:75], v[42:43], v[74:75] op_sel_hi:[0,1]
	v_pk_fma_f32 v[46:47], v[2:3], v[56:57], v[46:47]
	v_pk_fma_f32 v[56:57], v[0:1], v[70:71], v[62:63]
	v_pk_fma_f32 v[62:63], v[4:5], v[72:73], v[64:65]
	v_pk_fma_f32 v[48:49], v[6:7], v[58:59], v[48:49]
	v_pk_fma_f32 v[58:59], v[16:17], v[74:75], v[66:67]
	v_pk_fma_f32 v[50:51], v[18:19], v[60:61], v[50:51]
	v_pk_mul_f32 v[60:61], v[46:47], v[46:47]
	v_pk_mul_f32 v[64:65], v[56:57], v[56:57]
	v_pk_mul_f32 v[66:67], v[48:49], v[48:49]
	v_pk_mul_f32 v[70:71], v[62:63], v[62:63]
	v_pk_mov_b32 v[74:75], v[64:65], v[60:61] op_sel:[1,0]
	v_mov_b32_e32 v65, v61
	v_pk_mov_b32 v[60:61], v[70:71], v[66:67] op_sel:[1,0]
	v_mov_b32_e32 v71, v67
	v_pk_add_f32 v[60:61], v[60:61], v[70:71]
	s_waitcnt vmcnt(0)
	v_lshlrev_b32_e32 v76, 16, v54
	v_and_b32_e32 v77, 0xffff0000, v54
	v_lshlrev_b32_e32 v54, 16, v55
	v_and_b32_e32 v55, 0xffff0000, v55
	v_mul_f32_e32 v72, v58, v58
	v_pk_add_f32 v[60:61], v[60:61], v[60:61] op_sel_hi:[0,1]
	v_lshlrev_b32_e32 v68, 16, v52
	v_and_b32_e32 v69, 0xffff0000, v52
	v_lshlrev_b32_e32 v52, 16, v53
	v_and_b32_e32 v53, 0xffff0000, v53
	v_pk_fma_f32 v[66:67], v[58:59], v[58:59], v[72:73] op_sel_hi:[1,1,0]
	v_pk_add_f32 v[64:65], v[74:75], v[64:65]
	v_mul_f32_e32 v60, v50, v50
	v_pk_mul_f32 v[54:55], v[42:43], v[54:55] op_sel_hi:[0,1]
	v_pk_mul_f32 v[72:73], v[42:43], v[76:77] op_sel_hi:[0,1]
	v_pk_add_f32 v[64:65], v[64:65], v[64:65] op_sel_hi:[0,1]
	v_pk_fma_f32 v[70:71], v[50:51], v[50:51], v[60:61] op_sel_hi:[1,1,0]
	v_pk_fma_f32 v[68:69], v[20:21], v[72:73], v[68:69]
	v_pk_fma_f32 v[52:53], v[22:23], v[54:55], v[52:53]
	v_mul_f32_e32 v66, v68, v68
	v_mul_f32_e32 v70, v69, v69
	v_mul_f32_e32 v64, v52, v52
	v_mul_f32_e32 v60, v53, v53
	v_pk_add_f32 v[54:55], v[66:67], v[70:71]
	v_pk_add_f32 v[60:61], v[64:65], v[60:61]
	v_cvt_pk_bf16_f32 v66, v56, v57
	v_lshl_add_u64 v[64:65], v[44:45], 0, s[68:69]
	v_pk_add_f32 v[54:55], v[54:55], v[60:61]
	s_nop 0
	v_add_f32_e32 v42, v54, v55
	s_nop 1
	v_mov_b32_dpp v54, v42 quad_perm:[1,0,3,2] row_mask:0xf bank_mask:0xf
	s_waitcnt lgkmcnt(0)
	v_add_f32_e32 v42, v42, v54
	s_nop 1
	v_mov_b32_dpp v54, v42 quad_perm:[2,3,0,1] row_mask:0xf bank_mask:0xf
	s_waitcnt lgkmcnt(0)
	v_add_f32_e32 v42, v42, v54
	s_nop 1
	v_mov_b32_dpp v60, v42 row_half_mirror row_mask:0xf bank_mask:0xf
	v_lshl_add_u64 v[54:55], v[44:45], 0, s[62:63]
	s_waitcnt lgkmcnt(0)
	v_add_f32_e32 v42, v42, v60
	s_nop 1
	v_mov_b32_dpp v67, v42 row_mirror row_mask:0xf bank_mask:0xf
	v_lshl_add_u64 v[60:61], v[44:45], 0, s[64:65]
	v_lshl_add_u64 v[44:45], v[44:45], 0, s[70:71]
	s_waitcnt lgkmcnt(0)
	v_add_f32_e32 v42, v42, v67
	v_mov_b32_e32 v70, v42
	s_nop 1
	v_permlane16_swap_b32 v42, v70
	v_cvt_pk_bf16_f32 v67, v46, v47
	s_waitcnt lgkmcnt(0)
	v_add_f32_e32 v42, v42, v70
	v_mov_b32_e32 v208, v66
	v_mov_b32_e32 v209, v67
	s_nop 1
	v_mov_b32_e32 v66, v42
	s_nop 1
	v_permlane32_swap_b32 v42, v66
	v_cvt_pk_bf16_f32 v54, v62, v63
	v_cvt_pk_bf16_f32 v55, v48, v49
	s_waitcnt lgkmcnt(0)
	v_add_f32_e32 v42, v42, v66
	v_mov_b32_e32 v210, v54
	v_mov_b32_e32 v211, v55
	s_nop 1
	v_cvt_pk_bf16_f32 v54, v58, v59
	v_fmamk_f32 v42, v42, 0x3a800000, v146
	v_cvt_pk_bf16_f32 v55, v50, v51
	v_cmp_gt_f32_e32 vcc, s97, v42
	v_mov_b32_e32 v212, v54
	v_mov_b32_e32 v213, v55
	s_nop 1
	v_mul_f32_e32 v54, 0x4b800000, v42
	s_nop 0
	v_cndmask_b32_e32 v42, v42, v54, vcc
	v_rsq_f32_e32 v42, v42
	v_cvt_pk_bf16_f32 v54, v68, v69
	v_cvt_pk_bf16_f32 v55, v52, v53
	s_nop 0
	v_and_b32_e32 v232, 1, v152
	v_cmp_eq_u32_e64 s[98:99], 1, v232
	v_mul_u32_u24_e32 v230, 0x1f8, v232
	v_mov_b32_e32 v231, 0
	v_lshl_add_u64 v[228:229], v[44:45], 0, v[230:231]
	v_cndmask_b32_e64 v216, v210, v208, s[98:99]
	v_cndmask_b32_e64 v217, v211, v209, s[98:99]
	s_nop 1
	v_mov_b32_dpp v218, v216 quad_perm:[1,0,3,2] row_mask:0xf bank_mask:0xf
	v_mov_b32_dpp v219, v217 quad_perm:[1,0,3,2] row_mask:0xf bank_mask:0xf
	v_cndmask_b32_e64 v220, v208, v218, s[98:99]
	v_cndmask_b32_e64 v221, v209, v219, s[98:99]
	v_cndmask_b32_e64 v222, v218, v210, s[98:99]
	v_cndmask_b32_e64 v223, v219, v211, s[98:99]
	global_store_dwordx4 v[228:229], v[220:223], off offset:-1536 sc0 sc1
	s_nop 1
	v_cndmask_b32_e64 v216, v54, v212, s[98:99]
	v_cndmask_b32_e64 v217, v55, v213, s[98:99]
	s_nop 1
	v_mov_b32_dpp v218, v216 quad_perm:[1,0,3,2] row_mask:0xf bank_mask:0xf
	v_mov_b32_dpp v219, v217 quad_perm:[1,0,3,2] row_mask:0xf bank_mask:0xf
	v_cndmask_b32_e64 v224, v212, v218, s[98:99]
	v_cndmask_b32_e64 v225, v213, v219, s[98:99]
	v_cndmask_b32_e64 v226, v218, v54, s[98:99]
	v_cndmask_b32_e64 v227, v219, v55, s[98:99]
	global_store_dwordx4 v[228:229], v[224:227], off offset:-512 sc0 sc1
	s_nop 1
	s_mov_b32 s99, 0
	s_nop 1
	v_mul_f32_e32 v44, 0x45800000, v42
	v_cndmask_b32_e32 v42, v42, v44, vcc
	v_pk_mul_f32 v[54:55], v[56:57], v[42:43] op_sel_hi:[1,0]
	v_pk_mul_f32 v[46:47], v[46:47], v[42:43] op_sel_hi:[1,0]
	v_pk_mul_f32 v[54:55], v[24:25], v[54:55]
	v_pk_mul_f32 v[46:47], v[26:27], v[46:47]
	v_cvt_pk_bf16_f32 v54, v54, v55
	v_pk_mul_f32 v[48:49], v[48:49], v[42:43] op_sel_hi:[1,0]
	v_cvt_pk_bf16_f32 v55, v46, v47
	v_pk_mul_f32 v[46:47], v[62:63], v[42:43] op_sel_hi:[1,0]
	v_lshl_add_u64 v[44:45], v[36:37], 0, s[0:1]
	v_pk_mul_f32 v[46:47], v[8:9], v[46:47]
	v_mov_b32_e32 v208, v54
	v_mov_b32_e32 v209, v55
	s_nop 1
	v_pk_mul_f32 v[48:49], v[10:11], v[48:49]
	v_cvt_pk_bf16_f32 v46, v46, v47
	s_nop 0
	v_cvt_pk_bf16_f32 v47, v48, v49
	v_lshl_add_u64 v[48:49], v[44:45], 0, s[72:73]
	v_mov_b32_e32 v210, v46
	v_mov_b32_e32 v211, v47
	s_nop 1
	v_pk_mul_f32 v[46:47], v[58:59], v[42:43] op_sel_hi:[1,0]
	v_pk_mul_f32 v[48:49], v[50:51], v[42:43] op_sel_hi:[1,0]
	v_pk_mul_f32 v[46:47], v[12:13], v[46:47]
	v_pk_mul_f32 v[48:49], v[14:15], v[48:49]
	v_cvt_pk_bf16_f32 v46, v46, v47
	s_nop 0
	v_cvt_pk_bf16_f32 v47, v48, v49
	v_lshl_add_u64 v[48:49], v[44:45], 0, s[74:75]
	v_mov_b32_e32 v212, v46
	v_mov_b32_e32 v213, v47
	s_nop 1
	v_pk_mul_f32 v[46:47], v[68:69], v[42:43] op_sel_hi:[1,0]
	v_pk_mul_f32 v[48:49], v[52:53], v[42:43] op_sel_hi:[1,0]
	v_pk_mul_f32 v[46:47], v[28:29], v[46:47]
	v_pk_mul_f32 v[48:49], v[30:31], v[48:49]
	v_cvt_pk_bf16_f32 v46, v46, v47
	v_lshl_add_u64 v[44:45], v[44:45], 0, s[78:79]
	v_cvt_pk_bf16_f32 v47, v48, v49
	s_nop 0
	v_and_b32_e32 v232, 1, v152
	v_cmp_eq_u32_e64 s[98:99], 1, v232
	v_mul_u32_u24_e32 v230, 0x1f8, v232
	v_mov_b32_e32 v231, 0
	v_lshl_add_u64 v[228:229], v[44:45], 0, v[230:231]
	v_cndmask_b32_e64 v216, v210, v208, s[98:99]
	v_cndmask_b32_e64 v217, v211, v209, s[98:99]
	s_nop 1
	v_mov_b32_dpp v218, v216 quad_perm:[1,0,3,2] row_mask:0xf bank_mask:0xf
	v_mov_b32_dpp v219, v217 quad_perm:[1,0,3,2] row_mask:0xf bank_mask:0xf
	v_cndmask_b32_e64 v220, v208, v218, s[98:99]
	v_cndmask_b32_e64 v221, v209, v219, s[98:99]
	v_cndmask_b32_e64 v222, v218, v210, s[98:99]
	v_cndmask_b32_e64 v223, v219, v211, s[98:99]
	global_store_dwordx4 v[228:229], v[220:223], off offset:-1536 sc0 sc1
	s_nop 1
	v_cndmask_b32_e64 v216, v46, v212, s[98:99]
	v_cndmask_b32_e64 v217, v47, v213, s[98:99]
	s_nop 1
	v_mov_b32_dpp v218, v216 quad_perm:[1,0,3,2] row_mask:0xf bank_mask:0xf
	v_mov_b32_dpp v219, v217 quad_perm:[1,0,3,2] row_mask:0xf bank_mask:0xf
	v_cndmask_b32_e64 v224, v212, v218, s[98:99]
	v_cndmask_b32_e64 v225, v213, v219, s[98:99]
	v_cndmask_b32_e64 v226, v218, v46, s[98:99]
	v_cndmask_b32_e64 v227, v219, v47, s[98:99]
	global_store_dwordx4 v[228:229], v[224:227], off offset:-512 sc0 sc1
	s_nop 1
	s_mov_b32 s99, 0
	s_nop 1

.LBB0_1395:
	global_load_dwordx2 v[76:77], v[50:51], off offset:2048
	global_load_dwordx2 v[78:79], v[50:51], off offset:2560
	global_load_dwordx2 v[80:81], v[50:51], off offset:3072
	global_load_dwordx2 v[82:83], v[50:51], off offset:3584
	global_load_dwordx2 v[88:89], v[52:53], off offset:2048
	global_load_dwordx2 v[96:97], v[52:53], off offset:2560
	global_load_dwordx2 v[106:107], v[52:53], off offset:3072
	global_load_dwordx2 v[108:109], v[52:53], off offset:3584
	global_load_dwordx2 v[118:119], v[54:55], off offset:2048
	global_load_dwordx2 v[122:123], v[54:55], off offset:2560
	global_load_dwordx2 v[124:125], v[54:55], off offset:3072
	global_load_dwordx2 v[126:127], v[54:55], off offset:3584
	global_load_dwordx2 v[128:129], v[56:57], off offset:2048
	global_load_dwordx2 v[110:111], v[56:57], off offset:2560
	global_load_dwordx2 v[84:85], v[56:57], off offset:3072
	global_load_dwordx2 v[72:73], v[56:57], off offset:3584
	global_load_dwordx2 v[130:131], v[58:59], off offset:2048
	global_load_dwordx2 v[114:115], v[58:59], off offset:2560
	global_load_dwordx2 v[86:87], v[58:59], off offset:3072
	global_load_dwordx2 v[74:75], v[58:59], off offset:3584
	global_load_dwordx2 v[132:133], v[60:61], off offset:2048
	global_load_dwordx2 v[120:121], v[60:61], off offset:2560
	global_load_dwordx2 v[90:91], v[60:61], off offset:3072
	s_nop 0
	global_load_dwordx2 v[60:61], v[60:61], off offset:3584
	s_nop 0
	global_load_dwordx2 v[134:135], v[62:63], off offset:2048
	global_load_dwordx2 v[136:137], v[62:63], off offset:2560
	global_load_dwordx2 v[92:93], v[62:63], off offset:3072
	s_nop 0
	global_load_dwordx2 v[62:63], v[62:63], off offset:3584
	s_nop 0
	global_load_dwordx2 v[138:139], v[64:65], off offset:2048
	global_load_dwordx2 v[140:141], v[64:65], off offset:2560
	global_load_dwordx2 v[94:95], v[64:65], off offset:3072
	s_nop 0
	global_load_dwordx2 v[64:65], v[64:65], off offset:3584
	s_nop 0
	global_load_dwordx2 v[142:143], v[66:67], off offset:2048
	global_load_dwordx2 v[144:145], v[66:67], off offset:2560
	global_load_dwordx2 v[98:99], v[66:67], off offset:3072
	s_nop 0
	global_load_dwordx2 v[66:67], v[66:67], off offset:3584
	s_nop 0
	global_load_dwordx2 v[156:157], v[68:69], off offset:2048
	global_load_dwordx2 v[158:159], v[68:69], off offset:2560
	global_load_dwordx2 v[100:101], v[68:69], off offset:3072
	s_nop 0
	global_load_dwordx2 v[68:69], v[68:69], off offset:3584
	s_nop 0
	global_load_dwordx2 v[160:161], v[70:71], off offset:2048
	global_load_dwordx2 v[162:163], v[70:71], off offset:2560
	global_load_dwordx2 v[102:103], v[70:71], off offset:3072
	s_nop 0
	global_load_dwordx2 v[70:71], v[70:71], off offset:3584
	s_lshl_b64 s[8:9], s[8:9], 12
	s_add_u32 s6, s6, s8
	s_addc_u32 s7, s7, s9
	v_lshl_add_u64 v[50:51], v[32:33], 3, s[6:7]
	global_load_dwordx2 v[58:59], v[50:51], off offset:2048
	global_load_dwordx2 v[56:57], v[50:51], off offset:2560
	global_load_dwordx2 v[54:55], v[50:51], off offset:3072
	global_load_dwordx2 v[52:53], v[50:51], off offset:3584
	s_mov_b64 s[6:7], 0x3800800
	s_add_u32 s82, s82, 0x1000
	s_addc_u32 s83, s83, 0
	s_add_i32 s12, s12, 2
	s_add_u32 s0, s0, 2
	s_addc_u32 s1, s1, 0
	s_add_i32 s3, s3, 2
	s_cmpk_lg_i32 s82, 0x2000
	s_waitcnt vmcnt(37)
	v_lshlrev_b32_e32 v184, 16, v124
	v_and_b32_e32 v185, 0xffff0000, v124
	v_lshlrev_b32_e32 v164, 16, v76
	v_and_b32_e32 v165, 0xffff0000, v76
	v_lshlrev_b32_e32 v166, 16, v77
	v_and_b32_e32 v167, 0xffff0000, v77
	v_lshlrev_b32_e32 v76, 16, v88
	v_and_b32_e32 v77, 0xffff0000, v88
	v_lshlrev_b32_e32 v174, 16, v96
	v_and_b32_e32 v175, 0xffff0000, v96
	v_lshlrev_b32_e32 v176, 16, v97
	v_and_b32_e32 v177, 0xffff0000, v97
	v_lshlrev_b32_e32 v96, 16, v118
	v_and_b32_e32 v97, 0xffff0000, v118
	v_lshlrev_b32_e32 v180, 16, v119
	v_and_b32_e32 v181, 0xffff0000, v119
	v_lshlrev_b32_e32 v118, 16, v125
	v_and_b32_e32 v119, 0xffff0000, v125
	v_pk_add_f32 v[124:125], v[164:165], 0 op_sel_hi:[1,0]
	v_lshlrev_b32_e32 v172, 16, v80
	v_pk_add_f32 v[76:77], v[124:125], v[76:77]
	v_and_b32_e32 v173, 0xffff0000, v80
	v_pk_add_f32 v[76:77], v[76:77], v[96:97]
	s_waitcnt vmcnt(35)
	v_lshlrev_b32_e32 v96, 16, v128
	v_and_b32_e32 v97, 0xffff0000, v128
	v_pk_add_f32 v[76:77], v[76:77], v[96:97]
	s_waitcnt vmcnt(31)
	v_lshlrev_b32_e32 v96, 16, v130
	v_and_b32_e32 v97, 0xffff0000, v130
	v_pk_add_f32 v[76:77], v[76:77], v[96:97]
	s_waitcnt vmcnt(27)
	v_lshlrev_b32_e32 v96, 16, v132
	v_and_b32_e32 v97, 0xffff0000, v132
	v_pk_add_f32 v[76:77], v[76:77], v[96:97]
	s_waitcnt vmcnt(23)
	v_lshlrev_b32_e32 v96, 16, v134
	v_and_b32_e32 v97, 0xffff0000, v134
	v_pk_add_f32 v[76:77], v[76:77], v[96:97]
	s_waitcnt vmcnt(19)
	v_lshlrev_b32_e32 v96, 16, v138
	v_and_b32_e32 v97, 0xffff0000, v138
	v_pk_add_f32 v[76:77], v[76:77], v[96:97]
	s_waitcnt vmcnt(15)
	v_lshlrev_b32_e32 v96, 16, v142
	v_and_b32_e32 v97, 0xffff0000, v142
	v_pk_add_f32 v[76:77], v[76:77], v[96:97]
	s_waitcnt vmcnt(11)
	v_lshlrev_b32_e32 v96, 16, v156
	v_and_b32_e32 v97, 0xffff0000, v156
	v_pk_add_f32 v[76:77], v[76:77], v[96:97]
	s_waitcnt vmcnt(7)
	v_lshlrev_b32_e32 v96, 16, v160
	v_and_b32_e32 v97, 0xffff0000, v160
	v_lshlrev_b32_e32 v112, 16, v81
	v_and_b32_e32 v113, 0xffff0000, v81
	v_lshlrev_b32_e32 v80, 16, v89
	v_and_b32_e32 v81, 0xffff0000, v89
	v_pk_add_f32 v[76:77], v[76:77], v[96:97]
	v_pk_add_f32 v[96:97], v[166:167], 0 op_sel_hi:[1,0]
	v_lshlrev_b32_e32 v168, 16, v78
	v_pk_add_f32 v[80:81], v[96:97], v[80:81]
	v_lshlrev_b32_e32 v96, 16, v129
	v_pk_add_f32 v[80:81], v[80:81], v[180:181]
	v_and_b32_e32 v97, 0xffff0000, v129
	v_pk_add_f32 v[80:81], v[80:81], v[96:97]
	v_lshlrev_b32_e32 v96, 16, v131
	v_and_b32_e32 v97, 0xffff0000, v131
	v_pk_add_f32 v[80:81], v[80:81], v[96:97]
	v_lshlrev_b32_e32 v96, 16, v133
	v_and_b32_e32 v97, 0xffff0000, v133
	v_pk_add_f32 v[80:81], v[80:81], v[96:97]
	v_lshlrev_b32_e32 v96, 16, v135
	v_and_b32_e32 v97, 0xffff0000, v135
	v_pk_add_f32 v[80:81], v[80:81], v[96:97]
	v_lshlrev_b32_e32 v96, 16, v139
	v_and_b32_e32 v97, 0xffff0000, v139
	v_pk_add_f32 v[80:81], v[80:81], v[96:97]
	v_lshlrev_b32_e32 v96, 16, v143
	v_and_b32_e32 v97, 0xffff0000, v143
	v_pk_add_f32 v[80:81], v[80:81], v[96:97]
	v_lshlrev_b32_e32 v96, 16, v157
	v_and_b32_e32 v97, 0xffff0000, v157
	v_and_b32_e32 v169, 0xffff0000, v78
	v_pk_add_f32 v[80:81], v[80:81], v[96:97]
	v_lshlrev_b32_e32 v96, 16, v161
	v_and_b32_e32 v97, 0xffff0000, v161
	v_pk_add_f32 v[80:81], v[80:81], v[96:97]
	v_pk_add_f32 v[96:97], v[168:169], 0 op_sel_hi:[1,0]
	v_lshlrev_b32_e32 v182, 16, v122
	v_and_b32_e32 v183, 0xffff0000, v122
	v_pk_add_f32 v[96:97], v[96:97], v[174:175]
	v_lshlrev_b32_e32 v124, 16, v110
	v_pk_add_f32 v[96:97], v[96:97], v[182:183]
	v_and_b32_e32 v125, 0xffff0000, v110
	v_pk_add_f32 v[96:97], v[96:97], v[124:125]
	v_lshlrev_b32_e32 v124, 16, v114
	v_and_b32_e32 v125, 0xffff0000, v114
	v_pk_add_f32 v[96:97], v[96:97], v[124:125]
	v_lshlrev_b32_e32 v124, 16, v120
	v_and_b32_e32 v125, 0xffff0000, v120
	v_pk_add_f32 v[96:97], v[96:97], v[124:125]
	v_lshlrev_b32_e32 v124, 16, v136
	v_and_b32_e32 v125, 0xffff0000, v136
	v_pk_add_f32 v[96:97], v[96:97], v[124:125]
	v_lshlrev_b32_e32 v124, 16, v140
	v_and_b32_e32 v125, 0xffff0000, v140
	v_pk_add_f32 v[96:97], v[96:97], v[124:125]
	v_lshlrev_b32_e32 v124, 16, v144
	v_and_b32_e32 v125, 0xffff0000, v144
	v_pk_add_f32 v[96:97], v[96:97], v[124:125]
	v_lshlrev_b32_e32 v124, 16, v158
	v_and_b32_e32 v125, 0xffff0000, v158
	v_lshlrev_b32_e32 v170, 16, v79
	v_and_b32_e32 v171, 0xffff0000, v79
	v_pk_add_f32 v[96:97], v[96:97], v[124:125]
	s_waitcnt vmcnt(6)
	v_lshlrev_b32_e32 v124, 16, v162
	v_and_b32_e32 v125, 0xffff0000, v162
	v_pk_add_f32 v[96:97], v[96:97], v[124:125]
	v_pk_add_f32 v[124:125], v[170:171], 0 op_sel_hi:[1,0]
	v_lshlrev_b32_e32 v122, 16, v123
	v_and_b32_e32 v123, 0xffff0000, v123
	v_pk_add_f32 v[124:125], v[124:125], v[176:177]
	v_lshlrev_b32_e32 v110, 16, v111
	v_pk_add_f32 v[122:123], v[124:125], v[122:123]
	v_and_b32_e32 v111, 0xffff0000, v111
	v_pk_add_f32 v[110:111], v[122:123], v[110:111]
	v_lshlrev_b32_e32 v114, 16, v115
	v_and_b32_e32 v115, 0xffff0000, v115
	v_pk_add_f32 v[110:111], v[110:111], v[114:115]
	v_lshlrev_b32_e32 v114, 16, v121
	v_and_b32_e32 v115, 0xffff0000, v121
	v_pk_add_f32 v[110:111], v[110:111], v[114:115]
	v_lshlrev_b32_e32 v114, 16, v137
	v_and_b32_e32 v115, 0xffff0000, v137
	v_pk_add_f32 v[110:111], v[110:111], v[114:115]
	v_lshlrev_b32_e32 v114, 16, v141
	v_and_b32_e32 v115, 0xffff0000, v141
	v_pk_add_f32 v[110:111], v[110:111], v[114:115]
	v_lshlrev_b32_e32 v114, 16, v145
	v_and_b32_e32 v115, 0xffff0000, v145
	v_pk_add_f32 v[110:111], v[110:111], v[114:115]
	v_lshlrev_b32_e32 v114, 16, v159
	v_and_b32_e32 v115, 0xffff0000, v159
	v_pk_add_f32 v[110:111], v[110:111], v[114:115]
	v_lshlrev_b32_e32 v114, 16, v163
	v_and_b32_e32 v115, 0xffff0000, v163
	v_lshlrev_b32_e32 v178, 16, v106
	v_and_b32_e32 v179, 0xffff0000, v106
	v_lshlrev_b32_e32 v116, 16, v107
	v_and_b32_e32 v117, 0xffff0000, v107
	v_pk_add_f32 v[110:111], v[110:111], v[114:115]
	v_pk_add_f32 v[114:115], v[172:173], 0 op_sel_hi:[1,0]
	v_pk_add_f32 v[112:113], v[112:113], 0 op_sel_hi:[1,0]
	v_pk_add_f32 v[114:115], v[114:115], v[178:179]
	v_pk_add_f32 v[112:113], v[112:113], v[116:117]
	v_pk_add_f32 v[114:115], v[114:115], v[184:185]
	v_lshlrev_b32_e32 v120, 16, v84
	v_and_b32_e32 v121, 0xffff0000, v84
	v_pk_add_f32 v[112:113], v[112:113], v[118:119]
	v_lshlrev_b32_e32 v84, 16, v85
	v_and_b32_e32 v85, 0xffff0000, v85
	v_pk_add_f32 v[114:115], v[114:115], v[120:121]
	v_lshlrev_b32_e32 v120, 16, v86
	v_and_b32_e32 v121, 0xffff0000, v86
	v_pk_add_f32 v[84:85], v[112:113], v[84:85]
	v_lshlrev_b32_e32 v86, 16, v87
	v_and_b32_e32 v87, 0xffff0000, v87
	v_pk_add_f32 v[84:85], v[84:85], v[86:87]
	v_lshlrev_b32_e32 v86, 16, v91
	v_and_b32_e32 v87, 0xffff0000, v91
	v_pk_add_f32 v[84:85], v[84:85], v[86:87]
	v_lshlrev_b32_e32 v86, 16, v93
	v_and_b32_e32 v87, 0xffff0000, v93
	v_pk_add_f32 v[84:85], v[84:85], v[86:87]
	v_lshlrev_b32_e32 v86, 16, v95
	v_and_b32_e32 v87, 0xffff0000, v95
	v_pk_add_f32 v[84:85], v[84:85], v[86:87]
	v_lshlrev_b32_e32 v86, 16, v99
	v_and_b32_e32 v87, 0xffff0000, v99
	v_pk_add_f32 v[84:85], v[84:85], v[86:87]
	v_lshlrev_b32_e32 v86, 16, v101
	v_and_b32_e32 v87, 0xffff0000, v101
	v_lshlrev_b32_e32 v104, 16, v82
	v_and_b32_e32 v105, 0xffff0000, v82
	v_lshlrev_b32_e32 v78, 16, v83
	v_and_b32_e32 v79, 0xffff0000, v83
	v_pk_add_f32 v[84:85], v[84:85], v[86:87]
	s_waitcnt vmcnt(5)
	v_lshlrev_b32_e32 v86, 16, v103
	v_and_b32_e32 v87, 0xffff0000, v103
	v_lshlrev_b32_e32 v106, 16, v108
	v_and_b32_e32 v107, 0xffff0000, v108
	v_lshlrev_b32_e32 v82, 16, v109
	v_and_b32_e32 v83, 0xffff0000, v109
	v_pk_add_f32 v[84:85], v[84:85], v[86:87]
	v_pk_add_f32 v[86:87], v[104:105], 0 op_sel_hi:[1,0]
	v_pk_add_f32 v[78:79], v[78:79], 0 op_sel_hi:[1,0]
	v_lshlrev_b32_e32 v108, 16, v126
	v_and_b32_e32 v109, 0xffff0000, v126
	v_lshlrev_b32_e32 v88, 16, v127
	v_and_b32_e32 v89, 0xffff0000, v127
	v_pk_add_f32 v[86:87], v[86:87], v[106:107]
	v_pk_add_f32 v[78:79], v[78:79], v[82:83]
	v_pk_add_f32 v[114:115], v[114:115], v[120:121]
	v_lshlrev_b32_e32 v120, 16, v90
	v_and_b32_e32 v121, 0xffff0000, v90
	v_pk_add_f32 v[86:87], v[86:87], v[108:109]
	v_lshlrev_b32_e32 v90, 16, v72
	v_and_b32_e32 v91, 0xffff0000, v72
	v_pk_add_f32 v[78:79], v[78:79], v[88:89]
	v_lshlrev_b32_e32 v72, 16, v73
	v_and_b32_e32 v73, 0xffff0000, v73
	v_pk_add_f32 v[86:87], v[86:87], v[90:91]
	v_lshlrev_b32_e32 v90, 16, v74
	v_and_b32_e32 v91, 0xffff0000, v74
	v_pk_add_f32 v[72:73], v[78:79], v[72:73]
	v_lshlrev_b32_e32 v74, 16, v75
	v_and_b32_e32 v75, 0xffff0000, v75
	v_pk_add_f32 v[86:87], v[86:87], v[90:91]
	v_lshlrev_b32_e32 v90, 16, v60
	v_and_b32_e32 v91, 0xffff0000, v60
	v_pk_add_f32 v[72:73], v[72:73], v[74:75]
	v_lshlrev_b32_e32 v60, 16, v61
	v_and_b32_e32 v61, 0xffff0000, v61
	v_pk_add_f32 v[114:115], v[114:115], v[120:121]
	v_lshlrev_b32_e32 v120, 16, v92
	v_and_b32_e32 v121, 0xffff0000, v92
	v_pk_add_f32 v[86:87], v[86:87], v[90:91]
	v_lshlrev_b32_e32 v90, 16, v62
	v_and_b32_e32 v91, 0xffff0000, v62
	v_pk_add_f32 v[60:61], v[72:73], v[60:61]
	v_lshlrev_b32_e32 v62, 16, v63
	v_and_b32_e32 v63, 0xffff0000, v63
	v_pk_add_f32 v[114:115], v[114:115], v[120:121]
	v_lshlrev_b32_e32 v120, 16, v94
	v_and_b32_e32 v121, 0xffff0000, v94
	v_pk_add_f32 v[60:61], v[60:61], v[62:63]
	v_lshlrev_b32_e32 v62, 16, v65
	v_and_b32_e32 v63, 0xffff0000, v65
	v_pk_add_f32 v[114:115], v[114:115], v[120:121]
	v_lshlrev_b32_e32 v120, 16, v98
	v_and_b32_e32 v121, 0xffff0000, v98
	v_pk_add_f32 v[60:61], v[60:61], v[62:63]
	v_lshlrev_b32_e32 v62, 16, v67
	v_and_b32_e32 v63, 0xffff0000, v67
	v_pk_add_f32 v[114:115], v[114:115], v[120:121]
	v_lshlrev_b32_e32 v120, 16, v100
	v_and_b32_e32 v121, 0xffff0000, v100
	v_pk_add_f32 v[86:87], v[86:87], v[90:91]
	v_lshlrev_b32_e32 v90, 16, v64
	v_and_b32_e32 v91, 0xffff0000, v64
	v_pk_add_f32 v[60:61], v[60:61], v[62:63]
	v_lshlrev_b32_e32 v62, 16, v69
	v_and_b32_e32 v63, 0xffff0000, v69
	v_pk_add_f32 v[114:115], v[114:115], v[120:121]
	v_lshlrev_b32_e32 v120, 16, v102
	v_and_b32_e32 v121, 0xffff0000, v102
	v_pk_add_f32 v[86:87], v[86:87], v[90:91]
	v_lshlrev_b32_e32 v90, 16, v66
	v_and_b32_e32 v91, 0xffff0000, v66
	v_pk_add_f32 v[60:61], v[60:61], v[62:63]
	s_waitcnt vmcnt(4)
	v_lshlrev_b32_e32 v62, 16, v71
	v_and_b32_e32 v63, 0xffff0000, v71
	v_mov_b32_e32 v64, v77
	v_mov_b32_e32 v65, v81
	v_pk_add_f32 v[114:115], v[114:115], v[120:121]
	v_pk_add_f32 v[86:87], v[86:87], v[90:91]
	v_lshlrev_b32_e32 v90, 16, v68
	v_and_b32_e32 v91, 0xffff0000, v68
	v_pk_add_f32 v[60:61], v[60:61], v[62:63]
	v_mov_b32_e32 v62, v76
	v_mov_b32_e32 v63, v80
	v_pk_mul_f32 v[64:65], v[64:65], v[64:65]
	v_mov_b32_e32 v66, v97
	v_mov_b32_e32 v67, v111
	v_pk_add_f32 v[86:87], v[86:87], v[90:91]
	v_lshlrev_b32_e32 v90, 16, v70
	v_and_b32_e32 v91, 0xffff0000, v70
	v_pk_fma_f32 v[62:63], v[62:63], v[62:63], v[64:65]
	v_mov_b32_e32 v64, v96
	v_mov_b32_e32 v65, v110
	v_pk_mul_f32 v[66:67], v[66:67], v[66:67]
	v_mul_f32_e32 v42, v115, v115
	v_pk_add_f32 v[86:87], v[86:87], v[90:91]
	v_pk_fma_f32 v[64:65], v[64:65], v[64:65], v[66:67]
	v_pk_fma_f32 v[66:67], v[114:115], v[114:115], v[42:43] op_sel_hi:[1,1,0]
	v_mul_f32_e32 v42, v85, v85
	v_pk_add_f32 v[62:63], v[62:63], v[62:63] op_sel:[0,1] op_sel_hi:[1,0]
	v_pk_add_f32 v[64:65], v[64:65], v[64:65] op_sel:[0,1] op_sel_hi:[1,0]
	v_pk_fma_f32 v[68:69], v[84:85], v[84:85], v[42:43] op_sel_hi:[1,1,0]
	v_pk_mul_f32 v[70:71], v[86:87], v[86:87]
	v_pk_mul_f32 v[72:73], v[60:61], v[60:61]
	v_mov_b32_e32 v63, v70
	v_mov_b32_e32 v65, v71
	v_mov_b32_e32 v67, v72
	v_mov_b32_e32 v69, v73
	v_pk_add_f32 v[62:63], v[62:63], v[64:65]
	v_pk_add_f32 v[64:65], v[66:67], v[68:69]
	s_waitcnt vmcnt(1)
	v_lshlrev_b32_e32 v66, 16, v54
	v_pk_add_f32 v[62:63], v[62:63], v[64:65]
	v_lshlrev_b32_e32 v64, 16, v56
	v_add_f32_e32 v42, v62, v63
	s_nop 1
	v_mov_b32_dpp v62, v42 quad_perm:[1,0,3,2] row_mask:0xf bank_mask:0xf
	s_waitcnt vmcnt(0)
	v_lshlrev_b32_e32 v68, 16, v52
	s_waitcnt lgkmcnt(0)
	v_add_f32_e32 v42, v42, v62
	s_nop 1
	v_mov_b32_dpp v62, v42 quad_perm:[2,3,0,1] row_mask:0xf bank_mask:0xf
	s_waitcnt lgkmcnt(0)
	v_add_f32_e32 v42, v42, v62
	s_nop 1
	v_mov_b32_dpp v63, v42 row_half_mirror row_mask:0xf bank_mask:0xf
	v_lshlrev_b32_e32 v62, 16, v58
	s_waitcnt lgkmcnt(0)
	v_add_f32_e32 v42, v42, v63
	s_nop 1
	v_mov_b32_dpp v65, v42 row_mirror row_mask:0xf bank_mask:0xf
	v_and_b32_e32 v63, 0xffff0000, v58
	v_lshlrev_b32_e32 v58, 16, v59
	v_and_b32_e32 v59, 0xffff0000, v59
	s_waitcnt lgkmcnt(0)
	v_add_f32_e32 v42, v42, v65
	v_mov_b32_e32 v67, v42
	s_nop 1
	v_permlane16_swap_b32 v42, v67
	v_and_b32_e32 v65, 0xffff0000, v56
	v_lshlrev_b32_e32 v56, 16, v57
	v_and_b32_e32 v57, 0xffff0000, v57
	s_waitcnt lgkmcnt(0)
	v_add_f32_e32 v42, v42, v67
	v_mov_b32_e32 v69, v42
	s_nop 1
	v_permlane32_swap_b32 v42, v69
	v_and_b32_e32 v67, 0xffff0000, v54
	v_lshlrev_b32_e32 v54, 16, v55
	v_and_b32_e32 v55, 0xffff0000, v55
	s_waitcnt lgkmcnt(0)
	v_add_f32_e32 v42, v42, v69
	v_fmamk_f32 v42, v42, 0x3a800000, v146
	v_mul_f32_e32 v69, 0x4b800000, v42
	v_cmp_gt_f32_e32 vcc, s97, v42
	s_nop 1
	v_cndmask_b32_e32 v42, v42, v69, vcc
	v_rsq_f32_e32 v42, v42
	v_and_b32_e32 v69, 0xffff0000, v52
	v_lshlrev_b32_e32 v52, 16, v53
	v_and_b32_e32 v53, 0xffff0000, v53
	v_mul_f32_e32 v70, 0x45800000, v42
	v_cndmask_b32_e32 v42, v42, v70, vcc
	v_pk_mul_f32 v[70:71], v[76:77], v[42:43] op_sel_hi:[1,0]
	v_pk_mul_f32 v[72:73], v[80:81], v[42:43] op_sel_hi:[1,0]
	v_pk_fma_f32 v[62:63], v[0:1], v[70:71], v[62:63]
	v_pk_fma_f32 v[58:59], v[2:3], v[72:73], v[58:59]
	v_pk_mul_f32 v[72:73], v[62:63], v[62:63]
	v_pk_mul_f32 v[70:71], v[58:59], v[58:59]
	v_pk_mul_f32 v[60:61], v[60:61], v[42:43] op_sel_hi:[1,0]
	v_pk_mov_b32 v[74:75], v[72:73], v[70:71] op_sel:[1,0]
	v_mov_b32_e32 v73, v71
	v_pk_add_f32 v[70:71], v[74:75], v[72:73]
	v_pk_mul_f32 v[72:73], v[110:111], v[42:43] op_sel_hi:[1,0]
	v_pk_mul_f32 v[74:75], v[96:97], v[42:43] op_sel_hi:[1,0]
	v_pk_fma_f32 v[56:57], v[6:7], v[72:73], v[56:57]
	v_pk_fma_f32 v[64:65], v[4:5], v[74:75], v[64:65]
	v_pk_mul_f32 v[72:73], v[56:57], v[56:57]
	v_pk_mul_f32 v[74:75], v[64:65], v[64:65]
	v_pk_add_f32 v[70:71], v[70:71], v[70:71] op_sel_hi:[0,1]
	v_pk_mov_b32 v[76:77], v[74:75], v[72:73] op_sel:[1,0]
	v_mov_b32_e32 v75, v73
	v_pk_add_f32 v[72:73], v[76:77], v[74:75]
	v_pk_mul_f32 v[76:77], v[114:115], v[42:43] op_sel_hi:[1,0]
	v_pk_mul_f32 v[74:75], v[84:85], v[42:43] op_sel_hi:[1,0]
	v_pk_fma_f32 v[66:67], v[16:17], v[76:77], v[66:67]
	v_pk_fma_f32 v[54:55], v[18:19], v[74:75], v[54:55]
	v_mul_f32_e32 v70, v66, v66
	v_pk_fma_f32 v[74:75], v[66:67], v[66:67], v[70:71] op_sel_hi:[1,1,0]
	v_mul_f32_e32 v70, v54, v54
	v_pk_mul_f32 v[78:79], v[86:87], v[42:43] op_sel_hi:[1,0]
	v_pk_add_f32 v[72:73], v[72:73], v[72:73] op_sel_hi:[0,1]
	v_pk_fma_f32 v[76:77], v[54:55], v[54:55], v[70:71] op_sel_hi:[1,1,0]
	v_pk_fma_f32 v[68:69], v[20:21], v[78:79], v[68:69]
	v_pk_fma_f32 v[52:53], v[22:23], v[60:61], v[52:53]
	v_mul_f32_e32 v74, v68, v68
	v_mul_f32_e32 v76, v69, v69
	v_mul_f32_e32 v70, v52, v52
	v_mul_f32_e32 v72, v53, v53
	v_pk_add_f32 v[60:61], v[74:75], v[76:77]
	v_pk_add_f32 v[70:71], v[70:71], v[72:73]
	v_cvt_pk_bf16_f32 v74, v62, v63
	v_lshl_add_u64 v[72:73], v[50:51], 0, s[68:69]
	v_pk_add_f32 v[60:61], v[60:61], v[70:71]
	s_nop 0
	v_add_f32_e32 v42, v60, v61
	s_nop 1
	v_mov_b32_dpp v60, v42 quad_perm:[1,0,3,2] row_mask:0xf bank_mask:0xf
	s_waitcnt lgkmcnt(0)
	v_add_f32_e32 v42, v42, v60
	s_nop 1
	v_mov_b32_dpp v60, v42 quad_perm:[2,3,0,1] row_mask:0xf bank_mask:0xf
	s_waitcnt lgkmcnt(0)
	v_add_f32_e32 v42, v42, v60
	s_nop 1
	v_mov_b32_dpp v70, v42 row_half_mirror row_mask:0xf bank_mask:0xf
	v_lshl_add_u64 v[60:61], v[50:51], 0, s[62:63]
	s_waitcnt lgkmcnt(0)
	v_add_f32_e32 v42, v42, v70
	s_nop 1
	v_mov_b32_dpp v75, v42 row_mirror row_mask:0xf bank_mask:0xf
	v_lshl_add_u64 v[70:71], v[50:51], 0, s[64:65]
	v_lshl_add_u64 v[50:51], v[50:51], 0, s[70:71]
	s_waitcnt lgkmcnt(0)
	v_add_f32_e32 v42, v42, v75
	v_mov_b32_e32 v76, v42
	s_nop 1
	v_permlane16_swap_b32 v42, v76
	v_cvt_pk_bf16_f32 v75, v58, v59
	s_waitcnt lgkmcnt(0)
	v_add_f32_e32 v42, v42, v76
	v_mov_b32_e32 v208, v74
	v_mov_b32_e32 v209, v75
	s_nop 1
	v_mov_b32_e32 v74, v42
	s_nop 1
	v_permlane32_swap_b32 v42, v74
	v_cvt_pk_bf16_f32 v60, v64, v65
	v_cvt_pk_bf16_f32 v61, v56, v57
	s_waitcnt lgkmcnt(0)
	v_add_f32_e32 v42, v42, v74
	v_mov_b32_e32 v210, v60
	v_mov_b32_e32 v211, v61
	s_nop 1
	v_cvt_pk_bf16_f32 v60, v66, v67
	v_fmamk_f32 v42, v42, 0x3a800000, v146
	v_cvt_pk_bf16_f32 v61, v54, v55
	v_cmp_gt_f32_e32 vcc, s97, v42
	v_mov_b32_e32 v212, v60
	v_mov_b32_e32 v213, v61
	s_nop 1
	v_mul_f32_e32 v60, 0x4b800000, v42
	s_nop 0
	v_cndmask_b32_e32 v42, v42, v60, vcc
	v_rsq_f32_e32 v42, v42
	v_cvt_pk_bf16_f32 v60, v68, v69
	v_cvt_pk_bf16_f32 v61, v52, v53
	s_nop 0
	v_and_b32_e32 v232, 1, v152
	v_cmp_eq_u32_e64 s[98:99], 1, v232
	v_mul_u32_u24_e32 v230, 0x1f8, v232
	v_mov_b32_e32 v231, 0
	v_lshl_add_u64 v[228:229], v[50:51], 0, v[230:231]
	v_cndmask_b32_e64 v216, v210, v208, s[98:99]
	v_cndmask_b32_e64 v217, v211, v209, s[98:99]
	s_nop 1
	v_mov_b32_dpp v218, v216 quad_perm:[1,0,3,2] row_mask:0xf bank_mask:0xf
	v_mov_b32_dpp v219, v217 quad_perm:[1,0,3,2] row_mask:0xf bank_mask:0xf
	v_cndmask_b32_e64 v220, v208, v218, s[98:99]
	v_cndmask_b32_e64 v221, v209, v219, s[98:99]
	v_cndmask_b32_e64 v222, v218, v210, s[98:99]
	v_cndmask_b32_e64 v223, v219, v211, s[98:99]
	global_store_dwordx4 v[228:229], v[220:223], off offset:-1536 sc0 sc1
	s_nop 1
	v_cndmask_b32_e64 v216, v60, v212, s[98:99]
	v_cndmask_b32_e64 v217, v61, v213, s[98:99]
	s_nop 1
	v_mov_b32_dpp v218, v216 quad_perm:[1,0,3,2] row_mask:0xf bank_mask:0xf
	v_mov_b32_dpp v219, v217 quad_perm:[1,0,3,2] row_mask:0xf bank_mask:0xf
	v_cndmask_b32_e64 v224, v212, v218, s[98:99]
	v_cndmask_b32_e64 v225, v213, v219, s[98:99]
	v_cndmask_b32_e64 v226, v218, v60, s[98:99]
	v_cndmask_b32_e64 v227, v219, v61, s[98:99]
	global_store_dwordx4 v[228:229], v[224:227], off offset:-512 sc0 sc1
	s_nop 1
	s_mov_b32 s99, 0
	s_nop 1
	v_mul_f32_e32 v50, 0x45800000, v42
	v_cndmask_b32_e32 v42, v42, v50, vcc
	v_pk_mul_f32 v[60:61], v[62:63], v[42:43] op_sel_hi:[1,0]
	v_lshl_add_u64 v[50:51], v[48:49], 0, s[6:7]
	v_pk_mul_f32 v[58:59], v[58:59], v[42:43] op_sel_hi:[1,0]
	v_pk_mul_f32 v[60:61], v[24:25], v[60:61]
	v_pk_mul_f32 v[58:59], v[26:27], v[58:59]
	v_cvt_pk_bf16_f32 v60, v60, v61
	v_pk_mul_f32 v[56:57], v[56:57], v[42:43] op_sel_hi:[1,0]
	v_cvt_pk_bf16_f32 v61, v58, v59
	s_mov_b64 s[6:7], 0x3800a00
	v_mov_b32_e32 v208, v60
	v_mov_b32_e32 v209, v61
	s_nop 1
	v_pk_mul_f32 v[50:51], v[64:65], v[42:43] op_sel_hi:[1,0]
	v_pk_mul_f32 v[56:57], v[10:11], v[56:57]
	v_pk_mul_f32 v[50:51], v[8:9], v[50:51]
	v_pk_mul_f32 v[54:55], v[54:55], v[42:43] op_sel_hi:[1,0]
	v_cvt_pk_bf16_f32 v50, v50, v51
	v_cvt_pk_bf16_f32 v51, v56, v57
	v_lshl_add_u64 v[56:57], v[48:49], 0, s[6:7]
	v_mov_b32_e32 v210, v50
	v_mov_b32_e32 v211, v51
	s_nop 1
	v_pk_mul_f32 v[50:51], v[66:67], v[42:43] op_sel_hi:[1,0]
	v_pk_mul_f32 v[54:55], v[14:15], v[54:55]
	v_pk_mul_f32 v[50:51], v[12:13], v[50:51]
	s_mov_b64 s[6:7], 0x3800c00
	v_cvt_pk_bf16_f32 v50, v50, v51
	v_cvt_pk_bf16_f32 v51, v54, v55
	v_lshl_add_u64 v[54:55], v[48:49], 0, s[6:7]
	v_mov_b32_e32 v212, v50
	v_mov_b32_e32 v213, v51
	s_nop 1
	v_pk_mul_f32 v[50:51], v[68:69], v[42:43] op_sel_hi:[1,0]
	v_pk_mul_f32 v[52:53], v[52:53], v[42:43] op_sel_hi:[1,0]
	v_pk_mul_f32 v[50:51], v[28:29], v[50:51]
	s_mov_b64 s[6:7], 0x3800e00
	v_pk_mul_f32 v[52:53], v[30:31], v[52:53]
	v_cvt_pk_bf16_f32 v50, v50, v51
	v_lshl_add_u64 v[48:49], v[48:49], 0, s[6:7]
	v_cvt_pk_bf16_f32 v51, v52, v53
	s_nop 0
	v_and_b32_e32 v232, 1, v152
	v_cmp_eq_u32_e64 s[98:99], 1, v232
	v_mul_u32_u24_e32 v230, 0x1f8, v232
	v_mov_b32_e32 v231, 0
	v_lshl_add_u64 v[228:229], v[48:49], 0, v[230:231]
	v_cndmask_b32_e64 v216, v210, v208, s[98:99]
	v_cndmask_b32_e64 v217, v211, v209, s[98:99]
	s_nop 1
	v_mov_b32_dpp v218, v216 quad_perm:[1,0,3,2] row_mask:0xf bank_mask:0xf
	v_mov_b32_dpp v219, v217 quad_perm:[1,0,3,2] row_mask:0xf bank_mask:0xf
	v_cndmask_b32_e64 v220, v208, v218, s[98:99]
	v_cndmask_b32_e64 v221, v209, v219, s[98:99]
	v_cndmask_b32_e64 v222, v218, v210, s[98:99]
	v_cndmask_b32_e64 v223, v219, v211, s[98:99]
	global_store_dwordx4 v[228:229], v[220:223], off offset:-1536 sc0 sc1
	s_nop 1
	v_cndmask_b32_e64 v216, v50, v212, s[98:99]
	v_cndmask_b32_e64 v217, v51, v213, s[98:99]
	s_nop 1
	v_mov_b32_dpp v218, v216 quad_perm:[1,0,3,2] row_mask:0xf bank_mask:0xf
	v_mov_b32_dpp v219, v217 quad_perm:[1,0,3,2] row_mask:0xf bank_mask:0xf
	v_cndmask_b32_e64 v224, v212, v218, s[98:99]
	v_cndmask_b32_e64 v225, v213, v219, s[98:99]
	v_cndmask_b32_e64 v226, v218, v50, s[98:99]
	v_cndmask_b32_e64 v227, v219, v51, s[98:99]
	global_store_dwordx4 v[228:229], v[224:227], off offset:-512 sc0 sc1
	s_nop 1
	s_mov_b32 s99, 0
	s_nop 1
	s_cbranch_scc0 .LBB0_1410

.LBB0_1403:
	s_lshl_b64 s[6:7], s[6:7], 12
	s_add_u32 s6, s8, s6
	s_addc_u32 s7, s9, s7
	v_lshl_add_u64 v[48:49], v[32:33], 3, s[6:7]
	v_lshl_add_u64 v[70:71], v[46:47], 0, s[82:83]
	s_mov_b32 s6, 0xda00000
	v_add_co_u32_e32 v50, vcc, s6, v70
	s_mov_b32 s6, 0xdb80000
	s_nop 0
	v_addc_co_u32_e32 v51, vcc, 0, v71, vcc
	v_add_co_u32_e32 v52, vcc, s6, v70
	s_mov_b32 s6, 0xdd00000
	s_nop 0
	v_addc_co_u32_e32 v53, vcc, 0, v71, vcc
	v_add_co_u32_e32 v54, vcc, s6, v70
	s_mov_b32 s6, 0xde80000
	s_nop 0
	v_addc_co_u32_e32 v55, vcc, 0, v71, vcc
	v_add_co_u32_e32 v56, vcc, s6, v70
	s_mov_b32 s6, 0xe000000
	s_nop 0
	v_addc_co_u32_e32 v57, vcc, 0, v71, vcc
	v_add_co_u32_e32 v58, vcc, s6, v70
	s_mov_b32 s6, 0xe180000
	s_nop 0
	v_addc_co_u32_e32 v59, vcc, 0, v71, vcc
	v_add_co_u32_e32 v60, vcc, s6, v70
	s_mov_b32 s6, 0xe300000
	s_nop 0
	v_addc_co_u32_e32 v61, vcc, 0, v71, vcc
	v_add_co_u32_e32 v62, vcc, s6, v70
	global_load_dwordx2 v[74:75], v[48:49], off offset:2048
	global_load_dwordx2 v[76:77], v[48:49], off offset:2560
	global_load_dwordx2 v[78:79], v[48:49], off offset:3072
	global_load_dwordx2 v[72:73], v[48:49], off offset:3584
	global_load_dwordx2 v[96:97], v[50:51], off
	global_load_dwordx2 v[98:99], v[50:51], off offset:512
	global_load_dwordx2 v[102:103], v[50:51], off offset:1024
	global_load_dwordx2 v[108:109], v[50:51], off offset:1536
	global_load_dwordx2 v[114:115], v[52:53], off
	global_load_dwordx2 v[116:117], v[52:53], off offset:512
	global_load_dwordx2 v[126:127], v[52:53], off offset:1024
	global_load_dwordx2 v[128:129], v[52:53], off offset:1536
	global_load_dwordx2 v[144:145], v[54:55], off
	global_load_dwordx2 v[156:157], v[54:55], off offset:512
	global_load_dwordx2 v[158:159], v[54:55], off offset:1024
	global_load_dwordx2 v[160:161], v[54:55], off offset:1536
	v_addc_co_u32_e32 v63, vcc, 0, v71, vcc
	s_mov_b32 s6, 0xe480000
	v_add_co_u32_e32 v64, vcc, s6, v70
	s_mov_b32 s6, 0xe600000
	s_nop 0
	v_addc_co_u32_e32 v65, vcc, 0, v71, vcc
	v_add_co_u32_e32 v66, vcc, s6, v70
	global_load_dwordx2 v[162:163], v[56:57], off
	global_load_dwordx2 v[130:131], v[56:57], off offset:512
	global_load_dwordx2 v[100:101], v[56:57], off offset:1024
	global_load_dwordx2 v[80:81], v[56:57], off offset:1536
	v_addc_co_u32_e32 v67, vcc, 0, v71, vcc
	s_mov_b32 s6, 0xe780000
	global_load_dwordx2 v[164:165], v[58:59], off
	global_load_dwordx2 v[134:135], v[58:59], off offset:512
	global_load_dwordx2 v[104:105], v[58:59], off offset:1024
	global_load_dwordx2 v[82:83], v[58:59], off offset:1536
	v_add_co_u32_e32 v68, vcc, s6, v70
	global_load_dwordx2 v[166:167], v[60:61], off
	global_load_dwordx2 v[138:139], v[60:61], off offset:512
	global_load_dwordx2 v[106:107], v[60:61], off offset:1024
	global_load_dwordx2 v[84:85], v[60:61], off offset:1536
	global_load_dwordx2 v[168:169], v[62:63], off
	global_load_dwordx2 v[140:141], v[62:63], off offset:512
	global_load_dwordx2 v[110:111], v[62:63], off offset:1024
	global_load_dwordx2 v[86:87], v[62:63], off offset:1536
	global_load_dwordx2 v[170:171], v[64:65], off
	global_load_dwordx2 v[142:143], v[64:65], off offset:512
	global_load_dwordx2 v[112:113], v[64:65], off offset:1024
	global_load_dwordx2 v[88:89], v[64:65], off offset:1536
	global_load_dwordx2 v[172:173], v[66:67], off
	v_addc_co_u32_e32 v69, vcc, 0, v71, vcc
	global_load_dwordx2 v[174:175], v[68:69], off
	s_mov_b32 s6, 0xe900000
	v_add_co_u32_e32 v70, vcc, s6, v70
	s_mov_b64 s[6:7], 0x3800000
	s_nop 0
	v_addc_co_u32_e32 v71, vcc, 0, v71, vcc
	global_load_dwordx2 v[176:177], v[70:71], off
	global_load_dwordx2 v[178:179], v[66:67], off offset:512
	global_load_dwordx2 v[122:123], v[66:67], off offset:1024
	global_load_dwordx2 v[94:95], v[66:67], off offset:1536
	global_load_dwordx2 v[180:181], v[68:69], off offset:512
	global_load_dwordx2 v[120:121], v[68:69], off offset:1024
	global_load_dwordx2 v[92:93], v[68:69], off offset:1536
	global_load_dwordx2 v[182:183], v[70:71], off offset:512
	global_load_dwordx2 v[118:119], v[70:71], off offset:1024
	global_load_dwordx2 v[90:91], v[70:71], off offset:1536
	s_add_i32 s17, s17, 1
	s_cmpk_lt_u32 s17, 0x4080
	s_waitcnt vmcnt(43)
	v_lshlrev_b32_e32 v184, 16, v96
	v_and_b32_e32 v185, 0xffff0000, v96
	v_lshlrev_b32_e32 v186, 16, v97
	v_and_b32_e32 v187, 0xffff0000, v97
	s_waitcnt vmcnt(39)
	v_lshlrev_b32_e32 v96, 16, v114
	v_and_b32_e32 v97, 0xffff0000, v114
	s_waitcnt vmcnt(38)
	v_lshlrev_b32_e32 v194, 16, v116
	v_and_b32_e32 v195, 0xffff0000, v116
	v_lshlrev_b32_e32 v196, 16, v117
	v_and_b32_e32 v197, 0xffff0000, v117
	s_waitcnt vmcnt(35)
	v_lshlrev_b32_e32 v116, 16, v144
	v_and_b32_e32 v117, 0xffff0000, v144
	v_lshlrev_b32_e32 v200, 16, v145
	v_and_b32_e32 v201, 0xffff0000, v145
	s_waitcnt vmcnt(33)
	v_lshlrev_b32_e32 v204, 16, v158
	v_and_b32_e32 v205, 0xffff0000, v158
	v_lshlrev_b32_e32 v144, 16, v159
	v_and_b32_e32 v145, 0xffff0000, v159
	v_pk_add_f32 v[158:159], v[184:185], 0 op_sel_hi:[1,0]
	v_lshlrev_b32_e32 v192, 16, v102
	v_pk_add_f32 v[96:97], v[158:159], v[96:97]
	v_and_b32_e32 v193, 0xffff0000, v102
	v_pk_add_f32 v[96:97], v[96:97], v[116:117]
	s_waitcnt vmcnt(31)
	v_lshlrev_b32_e32 v116, 16, v162
	v_and_b32_e32 v117, 0xffff0000, v162
	v_pk_add_f32 v[96:97], v[96:97], v[116:117]
	s_waitcnt vmcnt(27)
	v_lshlrev_b32_e32 v116, 16, v164
	v_and_b32_e32 v117, 0xffff0000, v164
	v_pk_add_f32 v[96:97], v[96:97], v[116:117]
	s_waitcnt vmcnt(23)
	v_lshlrev_b32_e32 v116, 16, v166
	v_and_b32_e32 v117, 0xffff0000, v166
	v_pk_add_f32 v[96:97], v[96:97], v[116:117]
	s_waitcnt vmcnt(19)
	v_lshlrev_b32_e32 v116, 16, v168
	v_and_b32_e32 v117, 0xffff0000, v168
	v_pk_add_f32 v[96:97], v[96:97], v[116:117]
	s_waitcnt vmcnt(15)
	v_lshlrev_b32_e32 v116, 16, v170
	v_and_b32_e32 v117, 0xffff0000, v170
	v_pk_add_f32 v[96:97], v[96:97], v[116:117]
	s_waitcnt vmcnt(11)
	v_lshlrev_b32_e32 v116, 16, v172
	v_and_b32_e32 v117, 0xffff0000, v172
	v_pk_add_f32 v[96:97], v[96:97], v[116:117]
	s_waitcnt vmcnt(10)
	v_lshlrev_b32_e32 v116, 16, v174
	v_and_b32_e32 v117, 0xffff0000, v174
	v_pk_add_f32 v[96:97], v[96:97], v[116:117]
	s_waitcnt vmcnt(9)
	v_lshlrev_b32_e32 v116, 16, v176
	v_and_b32_e32 v117, 0xffff0000, v176
	v_lshlrev_b32_e32 v132, 16, v103
	v_and_b32_e32 v133, 0xffff0000, v103
	v_lshlrev_b32_e32 v102, 16, v115
	v_and_b32_e32 v103, 0xffff0000, v115
	v_pk_add_f32 v[96:97], v[96:97], v[116:117]
	v_pk_add_f32 v[116:117], v[186:187], 0 op_sel_hi:[1,0]
	v_lshlrev_b32_e32 v188, 16, v98
	v_pk_add_f32 v[102:103], v[116:117], v[102:103]
	v_lshlrev_b32_e32 v116, 16, v163
	v_pk_add_f32 v[102:103], v[102:103], v[200:201]
	v_and_b32_e32 v117, 0xffff0000, v163
	v_pk_add_f32 v[102:103], v[102:103], v[116:117]
	v_lshlrev_b32_e32 v116, 16, v165
	v_and_b32_e32 v117, 0xffff0000, v165
	v_pk_add_f32 v[102:103], v[102:103], v[116:117]
	v_lshlrev_b32_e32 v116, 16, v167
	v_and_b32_e32 v117, 0xffff0000, v167
	v_pk_add_f32 v[102:103], v[102:103], v[116:117]
	v_lshlrev_b32_e32 v116, 16, v169
	v_and_b32_e32 v117, 0xffff0000, v169
	v_pk_add_f32 v[102:103], v[102:103], v[116:117]
	v_lshlrev_b32_e32 v116, 16, v171
	v_and_b32_e32 v117, 0xffff0000, v171
	v_pk_add_f32 v[102:103], v[102:103], v[116:117]
	v_lshlrev_b32_e32 v116, 16, v173
	v_and_b32_e32 v117, 0xffff0000, v173
	v_pk_add_f32 v[102:103], v[102:103], v[116:117]
	v_lshlrev_b32_e32 v116, 16, v175
	v_and_b32_e32 v117, 0xffff0000, v175
	v_and_b32_e32 v189, 0xffff0000, v98
	v_pk_add_f32 v[102:103], v[102:103], v[116:117]
	v_lshlrev_b32_e32 v116, 16, v177
	v_and_b32_e32 v117, 0xffff0000, v177
	v_pk_add_f32 v[102:103], v[102:103], v[116:117]
	v_pk_add_f32 v[116:117], v[188:189], 0 op_sel_hi:[1,0]
	v_lshlrev_b32_e32 v202, 16, v156
	v_and_b32_e32 v203, 0xffff0000, v156
	v_pk_add_f32 v[116:117], v[116:117], v[194:195]
	v_lshlrev_b32_e32 v158, 16, v130
	v_pk_add_f32 v[116:117], v[116:117], v[202:203]
	v_and_b32_e32 v159, 0xffff0000, v130
	v_pk_add_f32 v[116:117], v[116:117], v[158:159]
	v_lshlrev_b32_e32 v158, 16, v134
	v_and_b32_e32 v159, 0xffff0000, v134
	v_pk_add_f32 v[116:117], v[116:117], v[158:159]
	v_lshlrev_b32_e32 v158, 16, v138
	v_and_b32_e32 v159, 0xffff0000, v138
	v_pk_add_f32 v[116:117], v[116:117], v[158:159]
	v_lshlrev_b32_e32 v158, 16, v140
	v_and_b32_e32 v159, 0xffff0000, v140
	v_pk_add_f32 v[116:117], v[116:117], v[158:159]
	v_lshlrev_b32_e32 v158, 16, v142
	v_and_b32_e32 v159, 0xffff0000, v142
	v_pk_add_f32 v[116:117], v[116:117], v[158:159]
	s_waitcnt vmcnt(8)
	v_lshlrev_b32_e32 v158, 16, v178
	v_and_b32_e32 v159, 0xffff0000, v178
	v_pk_add_f32 v[116:117], v[116:117], v[158:159]
	s_waitcnt vmcnt(5)
	v_lshlrev_b32_e32 v158, 16, v180
	v_and_b32_e32 v159, 0xffff0000, v180
	v_lshlrev_b32_e32 v190, 16, v99
	v_and_b32_e32 v191, 0xffff0000, v99
	v_pk_add_f32 v[116:117], v[116:117], v[158:159]
	s_waitcnt vmcnt(2)
	v_lshlrev_b32_e32 v158, 16, v182
	v_and_b32_e32 v159, 0xffff0000, v182
	v_pk_add_f32 v[116:117], v[116:117], v[158:159]
	v_pk_add_f32 v[158:159], v[190:191], 0 op_sel_hi:[1,0]
	v_lshlrev_b32_e32 v156, 16, v157
	v_and_b32_e32 v157, 0xffff0000, v157
	v_pk_add_f32 v[158:159], v[158:159], v[196:197]
	v_lshlrev_b32_e32 v130, 16, v131
	v_pk_add_f32 v[156:157], v[158:159], v[156:157]
	v_and_b32_e32 v131, 0xffff0000, v131
	v_pk_add_f32 v[130:131], v[156:157], v[130:131]
	v_lshlrev_b32_e32 v134, 16, v135
	v_and_b32_e32 v135, 0xffff0000, v135
	v_pk_add_f32 v[130:131], v[130:131], v[134:135]
	v_lshlrev_b32_e32 v134, 16, v139
	v_and_b32_e32 v135, 0xffff0000, v139
	v_pk_add_f32 v[130:131], v[130:131], v[134:135]
	v_lshlrev_b32_e32 v134, 16, v141
	v_and_b32_e32 v135, 0xffff0000, v141
	v_pk_add_f32 v[130:131], v[130:131], v[134:135]
	v_lshlrev_b32_e32 v134, 16, v143
	v_and_b32_e32 v135, 0xffff0000, v143
	v_pk_add_f32 v[130:131], v[130:131], v[134:135]
	v_lshlrev_b32_e32 v134, 16, v179
	v_and_b32_e32 v135, 0xffff0000, v179
	v_pk_add_f32 v[130:131], v[130:131], v[134:135]
	v_lshlrev_b32_e32 v134, 16, v181
	v_and_b32_e32 v135, 0xffff0000, v181
	v_pk_add_f32 v[130:131], v[130:131], v[134:135]
	v_lshlrev_b32_e32 v134, 16, v183
	v_and_b32_e32 v135, 0xffff0000, v183
	v_lshlrev_b32_e32 v198, 16, v126
	v_and_b32_e32 v199, 0xffff0000, v126
	v_lshlrev_b32_e32 v136, 16, v127
	v_and_b32_e32 v137, 0xffff0000, v127
	v_pk_add_f32 v[130:131], v[130:131], v[134:135]
	v_pk_add_f32 v[134:135], v[192:193], 0 op_sel_hi:[1,0]
	v_pk_add_f32 v[132:133], v[132:133], 0 op_sel_hi:[1,0]
	v_pk_add_f32 v[134:135], v[134:135], v[198:199]
	v_pk_add_f32 v[132:133], v[132:133], v[136:137]
	v_pk_add_f32 v[134:135], v[134:135], v[204:205]
	v_lshlrev_b32_e32 v138, 16, v100
	v_and_b32_e32 v139, 0xffff0000, v100
	v_pk_add_f32 v[132:133], v[132:133], v[144:145]
	v_lshlrev_b32_e32 v100, 16, v101
	v_and_b32_e32 v101, 0xffff0000, v101
	v_pk_add_f32 v[134:135], v[134:135], v[138:139]
	v_lshlrev_b32_e32 v138, 16, v104
	v_and_b32_e32 v139, 0xffff0000, v104
	v_pk_add_f32 v[100:101], v[132:133], v[100:101]
	v_lshlrev_b32_e32 v104, 16, v105
	v_and_b32_e32 v105, 0xffff0000, v105
	v_pk_add_f32 v[100:101], v[100:101], v[104:105]
	v_lshlrev_b32_e32 v104, 16, v107
	v_and_b32_e32 v105, 0xffff0000, v107
	v_pk_add_f32 v[100:101], v[100:101], v[104:105]
	v_lshlrev_b32_e32 v104, 16, v111
	v_and_b32_e32 v105, 0xffff0000, v111
	v_pk_add_f32 v[100:101], v[100:101], v[104:105]
	v_lshlrev_b32_e32 v104, 16, v113
	v_and_b32_e32 v105, 0xffff0000, v113
	v_pk_add_f32 v[100:101], v[100:101], v[104:105]
	v_lshlrev_b32_e32 v104, 16, v123
	v_and_b32_e32 v105, 0xffff0000, v123
	v_pk_add_f32 v[100:101], v[100:101], v[104:105]
	v_lshlrev_b32_e32 v104, 16, v121
	v_and_b32_e32 v105, 0xffff0000, v121
	v_lshlrev_b32_e32 v124, 16, v108
	v_and_b32_e32 v125, 0xffff0000, v108
	v_lshlrev_b32_e32 v98, 16, v109
	v_and_b32_e32 v99, 0xffff0000, v109
	v_pk_add_f32 v[100:101], v[100:101], v[104:105]
	s_waitcnt vmcnt(1)
	v_lshlrev_b32_e32 v104, 16, v119
	v_and_b32_e32 v105, 0xffff0000, v119
	v_lshlrev_b32_e32 v126, 16, v128
	v_and_b32_e32 v127, 0xffff0000, v128
	v_lshlrev_b32_e32 v108, 16, v129
	v_and_b32_e32 v109, 0xffff0000, v129
	v_pk_add_f32 v[100:101], v[100:101], v[104:105]
	v_pk_add_f32 v[104:105], v[124:125], 0 op_sel_hi:[1,0]
	v_pk_add_f32 v[98:99], v[98:99], 0 op_sel_hi:[1,0]
	v_lshlrev_b32_e32 v128, 16, v160
	v_and_b32_e32 v129, 0xffff0000, v160
	v_lshlrev_b32_e32 v114, 16, v161
	v_and_b32_e32 v115, 0xffff0000, v161
	v_pk_add_f32 v[104:105], v[104:105], v[126:127]
	v_pk_add_f32 v[98:99], v[98:99], v[108:109]
	v_pk_add_f32 v[134:135], v[134:135], v[138:139]
	v_lshlrev_b32_e32 v138, 16, v106
	v_and_b32_e32 v139, 0xffff0000, v106
	v_pk_add_f32 v[104:105], v[104:105], v[128:129]
	v_lshlrev_b32_e32 v106, 16, v80
	v_and_b32_e32 v107, 0xffff0000, v80
	v_pk_add_f32 v[98:99], v[98:99], v[114:115]
	v_lshlrev_b32_e32 v80, 16, v81
	v_and_b32_e32 v81, 0xffff0000, v81
	v_pk_add_f32 v[104:105], v[104:105], v[106:107]
	v_lshlrev_b32_e32 v106, 16, v82
	v_and_b32_e32 v107, 0xffff0000, v82
	v_pk_add_f32 v[80:81], v[98:99], v[80:81]
	v_lshlrev_b32_e32 v82, 16, v83
	v_and_b32_e32 v83, 0xffff0000, v83
	v_pk_add_f32 v[80:81], v[80:81], v[82:83]
	v_lshlrev_b32_e32 v82, 16, v85
	v_and_b32_e32 v83, 0xffff0000, v85
	v_pk_add_f32 v[134:135], v[134:135], v[138:139]
	v_lshlrev_b32_e32 v138, 16, v110
	v_and_b32_e32 v139, 0xffff0000, v110
	v_pk_add_f32 v[80:81], v[80:81], v[82:83]
	v_lshlrev_b32_e32 v82, 16, v87
	v_and_b32_e32 v83, 0xffff0000, v87
	v_pk_add_f32 v[134:135], v[134:135], v[138:139]
	v_lshlrev_b32_e32 v138, 16, v112
	v_and_b32_e32 v139, 0xffff0000, v112
	v_pk_add_f32 v[104:105], v[104:105], v[106:107]
	v_lshlrev_b32_e32 v106, 16, v84
	v_and_b32_e32 v107, 0xffff0000, v84
	v_pk_add_f32 v[80:81], v[80:81], v[82:83]
	v_lshlrev_b32_e32 v82, 16, v89
	v_and_b32_e32 v83, 0xffff0000, v89
	v_pk_add_f32 v[134:135], v[134:135], v[138:139]
	v_lshlrev_b32_e32 v138, 16, v122
	v_and_b32_e32 v139, 0xffff0000, v122
	v_pk_add_f32 v[104:105], v[104:105], v[106:107]
	v_lshlrev_b32_e32 v106, 16, v86
	v_and_b32_e32 v107, 0xffff0000, v86
	v_pk_add_f32 v[80:81], v[80:81], v[82:83]
	v_lshlrev_b32_e32 v82, 16, v95
	v_and_b32_e32 v83, 0xffff0000, v95
	v_pk_add_f32 v[134:135], v[134:135], v[138:139]
	v_lshlrev_b32_e32 v138, 16, v120
	v_and_b32_e32 v139, 0xffff0000, v120
	v_pk_add_f32 v[104:105], v[104:105], v[106:107]
	v_lshlrev_b32_e32 v106, 16, v88
	v_and_b32_e32 v107, 0xffff0000, v88
	v_pk_add_f32 v[80:81], v[80:81], v[82:83]
	v_lshlrev_b32_e32 v82, 16, v93
	v_and_b32_e32 v83, 0xffff0000, v93
	v_pk_add_f32 v[134:135], v[134:135], v[138:139]
	v_lshlrev_b32_e32 v138, 16, v118
	v_and_b32_e32 v139, 0xffff0000, v118
	v_pk_add_f32 v[104:105], v[104:105], v[106:107]
	v_lshlrev_b32_e32 v106, 16, v94
	v_and_b32_e32 v107, 0xffff0000, v94
	v_pk_add_f32 v[80:81], v[80:81], v[82:83]
	s_waitcnt vmcnt(0)
	v_lshlrev_b32_e32 v82, 16, v91
	v_and_b32_e32 v83, 0xffff0000, v91
	v_mov_b32_e32 v84, v97
	v_mov_b32_e32 v85, v103
	v_pk_add_f32 v[134:135], v[134:135], v[138:139]
	v_pk_add_f32 v[104:105], v[104:105], v[106:107]
	v_lshlrev_b32_e32 v106, 16, v92
	v_and_b32_e32 v107, 0xffff0000, v92
	v_pk_add_f32 v[80:81], v[80:81], v[82:83]
	v_mov_b32_e32 v82, v96
	v_mov_b32_e32 v83, v102
	v_pk_mul_f32 v[84:85], v[84:85], v[84:85]
	v_mov_b32_e32 v86, v117
	v_mov_b32_e32 v87, v131
	v_pk_add_f32 v[104:105], v[104:105], v[106:107]
	v_lshlrev_b32_e32 v106, 16, v90
	v_and_b32_e32 v107, 0xffff0000, v90
	v_pk_fma_f32 v[82:83], v[82:83], v[82:83], v[84:85]
	v_mov_b32_e32 v84, v116
	v_mov_b32_e32 v85, v130
	v_pk_mul_f32 v[86:87], v[86:87], v[86:87]
	v_mul_f32_e32 v42, v135, v135
	v_pk_add_f32 v[104:105], v[104:105], v[106:107]
	v_pk_fma_f32 v[84:85], v[84:85], v[84:85], v[86:87]
	v_pk_fma_f32 v[86:87], v[134:135], v[134:135], v[42:43] op_sel_hi:[1,1,0]
	v_mul_f32_e32 v42, v101, v101
	v_pk_add_f32 v[82:83], v[82:83], v[82:83] op_sel:[0,1] op_sel_hi:[1,0]
	v_pk_add_f32 v[84:85], v[84:85], v[84:85] op_sel:[0,1] op_sel_hi:[1,0]
	v_pk_fma_f32 v[88:89], v[100:101], v[100:101], v[42:43] op_sel_hi:[1,1,0]
	v_pk_mul_f32 v[90:91], v[104:105], v[104:105]
	v_pk_mul_f32 v[92:93], v[80:81], v[80:81]
	v_mov_b32_e32 v83, v90
	v_mov_b32_e32 v85, v91
	v_mov_b32_e32 v87, v92
	v_mov_b32_e32 v89, v93
	v_pk_add_f32 v[82:83], v[82:83], v[84:85]
	v_pk_add_f32 v[84:85], v[86:87], v[88:89]
	v_lshlrev_b32_e32 v86, 16, v78
	v_pk_add_f32 v[82:83], v[82:83], v[84:85]
	v_lshlrev_b32_e32 v84, 16, v76
	v_add_f32_e32 v42, v82, v83
	s_nop 1
	v_mov_b32_dpp v82, v42 quad_perm:[1,0,3,2] row_mask:0xf bank_mask:0xf
	v_lshlrev_b32_e32 v88, 16, v72
	s_waitcnt lgkmcnt(0)
	v_add_f32_e32 v42, v42, v82
	s_nop 1
	v_mov_b32_dpp v82, v42 quad_perm:[2,3,0,1] row_mask:0xf bank_mask:0xf
	s_waitcnt lgkmcnt(0)
	v_add_f32_e32 v42, v42, v82
	s_nop 1
	v_mov_b32_dpp v83, v42 row_half_mirror row_mask:0xf bank_mask:0xf
	v_lshlrev_b32_e32 v82, 16, v74
	s_waitcnt lgkmcnt(0)
	v_add_f32_e32 v42, v42, v83
	s_nop 1
	v_mov_b32_dpp v85, v42 row_mirror row_mask:0xf bank_mask:0xf
	v_and_b32_e32 v83, 0xffff0000, v74
	v_lshlrev_b32_e32 v74, 16, v75
	v_and_b32_e32 v75, 0xffff0000, v75
	s_waitcnt lgkmcnt(0)
	v_add_f32_e32 v42, v42, v85
	v_mov_b32_e32 v87, v42
	s_nop 1
	v_permlane16_swap_b32 v42, v87
	v_and_b32_e32 v85, 0xffff0000, v76
	v_lshlrev_b32_e32 v76, 16, v77
	v_and_b32_e32 v77, 0xffff0000, v77
	s_waitcnt lgkmcnt(0)
	v_add_f32_e32 v42, v42, v87
	v_mov_b32_e32 v89, v42
	s_nop 1
	v_permlane32_swap_b32 v42, v89
	v_and_b32_e32 v87, 0xffff0000, v78
	v_lshlrev_b32_e32 v78, 16, v79
	v_and_b32_e32 v79, 0xffff0000, v79
	s_waitcnt lgkmcnt(0)
	v_add_f32_e32 v42, v42, v89
	v_fmamk_f32 v42, v42, 0x3a800000, v146
	v_mul_f32_e32 v89, 0x4b800000, v42
	v_cmp_gt_f32_e32 vcc, s97, v42
	s_nop 1
	v_cndmask_b32_e32 v42, v42, v89, vcc
	v_rsq_f32_e32 v42, v42
	v_and_b32_e32 v89, 0xffff0000, v72
	v_lshlrev_b32_e32 v72, 16, v73
	v_and_b32_e32 v73, 0xffff0000, v73
	v_mul_f32_e32 v90, 0x45800000, v42
	v_cndmask_b32_e32 v42, v42, v90, vcc
	v_pk_mul_f32 v[90:91], v[96:97], v[42:43] op_sel_hi:[1,0]
	v_pk_mul_f32 v[92:93], v[102:103], v[42:43] op_sel_hi:[1,0]
	v_pk_fma_f32 v[82:83], v[0:1], v[90:91], v[82:83]
	v_pk_fma_f32 v[74:75], v[2:3], v[92:93], v[74:75]
	v_pk_mul_f32 v[92:93], v[82:83], v[82:83]
	v_pk_mul_f32 v[90:91], v[74:75], v[74:75]
	v_pk_mul_f32 v[80:81], v[80:81], v[42:43] op_sel_hi:[1,0]
	v_pk_mov_b32 v[94:95], v[92:93], v[90:91] op_sel:[1,0]
	v_mov_b32_e32 v93, v91
	v_pk_add_f32 v[90:91], v[94:95], v[92:93]
	v_pk_mul_f32 v[92:93], v[130:131], v[42:43] op_sel_hi:[1,0]
	v_pk_mul_f32 v[94:95], v[116:117], v[42:43] op_sel_hi:[1,0]
	v_pk_fma_f32 v[76:77], v[6:7], v[92:93], v[76:77]
	v_pk_fma_f32 v[84:85], v[4:5], v[94:95], v[84:85]
	v_pk_mul_f32 v[92:93], v[76:77], v[76:77]
	v_pk_mul_f32 v[94:95], v[84:85], v[84:85]
	v_pk_add_f32 v[90:91], v[90:91], v[90:91] op_sel_hi:[0,1]
	v_pk_mov_b32 v[96:97], v[94:95], v[92:93] op_sel:[1,0]
	v_mov_b32_e32 v95, v93
	v_pk_add_f32 v[92:93], v[96:97], v[94:95]
	v_pk_mul_f32 v[96:97], v[134:135], v[42:43] op_sel_hi:[1,0]
	v_pk_mul_f32 v[94:95], v[100:101], v[42:43] op_sel_hi:[1,0]
	v_pk_fma_f32 v[86:87], v[16:17], v[96:97], v[86:87]
	v_pk_fma_f32 v[78:79], v[18:19], v[94:95], v[78:79]
	v_mul_f32_e32 v90, v86, v86
	v_pk_fma_f32 v[94:95], v[86:87], v[86:87], v[90:91] op_sel_hi:[1,1,0]
	v_mul_f32_e32 v90, v78, v78
	v_pk_mul_f32 v[98:99], v[104:105], v[42:43] op_sel_hi:[1,0]
	v_pk_add_f32 v[92:93], v[92:93], v[92:93] op_sel_hi:[0,1]
	v_pk_fma_f32 v[96:97], v[78:79], v[78:79], v[90:91] op_sel_hi:[1,1,0]
	v_pk_fma_f32 v[88:89], v[20:21], v[98:99], v[88:89]
	v_pk_fma_f32 v[72:73], v[22:23], v[80:81], v[72:73]
	v_mul_f32_e32 v94, v88, v88
	v_mul_f32_e32 v96, v89, v89
	v_mul_f32_e32 v90, v72, v72
	v_mul_f32_e32 v92, v73, v73
	v_pk_add_f32 v[80:81], v[94:95], v[96:97]
	v_pk_add_f32 v[90:91], v[90:91], v[92:93]
	v_cvt_pk_bf16_f32 v94, v82, v83
	v_lshl_add_u64 v[92:93], v[48:49], 0, s[68:69]
	v_pk_add_f32 v[80:81], v[80:81], v[90:91]
	s_nop 0
	v_add_f32_e32 v42, v80, v81
	s_nop 1
	v_mov_b32_dpp v80, v42 quad_perm:[1,0,3,2] row_mask:0xf bank_mask:0xf
	s_waitcnt lgkmcnt(0)
	v_add_f32_e32 v42, v42, v80
	s_nop 1
	v_mov_b32_dpp v80, v42 quad_perm:[2,3,0,1] row_mask:0xf bank_mask:0xf
	s_waitcnt lgkmcnt(0)
	v_add_f32_e32 v42, v42, v80
	s_nop 1
	v_mov_b32_dpp v90, v42 row_half_mirror row_mask:0xf bank_mask:0xf
	v_lshl_add_u64 v[80:81], v[48:49], 0, s[62:63]
	s_waitcnt lgkmcnt(0)
	v_add_f32_e32 v42, v42, v90
	s_nop 1
	v_mov_b32_dpp v95, v42 row_mirror row_mask:0xf bank_mask:0xf
	v_lshl_add_u64 v[90:91], v[48:49], 0, s[64:65]
	v_lshl_add_u64 v[48:49], v[48:49], 0, s[70:71]
	s_waitcnt lgkmcnt(0)
	v_add_f32_e32 v42, v42, v95
	v_mov_b32_e32 v96, v42
	s_nop 1
	v_permlane16_swap_b32 v42, v96
	v_cvt_pk_bf16_f32 v95, v74, v75
	s_waitcnt lgkmcnt(0)
	v_add_f32_e32 v42, v42, v96
	v_mov_b32_e32 v208, v94
	v_mov_b32_e32 v209, v95
	s_nop 1
	v_mov_b32_e32 v94, v42
	s_nop 1
	v_permlane32_swap_b32 v42, v94
	v_cvt_pk_bf16_f32 v80, v84, v85
	v_cvt_pk_bf16_f32 v81, v76, v77
	s_waitcnt lgkmcnt(0)
	v_add_f32_e32 v42, v42, v94
	v_mov_b32_e32 v210, v80
	v_mov_b32_e32 v211, v81
	s_nop 1
	v_cvt_pk_bf16_f32 v80, v86, v87
	v_fmamk_f32 v42, v42, 0x3a800000, v146
	v_cvt_pk_bf16_f32 v81, v78, v79
	v_cmp_gt_f32_e32 vcc, s97, v42
	v_mov_b32_e32 v212, v80
	v_mov_b32_e32 v213, v81
	s_nop 1
	v_mul_f32_e32 v80, 0x4b800000, v42
	s_nop 0
	v_cndmask_b32_e32 v42, v42, v80, vcc
	v_rsq_f32_e32 v42, v42
	v_cvt_pk_bf16_f32 v80, v88, v89
	v_cvt_pk_bf16_f32 v81, v72, v73
	s_nop 0
	v_and_b32_e32 v232, 1, v152
	v_cmp_eq_u32_e64 s[98:99], 1, v232
	v_mul_u32_u24_e32 v230, 0x1f8, v232
	v_mov_b32_e32 v231, 0
	v_lshl_add_u64 v[228:229], v[48:49], 0, v[230:231]
	v_cndmask_b32_e64 v216, v210, v208, s[98:99]
	v_cndmask_b32_e64 v217, v211, v209, s[98:99]
	s_nop 1
	v_mov_b32_dpp v218, v216 quad_perm:[1,0,3,2] row_mask:0xf bank_mask:0xf
	v_mov_b32_dpp v219, v217 quad_perm:[1,0,3,2] row_mask:0xf bank_mask:0xf
	v_cndmask_b32_e64 v220, v208, v218, s[98:99]
	v_cndmask_b32_e64 v221, v209, v219, s[98:99]
	v_cndmask_b32_e64 v222, v218, v210, s[98:99]
	v_cndmask_b32_e64 v223, v219, v211, s[98:99]
	global_store_dwordx4 v[228:229], v[220:223], off offset:-1536 sc0 sc1
	s_nop 1
	v_cndmask_b32_e64 v216, v80, v212, s[98:99]
	v_cndmask_b32_e64 v217, v81, v213, s[98:99]
	s_nop 1
	v_mov_b32_dpp v218, v216 quad_perm:[1,0,3,2] row_mask:0xf bank_mask:0xf
	v_mov_b32_dpp v219, v217 quad_perm:[1,0,3,2] row_mask:0xf bank_mask:0xf
	v_cndmask_b32_e64 v224, v212, v218, s[98:99]
	v_cndmask_b32_e64 v225, v213, v219, s[98:99]
	v_cndmask_b32_e64 v226, v218, v80, s[98:99]
	v_cndmask_b32_e64 v227, v219, v81, s[98:99]
	global_store_dwordx4 v[228:229], v[224:227], off offset:-512 sc0 sc1
	s_nop 1
	s_mov_b32 s99, 0
	s_nop 1
	v_mul_f32_e32 v48, 0x45800000, v42
	v_cndmask_b32_e32 v42, v42, v48, vcc
	v_pk_mul_f32 v[82:83], v[82:83], v[42:43] op_sel_hi:[1,0]
	v_pk_mul_f32 v[74:75], v[74:75], v[42:43] op_sel_hi:[1,0]
	v_pk_mul_f32 v[82:83], v[24:25], v[82:83]
	v_pk_mul_f32 v[74:75], v[26:27], v[74:75]
	v_cvt_pk_bf16_f32 v82, v82, v83
	v_lshl_add_u64 v[48:49], v[44:45], 0, s[82:83]
	v_cvt_pk_bf16_f32 v83, v74, v75
	v_pk_mul_f32 v[74:75], v[84:85], v[42:43] op_sel_hi:[1,0]
	v_pk_mul_f32 v[76:77], v[76:77], v[42:43] op_sel_hi:[1,0]
	v_pk_mul_f32 v[74:75], v[8:9], v[74:75]
	v_lshl_add_u64 v[80:81], v[48:49], 0, s[6:7]
	v_mov_b32_e32 v208, v82
	v_mov_b32_e32 v209, v83
	s_nop 1
	v_pk_mul_f32 v[76:77], v[10:11], v[76:77]
	v_cvt_pk_bf16_f32 v74, v74, v75
	s_mov_b64 s[6:7], 0x3800200
	v_cvt_pk_bf16_f32 v75, v76, v77
	v_lshl_add_u64 v[76:77], v[48:49], 0, s[6:7]
	v_mov_b32_e32 v210, v74
	v_mov_b32_e32 v211, v75
	s_nop 1
	v_pk_mul_f32 v[74:75], v[86:87], v[42:43] op_sel_hi:[1,0]
	v_pk_mul_f32 v[76:77], v[78:79], v[42:43] op_sel_hi:[1,0]
	v_pk_mul_f32 v[74:75], v[12:13], v[74:75]
	v_pk_mul_f32 v[76:77], v[14:15], v[76:77]
	v_cvt_pk_bf16_f32 v74, v74, v75
	s_mov_b64 s[6:7], 0x3800400
	v_cvt_pk_bf16_f32 v75, v76, v77
	v_lshl_add_u64 v[76:77], v[48:49], 0, s[6:7]
	v_mov_b32_e32 v212, v74
	v_mov_b32_e32 v213, v75
	s_nop 1
	v_pk_mul_f32 v[74:75], v[88:89], v[42:43] op_sel_hi:[1,0]
	v_pk_mul_f32 v[72:73], v[72:73], v[42:43] op_sel_hi:[1,0]
	v_pk_mul_f32 v[74:75], v[28:29], v[74:75]
	v_pk_mul_f32 v[72:73], v[30:31], v[72:73]
	s_mov_b64 s[6:7], 0x3800600
	v_cvt_pk_bf16_f32 v74, v74, v75
	v_cvt_pk_bf16_f32 v75, v72, v73
	v_lshl_add_u64 v[72:73], v[48:49], 0, s[6:7]
	v_and_b32_e32 v232, 1, v152
	v_cmp_eq_u32_e64 s[98:99], 1, v232
	v_mul_u32_u24_e32 v230, 0x1f8, v232
	v_mov_b32_e32 v231, 0
	v_lshl_add_u64 v[228:229], v[72:73], 0, v[230:231]
	v_cndmask_b32_e64 v216, v210, v208, s[98:99]
	v_cndmask_b32_e64 v217, v211, v209, s[98:99]
	s_nop 1
	v_mov_b32_dpp v218, v216 quad_perm:[1,0,3,2] row_mask:0xf bank_mask:0xf
	v_mov_b32_dpp v219, v217 quad_perm:[1,0,3,2] row_mask:0xf bank_mask:0xf
	v_cndmask_b32_e64 v220, v208, v218, s[98:99]
	v_cndmask_b32_e64 v221, v209, v219, s[98:99]
	v_cndmask_b32_e64 v222, v218, v210, s[98:99]
	v_cndmask_b32_e64 v223, v219, v211, s[98:99]
	global_store_dwordx4 v[228:229], v[220:223], off offset:-1536 sc0 sc1
	s_nop 1
	v_cndmask_b32_e64 v216, v74, v212, s[98:99]
	v_cndmask_b32_e64 v217, v75, v213, s[98:99]
	s_nop 1
	v_mov_b32_dpp v218, v216 quad_perm:[1,0,3,2] row_mask:0xf bank_mask:0xf
	v_mov_b32_dpp v219, v217 quad_perm:[1,0,3,2] row_mask:0xf bank_mask:0xf
	v_cndmask_b32_e64 v224, v212, v218, s[98:99]
	v_cndmask_b32_e64 v225, v213, v219, s[98:99]
	v_cndmask_b32_e64 v226, v218, v74, s[98:99]
	v_cndmask_b32_e64 v227, v219, v75, s[98:99]
	global_store_dwordx4 v[228:229], v[224:227], off offset:-512 sc0 sc1
	s_nop 1
	s_mov_b32 s99, 0
	s_nop 1
	s_mov_b64 s[6:7], -1
	s_cbranch_scc1 .LBB0_1405
	s_add_u32 s6, s16, s0
	s_addc_u32 s7, 0, s1
	s_add_u32 s8, s6, 1
	s_addc_u32 s9, s7, 0
	s_mov_b64 s[6:7], 0

.LBB0_1421:
	s_or_b64 exec, exec, s[10:11]
	s_lshl_b64 s[0:1], s[0:1], 12
	s_add_u32 s0, s8, s0
	s_addc_u32 s1, s9, s1
	v_lshl_add_u64 v[44:45], v[32:33], 3, s[0:1]
	s_lshl_b64 s[0:1], s[80:81], 11
	v_lshl_add_u64 v[54:55], v[38:39], 0, s[0:1]
	global_load_dwordx2 v[46:47], v[44:45], off offset:2048
	global_load_dwordx2 v[48:49], v[44:45], off offset:2560
	global_load_dwordx2 v[50:51], v[44:45], off offset:3072
	global_load_dwordx2 v[52:53], v[44:45], off offset:3584
	global_load_dwordx2 v[56:57], v[54:55], off
	global_load_dwordx2 v[58:59], v[54:55], off offset:512
	global_load_dwordx2 v[60:61], v[54:55], off offset:1024
	s_nop 0
	global_load_dwordx2 v[54:55], v[54:55], off offset:1536
	s_waitcnt vmcnt(8)
	s_nop 1
	v_mov_b32_dpp v62, v42 quad_perm:[1,0,3,2] row_mask:0xf bank_mask:0xf
	s_mov_b64 s[8:9], -1
	s_waitcnt lgkmcnt(0)
	v_add_f32_e32 v42, v42, v62
	s_nop 1
	v_mov_b32_dpp v62, v42 quad_perm:[2,3,0,1] row_mask:0xf bank_mask:0xf
	s_waitcnt lgkmcnt(0)
	v_add_f32_e32 v42, v42, v62
	s_nop 1
	v_mov_b32_dpp v62, v42 row_half_mirror row_mask:0xf bank_mask:0xf
	s_waitcnt lgkmcnt(0)
	v_add_f32_e32 v42, v42, v62
	s_nop 1
	v_mov_b32_dpp v62, v42 row_mirror row_mask:0xf bank_mask:0xf
	s_waitcnt lgkmcnt(0)
	v_add_f32_e32 v42, v42, v62
	v_mov_b32_e32 v62, v42
	s_nop 1
	v_permlane16_swap_b32 v42, v62
	s_waitcnt lgkmcnt(0)
	v_add_f32_e32 v42, v42, v62
	v_mov_b32_e32 v62, v42
	s_nop 1
	v_permlane32_swap_b32 v42, v62
	s_waitcnt lgkmcnt(0)
	v_add_f32_e32 v42, v42, v62
	v_fmamk_f32 v42, v42, 0x3a800000, v146
	v_mul_f32_e32 v62, 0x4b800000, v42
	v_cmp_gt_f32_e32 vcc, s97, v42
	s_waitcnt vmcnt(7)
	v_and_b32_e32 v63, 0xffff0000, v46
	v_cndmask_b32_e32 v42, v42, v62, vcc
	v_rsq_f32_e32 v42, v42
	s_waitcnt vmcnt(3)
	v_lshlrev_b32_e32 v70, 16, v56
	v_and_b32_e32 v71, 0xffff0000, v56
	v_lshlrev_b32_e32 v56, 16, v57
	v_mul_f32_e32 v62, 0x45800000, v42
	v_cndmask_b32_e32 v42, v42, v62, vcc
	v_and_b32_e32 v57, 0xffff0000, v57
	s_waitcnt vmcnt(2)
	v_lshlrev_b32_e32 v72, 16, v58
	v_and_b32_e32 v73, 0xffff0000, v58
	v_lshlrev_b32_e32 v58, 16, v59
	v_and_b32_e32 v59, 0xffff0000, v59
	v_lshlrev_b32_e32 v62, 16, v46
	v_lshlrev_b32_e32 v46, 16, v47
	v_and_b32_e32 v47, 0xffff0000, v47
	v_lshlrev_b32_e32 v64, 16, v48
	v_and_b32_e32 v65, 0xffff0000, v48
	v_lshlrev_b32_e32 v48, 16, v49
	v_and_b32_e32 v49, 0xffff0000, v49
	s_waitcnt vmcnt(1)
	v_lshlrev_b32_e32 v74, 16, v60
	v_and_b32_e32 v75, 0xffff0000, v60
	v_lshlrev_b32_e32 v60, 16, v61
	v_and_b32_e32 v61, 0xffff0000, v61
	v_pk_mul_f32 v[70:71], v[42:43], v[70:71] op_sel_hi:[0,1]
	v_pk_mul_f32 v[56:57], v[42:43], v[56:57] op_sel_hi:[0,1]
	v_pk_mul_f32 v[58:59], v[42:43], v[58:59] op_sel_hi:[0,1]
	v_pk_mul_f32 v[72:73], v[42:43], v[72:73] op_sel_hi:[0,1]
	v_lshlrev_b32_e32 v66, 16, v50
	v_and_b32_e32 v67, 0xffff0000, v50
	v_lshlrev_b32_e32 v50, 16, v51
	v_and_b32_e32 v51, 0xffff0000, v51
	v_pk_mul_f32 v[60:61], v[42:43], v[60:61] op_sel_hi:[0,1]
	v_pk_mul_f32 v[74:75], v[42:43], v[74:75] op_sel_hi:[0,1]
	v_pk_fma_f32 v[46:47], v[2:3], v[56:57], v[46:47]
	v_pk_fma_f32 v[56:57], v[0:1], v[70:71], v[62:63]
	v_pk_fma_f32 v[62:63], v[4:5], v[72:73], v[64:65]
	v_pk_fma_f32 v[48:49], v[6:7], v[58:59], v[48:49]
	v_pk_fma_f32 v[58:59], v[16:17], v[74:75], v[66:67]
	v_pk_fma_f32 v[50:51], v[18:19], v[60:61], v[50:51]
	v_pk_mul_f32 v[60:61], v[46:47], v[46:47]
	v_pk_mul_f32 v[64:65], v[56:57], v[56:57]
	v_pk_mul_f32 v[66:67], v[48:49], v[48:49]
	v_pk_mul_f32 v[70:71], v[62:63], v[62:63]
	v_pk_mov_b32 v[74:75], v[64:65], v[60:61] op_sel:[1,0]
	v_mov_b32_e32 v65, v61
	v_pk_mov_b32 v[60:61], v[70:71], v[66:67] op_sel:[1,0]
	v_mov_b32_e32 v71, v67
	v_pk_add_f32 v[60:61], v[60:61], v[70:71]
	s_waitcnt vmcnt(0)
	v_lshlrev_b32_e32 v76, 16, v54
	v_and_b32_e32 v77, 0xffff0000, v54
	v_lshlrev_b32_e32 v54, 16, v55
	v_and_b32_e32 v55, 0xffff0000, v55
	v_mul_f32_e32 v72, v58, v58
	v_pk_add_f32 v[60:61], v[60:61], v[60:61] op_sel_hi:[0,1]
	v_lshlrev_b32_e32 v68, 16, v52
	v_and_b32_e32 v69, 0xffff0000, v52
	v_lshlrev_b32_e32 v52, 16, v53
	v_and_b32_e32 v53, 0xffff0000, v53
	v_pk_fma_f32 v[66:67], v[58:59], v[58:59], v[72:73] op_sel_hi:[1,1,0]
	v_pk_add_f32 v[64:65], v[74:75], v[64:65]
	v_mul_f32_e32 v60, v50, v50
	v_pk_mul_f32 v[54:55], v[42:43], v[54:55] op_sel_hi:[0,1]
	v_pk_mul_f32 v[72:73], v[42:43], v[76:77] op_sel_hi:[0,1]
	v_pk_add_f32 v[64:65], v[64:65], v[64:65] op_sel_hi:[0,1]
	v_pk_fma_f32 v[70:71], v[50:51], v[50:51], v[60:61] op_sel_hi:[1,1,0]
	v_pk_fma_f32 v[68:69], v[20:21], v[72:73], v[68:69]
	v_pk_fma_f32 v[52:53], v[22:23], v[54:55], v[52:53]
	v_mul_f32_e32 v66, v68, v68
	v_mul_f32_e32 v70, v69, v69
	v_mul_f32_e32 v64, v52, v52
	v_mul_f32_e32 v60, v53, v53
	v_pk_add_f32 v[54:55], v[66:67], v[70:71]
	v_pk_add_f32 v[60:61], v[64:65], v[60:61]
	v_cvt_pk_bf16_f32 v66, v56, v57
	v_lshl_add_u64 v[64:65], v[44:45], 0, s[68:69]
	v_pk_add_f32 v[54:55], v[54:55], v[60:61]
	s_nop 0
	v_add_f32_e32 v42, v54, v55
	s_nop 1
	v_mov_b32_dpp v54, v42 quad_perm:[1,0,3,2] row_mask:0xf bank_mask:0xf
	s_waitcnt lgkmcnt(0)
	v_add_f32_e32 v42, v42, v54
	s_nop 1
	v_mov_b32_dpp v54, v42 quad_perm:[2,3,0,1] row_mask:0xf bank_mask:0xf
	s_waitcnt lgkmcnt(0)
	v_add_f32_e32 v42, v42, v54
	s_nop 1
	v_mov_b32_dpp v60, v42 row_half_mirror row_mask:0xf bank_mask:0xf
	v_lshl_add_u64 v[54:55], v[44:45], 0, s[62:63]
	s_waitcnt lgkmcnt(0)
	v_add_f32_e32 v42, v42, v60
	s_nop 1
	v_mov_b32_dpp v67, v42 row_mirror row_mask:0xf bank_mask:0xf
	v_lshl_add_u64 v[60:61], v[44:45], 0, s[64:65]
	v_lshl_add_u64 v[44:45], v[44:45], 0, s[70:71]
	s_waitcnt lgkmcnt(0)
	v_add_f32_e32 v42, v42, v67
	v_mov_b32_e32 v70, v42
	s_nop 1
	v_permlane16_swap_b32 v42, v70
	v_cvt_pk_bf16_f32 v67, v46, v47
	s_waitcnt lgkmcnt(0)
	v_add_f32_e32 v42, v42, v70
	v_mov_b32_e32 v208, v66
	v_mov_b32_e32 v209, v67
	s_nop 1
	v_mov_b32_e32 v66, v42
	s_nop 1
	v_permlane32_swap_b32 v42, v66
	v_cvt_pk_bf16_f32 v54, v62, v63
	v_cvt_pk_bf16_f32 v55, v48, v49
	s_waitcnt lgkmcnt(0)
	v_add_f32_e32 v42, v42, v66
	v_mov_b32_e32 v210, v54
	v_mov_b32_e32 v211, v55
	s_nop 1
	v_cvt_pk_bf16_f32 v54, v58, v59
	v_fmamk_f32 v42, v42, 0x3a800000, v146
	v_cvt_pk_bf16_f32 v55, v50, v51
	v_cmp_gt_f32_e32 vcc, s97, v42
	v_mov_b32_e32 v212, v54
	v_mov_b32_e32 v213, v55
	s_nop 1
	v_mul_f32_e32 v54, 0x4b800000, v42
	s_nop 0
	v_cndmask_b32_e32 v42, v42, v54, vcc
	v_rsq_f32_e32 v42, v42
	v_cvt_pk_bf16_f32 v54, v68, v69
	v_cvt_pk_bf16_f32 v55, v52, v53
	s_nop 0
	v_and_b32_e32 v232, 1, v152
	v_cmp_eq_u32_e64 s[98:99], 1, v232
	v_mul_u32_u24_e32 v230, 0x1f8, v232
	v_mov_b32_e32 v231, 0
	v_lshl_add_u64 v[228:229], v[44:45], 0, v[230:231]
	v_cndmask_b32_e64 v216, v210, v208, s[98:99]
	v_cndmask_b32_e64 v217, v211, v209, s[98:99]
	s_nop 1
	v_mov_b32_dpp v218, v216 quad_perm:[1,0,3,2] row_mask:0xf bank_mask:0xf
	v_mov_b32_dpp v219, v217 quad_perm:[1,0,3,2] row_mask:0xf bank_mask:0xf
	v_cndmask_b32_e64 v220, v208, v218, s[98:99]
	v_cndmask_b32_e64 v221, v209, v219, s[98:99]
	v_cndmask_b32_e64 v222, v218, v210, s[98:99]
	v_cndmask_b32_e64 v223, v219, v211, s[98:99]
	global_store_dwordx4 v[228:229], v[220:223], off offset:-1536 sc0 sc1
	s_nop 1
	v_cndmask_b32_e64 v216, v54, v212, s[98:99]
	v_cndmask_b32_e64 v217, v55, v213, s[98:99]
	s_nop 1
	v_mov_b32_dpp v218, v216 quad_perm:[1,0,3,2] row_mask:0xf bank_mask:0xf
	v_mov_b32_dpp v219, v217 quad_perm:[1,0,3,2] row_mask:0xf bank_mask:0xf
	v_cndmask_b32_e64 v224, v212, v218, s[98:99]
	v_cndmask_b32_e64 v225, v213, v219, s[98:99]
	v_cndmask_b32_e64 v226, v218, v54, s[98:99]
	v_cndmask_b32_e64 v227, v219, v55, s[98:99]
	global_store_dwordx4 v[228:229], v[224:227], off offset:-512 sc0 sc1
	s_nop 1
	s_mov_b32 s99, 0
	s_nop 1
	v_mul_f32_e32 v44, 0x45800000, v42
	v_cndmask_b32_e32 v42, v42, v44, vcc
	v_pk_mul_f32 v[54:55], v[56:57], v[42:43] op_sel_hi:[1,0]
	v_pk_mul_f32 v[46:47], v[46:47], v[42:43] op_sel_hi:[1,0]
	v_pk_mul_f32 v[54:55], v[24:25], v[54:55]
	v_pk_mul_f32 v[46:47], v[26:27], v[46:47]
	v_cvt_pk_bf16_f32 v54, v54, v55
	v_pk_mul_f32 v[48:49], v[48:49], v[42:43] op_sel_hi:[1,0]
	v_cvt_pk_bf16_f32 v55, v46, v47
	v_pk_mul_f32 v[46:47], v[62:63], v[42:43] op_sel_hi:[1,0]
	v_lshl_add_u64 v[44:45], v[36:37], 0, s[0:1]
	v_pk_mul_f32 v[46:47], v[8:9], v[46:47]
	v_mov_b32_e32 v208, v54
	v_mov_b32_e32 v209, v55
	s_nop 1
	v_pk_mul_f32 v[48:49], v[10:11], v[48:49]
	v_cvt_pk_bf16_f32 v46, v46, v47
	s_andn2_b64 vcc, exec, s[6:7]
	v_cvt_pk_bf16_f32 v47, v48, v49
	v_lshl_add_u64 v[48:49], v[44:45], 0, s[72:73]
	v_mov_b32_e32 v210, v46
	v_mov_b32_e32 v211, v47
	s_nop 1
	v_pk_mul_f32 v[46:47], v[58:59], v[42:43] op_sel_hi:[1,0]
	v_pk_mul_f32 v[48:49], v[50:51], v[42:43] op_sel_hi:[1,0]
	v_pk_mul_f32 v[46:47], v[12:13], v[46:47]
	v_pk_mul_f32 v[48:49], v[14:15], v[48:49]
	v_cvt_pk_bf16_f32 v46, v46, v47
	s_nop 0
	v_cvt_pk_bf16_f32 v47, v48, v49
	v_lshl_add_u64 v[48:49], v[44:45], 0, s[74:75]
	v_mov_b32_e32 v212, v46
	v_mov_b32_e32 v213, v47
	s_nop 1
	v_pk_mul_f32 v[46:47], v[68:69], v[42:43] op_sel_hi:[1,0]
	v_pk_mul_f32 v[48:49], v[52:53], v[42:43] op_sel_hi:[1,0]
	v_pk_mul_f32 v[46:47], v[28:29], v[46:47]
	v_pk_mul_f32 v[48:49], v[30:31], v[48:49]
	v_cvt_pk_bf16_f32 v46, v46, v47
	v_lshl_add_u64 v[44:45], v[44:45], 0, s[78:79]
	v_cvt_pk_bf16_f32 v47, v48, v49
	v_cndmask_b32_e64 v42, 0, 1, s[6:7]
	v_and_b32_e32 v232, 1, v152
	v_cmp_eq_u32_e64 s[98:99], 1, v232
	v_mul_u32_u24_e32 v230, 0x1f8, v232
	v_mov_b32_e32 v231, 0
	v_lshl_add_u64 v[228:229], v[44:45], 0, v[230:231]
	v_cndmask_b32_e64 v216, v210, v208, s[98:99]
	v_cndmask_b32_e64 v217, v211, v209, s[98:99]
	s_nop 1
	v_mov_b32_dpp v218, v216 quad_perm:[1,0,3,2] row_mask:0xf bank_mask:0xf
	v_mov_b32_dpp v219, v217 quad_perm:[1,0,3,2] row_mask:0xf bank_mask:0xf
	v_cndmask_b32_e64 v220, v208, v218, s[98:99]
	v_cndmask_b32_e64 v221, v209, v219, s[98:99]
	v_cndmask_b32_e64 v222, v218, v210, s[98:99]
	v_cndmask_b32_e64 v223, v219, v211, s[98:99]
	global_store_dwordx4 v[228:229], v[220:223], off offset:-1536 sc0 sc1
	s_nop 1
	v_cndmask_b32_e64 v216, v46, v212, s[98:99]
	v_cndmask_b32_e64 v217, v47, v213, s[98:99]
	s_nop 1
	v_mov_b32_dpp v218, v216 quad_perm:[1,0,3,2] row_mask:0xf bank_mask:0xf
	v_mov_b32_dpp v219, v217 quad_perm:[1,0,3,2] row_mask:0xf bank_mask:0xf
	v_cndmask_b32_e64 v224, v212, v218, s[98:99]
	v_cndmask_b32_e64 v225, v213, v219, s[98:99]
	v_cndmask_b32_e64 v226, v218, v46, s[98:99]
	v_cndmask_b32_e64 v227, v219, v47, s[98:99]
	global_store_dwordx4 v[228:229], v[224:227], off offset:-512 sc0 sc1
	s_nop 1
	s_mov_b32 s99, 0
	s_nop 1
	v_cmp_ne_u32_e64 s[0:1], 1, v42
	s_cbranch_vccnz .LBB0_1423
	s_add_i32 s56, s80, 0xffffbf81
	s_mov_b64 s[8:9], 0
	s_mov_b64 s[6:7], s[56:57]

.LBB0_1430:
	s_or_b64 exec, exec, s[10:11]
	s_lshl_b64 s[6:7], s[6:7], 12
	s_add_u32 s6, s8, s6
	s_addc_u32 s7, s9, s7
	v_lshl_add_u64 v[44:45], v[32:33], 3, s[6:7]
	s_lshl_b64 s[6:7], s[56:57], 11
	v_lshl_add_u64 v[54:55], v[38:39], 0, s[6:7]
	global_load_dwordx2 v[46:47], v[44:45], off offset:2048
	global_load_dwordx2 v[48:49], v[44:45], off offset:2560
	global_load_dwordx2 v[50:51], v[44:45], off offset:3072
	global_load_dwordx2 v[52:53], v[44:45], off offset:3584
	global_load_dwordx2 v[56:57], v[54:55], off
	global_load_dwordx2 v[58:59], v[54:55], off offset:512
	global_load_dwordx2 v[60:61], v[54:55], off offset:1024
	s_nop 0
	global_load_dwordx2 v[54:55], v[54:55], off offset:1536
	s_waitcnt vmcnt(8)
	s_nop 1
	v_mov_b32_dpp v62, v42 quad_perm:[1,0,3,2] row_mask:0xf bank_mask:0xf
	s_mov_b64 s[8:9], -1
	s_waitcnt lgkmcnt(0)
	v_add_f32_e32 v42, v42, v62
	s_nop 1
	v_mov_b32_dpp v62, v42 quad_perm:[2,3,0,1] row_mask:0xf bank_mask:0xf
	s_waitcnt lgkmcnt(0)
	v_add_f32_e32 v42, v42, v62
	s_nop 1
	v_mov_b32_dpp v62, v42 row_half_mirror row_mask:0xf bank_mask:0xf
	s_waitcnt lgkmcnt(0)
	v_add_f32_e32 v42, v42, v62
	s_nop 1
	v_mov_b32_dpp v62, v42 row_mirror row_mask:0xf bank_mask:0xf
	s_waitcnt lgkmcnt(0)
	v_add_f32_e32 v42, v42, v62
	v_mov_b32_e32 v62, v42
	s_nop 1
	v_permlane16_swap_b32 v42, v62
	s_waitcnt lgkmcnt(0)
	v_add_f32_e32 v42, v42, v62
	v_mov_b32_e32 v62, v42
	s_nop 1
	v_permlane32_swap_b32 v42, v62
	s_waitcnt lgkmcnt(0)
	v_add_f32_e32 v42, v42, v62
	v_fmamk_f32 v42, v42, 0x3a800000, v146
	v_mul_f32_e32 v62, 0x4b800000, v42
	v_cmp_gt_f32_e32 vcc, s97, v42
	s_waitcnt vmcnt(7)
	v_and_b32_e32 v63, 0xffff0000, v46
	v_cndmask_b32_e32 v42, v42, v62, vcc
	v_rsq_f32_e32 v42, v42
	s_waitcnt vmcnt(3)
	v_lshlrev_b32_e32 v70, 16, v56
	v_and_b32_e32 v71, 0xffff0000, v56
	v_lshlrev_b32_e32 v56, 16, v57
	v_mul_f32_e32 v62, 0x45800000, v42
	v_cndmask_b32_e32 v42, v42, v62, vcc
	v_and_b32_e32 v57, 0xffff0000, v57
	s_waitcnt vmcnt(2)
	v_lshlrev_b32_e32 v72, 16, v58
	v_and_b32_e32 v73, 0xffff0000, v58
	v_lshlrev_b32_e32 v58, 16, v59
	v_and_b32_e32 v59, 0xffff0000, v59
	v_lshlrev_b32_e32 v62, 16, v46
	v_lshlrev_b32_e32 v46, 16, v47
	v_and_b32_e32 v47, 0xffff0000, v47
	v_lshlrev_b32_e32 v64, 16, v48
	v_and_b32_e32 v65, 0xffff0000, v48
	v_lshlrev_b32_e32 v48, 16, v49
	v_and_b32_e32 v49, 0xffff0000, v49
	s_waitcnt vmcnt(1)
	v_lshlrev_b32_e32 v74, 16, v60
	v_and_b32_e32 v75, 0xffff0000, v60
	v_lshlrev_b32_e32 v60, 16, v61
	v_and_b32_e32 v61, 0xffff0000, v61
	v_pk_mul_f32 v[70:71], v[42:43], v[70:71] op_sel_hi:[0,1]
	v_pk_mul_f32 v[56:57], v[42:43], v[56:57] op_sel_hi:[0,1]
	v_pk_mul_f32 v[58:59], v[42:43], v[58:59] op_sel_hi:[0,1]
	v_pk_mul_f32 v[72:73], v[42:43], v[72:73] op_sel_hi:[0,1]
	v_lshlrev_b32_e32 v66, 16, v50
	v_and_b32_e32 v67, 0xffff0000, v50
	v_lshlrev_b32_e32 v50, 16, v51
	v_and_b32_e32 v51, 0xffff0000, v51
	v_pk_mul_f32 v[60:61], v[42:43], v[60:61] op_sel_hi:[0,1]
	v_pk_mul_f32 v[74:75], v[42:43], v[74:75] op_sel_hi:[0,1]
	v_pk_fma_f32 v[46:47], v[2:3], v[56:57], v[46:47]
	v_pk_fma_f32 v[56:57], v[0:1], v[70:71], v[62:63]
	v_pk_fma_f32 v[62:63], v[4:5], v[72:73], v[64:65]
	v_pk_fma_f32 v[48:49], v[6:7], v[58:59], v[48:49]
	v_pk_fma_f32 v[58:59], v[16:17], v[74:75], v[66:67]
	v_pk_fma_f32 v[50:51], v[18:19], v[60:61], v[50:51]
	v_pk_mul_f32 v[60:61], v[46:47], v[46:47]
	v_pk_mul_f32 v[64:65], v[56:57], v[56:57]
	v_pk_mul_f32 v[66:67], v[48:49], v[48:49]
	v_pk_mul_f32 v[70:71], v[62:63], v[62:63]
	v_pk_mov_b32 v[74:75], v[64:65], v[60:61] op_sel:[1,0]
	v_mov_b32_e32 v65, v61
	v_pk_mov_b32 v[60:61], v[70:71], v[66:67] op_sel:[1,0]
	v_mov_b32_e32 v71, v67
	v_pk_add_f32 v[60:61], v[60:61], v[70:71]
	s_waitcnt vmcnt(0)
	v_lshlrev_b32_e32 v76, 16, v54
	v_and_b32_e32 v77, 0xffff0000, v54
	v_lshlrev_b32_e32 v54, 16, v55
	v_and_b32_e32 v55, 0xffff0000, v55
	v_mul_f32_e32 v72, v58, v58
	v_pk_add_f32 v[60:61], v[60:61], v[60:61] op_sel_hi:[0,1]
	v_lshlrev_b32_e32 v68, 16, v52
	v_and_b32_e32 v69, 0xffff0000, v52
	v_lshlrev_b32_e32 v52, 16, v53
	v_and_b32_e32 v53, 0xffff0000, v53
	v_pk_fma_f32 v[66:67], v[58:59], v[58:59], v[72:73] op_sel_hi:[1,1,0]
	v_pk_add_f32 v[64:65], v[74:75], v[64:65]
	v_mul_f32_e32 v60, v50, v50
	v_pk_mul_f32 v[54:55], v[42:43], v[54:55] op_sel_hi:[0,1]
	v_pk_mul_f32 v[72:73], v[42:43], v[76:77] op_sel_hi:[0,1]
	v_pk_add_f32 v[64:65], v[64:65], v[64:65] op_sel_hi:[0,1]
	v_pk_fma_f32 v[70:71], v[50:51], v[50:51], v[60:61] op_sel_hi:[1,1,0]
	v_pk_fma_f32 v[68:69], v[20:21], v[72:73], v[68:69]
	v_pk_fma_f32 v[52:53], v[22:23], v[54:55], v[52:53]
	v_mul_f32_e32 v66, v68, v68
	v_mul_f32_e32 v70, v69, v69
	v_mul_f32_e32 v64, v52, v52
	v_mul_f32_e32 v60, v53, v53
	v_pk_add_f32 v[54:55], v[66:67], v[70:71]
	v_pk_add_f32 v[60:61], v[64:65], v[60:61]
	v_cvt_pk_bf16_f32 v66, v56, v57
	v_lshl_add_u64 v[64:65], v[44:45], 0, s[68:69]
	v_pk_add_f32 v[54:55], v[54:55], v[60:61]
	s_nop 0
	v_add_f32_e32 v42, v54, v55
	s_nop 1
	v_mov_b32_dpp v54, v42 quad_perm:[1,0,3,2] row_mask:0xf bank_mask:0xf
	s_waitcnt lgkmcnt(0)
	v_add_f32_e32 v42, v42, v54
	s_nop 1
	v_mov_b32_dpp v54, v42 quad_perm:[2,3,0,1] row_mask:0xf bank_mask:0xf
	s_waitcnt lgkmcnt(0)
	v_add_f32_e32 v42, v42, v54
	s_nop 1
	v_mov_b32_dpp v60, v42 row_half_mirror row_mask:0xf bank_mask:0xf
	v_lshl_add_u64 v[54:55], v[44:45], 0, s[62:63]
	s_waitcnt lgkmcnt(0)
	v_add_f32_e32 v42, v42, v60
	s_nop 1
	v_mov_b32_dpp v67, v42 row_mirror row_mask:0xf bank_mask:0xf
	v_lshl_add_u64 v[60:61], v[44:45], 0, s[64:65]
	v_lshl_add_u64 v[44:45], v[44:45], 0, s[70:71]
	s_waitcnt lgkmcnt(0)
	v_add_f32_e32 v42, v42, v67
	v_mov_b32_e32 v70, v42
	s_nop 1
	v_permlane16_swap_b32 v42, v70
	v_cvt_pk_bf16_f32 v67, v46, v47
	s_waitcnt lgkmcnt(0)
	v_add_f32_e32 v42, v42, v70
	v_mov_b32_e32 v208, v66
	v_mov_b32_e32 v209, v67
	s_nop 1
	v_mov_b32_e32 v66, v42
	s_nop 1
	v_permlane32_swap_b32 v42, v66
	v_cvt_pk_bf16_f32 v54, v62, v63
	v_cvt_pk_bf16_f32 v55, v48, v49
	s_waitcnt lgkmcnt(0)
	v_add_f32_e32 v42, v42, v66
	v_mov_b32_e32 v210, v54
	v_mov_b32_e32 v211, v55
	s_nop 1
	v_cvt_pk_bf16_f32 v54, v58, v59
	v_fmamk_f32 v42, v42, 0x3a800000, v146
	v_cvt_pk_bf16_f32 v55, v50, v51
	v_cmp_gt_f32_e32 vcc, s97, v42
	v_mov_b32_e32 v212, v54
	v_mov_b32_e32 v213, v55
	s_nop 1
	v_mul_f32_e32 v54, 0x4b800000, v42
	s_nop 0
	v_cndmask_b32_e32 v42, v42, v54, vcc
	v_rsq_f32_e32 v42, v42
	v_cvt_pk_bf16_f32 v54, v68, v69
	v_cvt_pk_bf16_f32 v55, v52, v53
	s_nop 0
	v_and_b32_e32 v232, 1, v152
	v_cmp_eq_u32_e64 s[98:99], 1, v232
	v_mul_u32_u24_e32 v230, 0x1f8, v232
	v_mov_b32_e32 v231, 0
	v_lshl_add_u64 v[228:229], v[44:45], 0, v[230:231]
	v_cndmask_b32_e64 v216, v210, v208, s[98:99]
	v_cndmask_b32_e64 v217, v211, v209, s[98:99]
	s_nop 1
	v_mov_b32_dpp v218, v216 quad_perm:[1,0,3,2] row_mask:0xf bank_mask:0xf
	v_mov_b32_dpp v219, v217 quad_perm:[1,0,3,2] row_mask:0xf bank_mask:0xf
	v_cndmask_b32_e64 v220, v208, v218, s[98:99]
	v_cndmask_b32_e64 v221, v209, v219, s[98:99]
	v_cndmask_b32_e64 v222, v218, v210, s[98:99]
	v_cndmask_b32_e64 v223, v219, v211, s[98:99]
	global_store_dwordx4 v[228:229], v[220:223], off offset:-1536 sc0 sc1
	s_nop 1
	v_cndmask_b32_e64 v216, v54, v212, s[98:99]
	v_cndmask_b32_e64 v217, v55, v213, s[98:99]
	s_nop 1
	v_mov_b32_dpp v218, v216 quad_perm:[1,0,3,2] row_mask:0xf bank_mask:0xf
	v_mov_b32_dpp v219, v217 quad_perm:[1,0,3,2] row_mask:0xf bank_mask:0xf
	v_cndmask_b32_e64 v224, v212, v218, s[98:99]
	v_cndmask_b32_e64 v225, v213, v219, s[98:99]
	v_cndmask_b32_e64 v226, v218, v54, s[98:99]
	v_cndmask_b32_e64 v227, v219, v55, s[98:99]
	global_store_dwordx4 v[228:229], v[224:227], off offset:-512 sc0 sc1
	s_nop 1
	s_mov_b32 s99, 0
	s_nop 1
	v_mul_f32_e32 v44, 0x45800000, v42
	v_cndmask_b32_e32 v42, v42, v44, vcc
	v_pk_mul_f32 v[54:55], v[56:57], v[42:43] op_sel_hi:[1,0]
	v_pk_mul_f32 v[46:47], v[46:47], v[42:43] op_sel_hi:[1,0]
	v_pk_mul_f32 v[54:55], v[24:25], v[54:55]
	v_pk_mul_f32 v[46:47], v[26:27], v[46:47]
	v_cvt_pk_bf16_f32 v54, v54, v55
	v_pk_mul_f32 v[48:49], v[48:49], v[42:43] op_sel_hi:[1,0]
	v_cvt_pk_bf16_f32 v55, v46, v47
	v_pk_mul_f32 v[46:47], v[62:63], v[42:43] op_sel_hi:[1,0]
	v_lshl_add_u64 v[44:45], v[36:37], 0, s[6:7]
	v_pk_mul_f32 v[46:47], v[8:9], v[46:47]
	v_mov_b32_e32 v208, v54
	v_mov_b32_e32 v209, v55
	s_nop 1
	v_pk_mul_f32 v[48:49], v[10:11], v[48:49]
	v_cvt_pk_bf16_f32 v46, v46, v47
	s_and_b64 vcc, exec, s[0:1]
	v_cvt_pk_bf16_f32 v47, v48, v49
	v_lshl_add_u64 v[48:49], v[44:45], 0, s[72:73]
	v_mov_b32_e32 v210, v46
	v_mov_b32_e32 v211, v47
	s_nop 1
	v_pk_mul_f32 v[46:47], v[58:59], v[42:43] op_sel_hi:[1,0]
	v_pk_mul_f32 v[48:49], v[50:51], v[42:43] op_sel_hi:[1,0]
	v_pk_mul_f32 v[46:47], v[12:13], v[46:47]
	v_pk_mul_f32 v[48:49], v[14:15], v[48:49]
	v_cvt_pk_bf16_f32 v46, v46, v47
	s_nop 0
	v_cvt_pk_bf16_f32 v47, v48, v49
	v_lshl_add_u64 v[48:49], v[44:45], 0, s[74:75]
	v_mov_b32_e32 v212, v46
	v_mov_b32_e32 v213, v47
	s_nop 1
	v_pk_mul_f32 v[46:47], v[68:69], v[42:43] op_sel_hi:[1,0]
	v_pk_mul_f32 v[48:49], v[52:53], v[42:43] op_sel_hi:[1,0]
	v_pk_mul_f32 v[46:47], v[28:29], v[46:47]
	v_pk_mul_f32 v[48:49], v[30:31], v[48:49]
	v_cvt_pk_bf16_f32 v46, v46, v47
	v_lshl_add_u64 v[44:45], v[44:45], 0, s[78:79]
	v_cvt_pk_bf16_f32 v47, v48, v49
	s_nop 0
	v_and_b32_e32 v232, 1, v152
	v_cmp_eq_u32_e64 s[98:99], 1, v232
	v_mul_u32_u24_e32 v230, 0x1f8, v232
	v_mov_b32_e32 v231, 0
	v_lshl_add_u64 v[228:229], v[44:45], 0, v[230:231]
	v_cndmask_b32_e64 v216, v210, v208, s[98:99]
	v_cndmask_b32_e64 v217, v211, v209, s[98:99]
	s_nop 1
	v_mov_b32_dpp v218, v216 quad_perm:[1,0,3,2] row_mask:0xf bank_mask:0xf
	v_mov_b32_dpp v219, v217 quad_perm:[1,0,3,2] row_mask:0xf bank_mask:0xf
	v_cndmask_b32_e64 v220, v208, v218, s[98:99]
	v_cndmask_b32_e64 v221, v209, v219, s[98:99]
	v_cndmask_b32_e64 v222, v218, v210, s[98:99]
	v_cndmask_b32_e64 v223, v219, v211, s[98:99]
	global_store_dwordx4 v[228:229], v[220:223], off offset:-1536 sc0 sc1
	s_nop 1
	v_cndmask_b32_e64 v216, v46, v212, s[98:99]
	v_cndmask_b32_e64 v217, v47, v213, s[98:99]
	s_nop 1
	v_mov_b32_dpp v218, v216 quad_perm:[1,0,3,2] row_mask:0xf bank_mask:0xf
	v_mov_b32_dpp v219, v217 quad_perm:[1,0,3,2] row_mask:0xf bank_mask:0xf
	v_cndmask_b32_e64 v224, v212, v218, s[98:99]
	v_cndmask_b32_e64 v225, v213, v219, s[98:99]
	v_cndmask_b32_e64 v226, v218, v46, s[98:99]
	v_cndmask_b32_e64 v227, v219, v47, s[98:99]
	global_store_dwordx4 v[228:229], v[224:227], off offset:-512 sc0 sc1
	s_nop 1
	s_mov_b32 s99, 0
	s_nop 1
	s_cbranch_vccnz .LBB0_1432
	s_add_i32 s56, s80, 0xffffbf82
	s_mov_b64 s[8:9], 0
	s_mov_b64 s[6:7], s[56:57]

.LBB0_1439:
	s_or_b64 exec, exec, s[10:11]
	s_lshl_b64 s[6:7], s[6:7], 12
	s_add_u32 s6, s8, s6
	s_addc_u32 s7, s9, s7
	v_lshl_add_u64 v[44:45], v[32:33], 3, s[6:7]
	s_lshl_b64 s[6:7], s[56:57], 11
	v_lshl_add_u64 v[54:55], v[38:39], 0, s[6:7]
	global_load_dwordx2 v[46:47], v[44:45], off offset:2048
	global_load_dwordx2 v[48:49], v[44:45], off offset:2560
	global_load_dwordx2 v[50:51], v[44:45], off offset:3072
	global_load_dwordx2 v[52:53], v[44:45], off offset:3584
	global_load_dwordx2 v[56:57], v[54:55], off
	global_load_dwordx2 v[58:59], v[54:55], off offset:512
	global_load_dwordx2 v[60:61], v[54:55], off offset:1024
	s_nop 0
	global_load_dwordx2 v[54:55], v[54:55], off offset:1536
	s_waitcnt vmcnt(8)
	s_nop 1
	v_mov_b32_dpp v62, v42 quad_perm:[1,0,3,2] row_mask:0xf bank_mask:0xf
	s_waitcnt lgkmcnt(0)
	v_add_f32_e32 v42, v42, v62
	s_nop 1
	v_mov_b32_dpp v62, v42 quad_perm:[2,3,0,1] row_mask:0xf bank_mask:0xf
	s_waitcnt lgkmcnt(0)
	v_add_f32_e32 v42, v42, v62
	s_nop 1
	v_mov_b32_dpp v62, v42 row_half_mirror row_mask:0xf bank_mask:0xf
	s_waitcnt lgkmcnt(0)
	v_add_f32_e32 v42, v42, v62
	s_nop 1
	v_mov_b32_dpp v62, v42 row_mirror row_mask:0xf bank_mask:0xf
	s_waitcnt lgkmcnt(0)
	v_add_f32_e32 v42, v42, v62
	v_mov_b32_e32 v62, v42
	s_nop 1
	v_permlane16_swap_b32 v42, v62
	s_waitcnt lgkmcnt(0)
	v_add_f32_e32 v42, v42, v62
	v_mov_b32_e32 v62, v42
	s_nop 1
	v_permlane32_swap_b32 v42, v62
	s_waitcnt lgkmcnt(0)
	v_add_f32_e32 v42, v42, v62
	v_fmamk_f32 v42, v42, 0x3a800000, v146
	v_mul_f32_e32 v62, 0x4b800000, v42
	v_cmp_gt_f32_e32 vcc, s97, v42
	s_waitcnt vmcnt(7)
	v_and_b32_e32 v63, 0xffff0000, v46
	v_cndmask_b32_e32 v42, v42, v62, vcc
	v_rsq_f32_e32 v42, v42
	s_waitcnt vmcnt(3)
	v_lshlrev_b32_e32 v70, 16, v56
	v_and_b32_e32 v71, 0xffff0000, v56
	v_lshlrev_b32_e32 v56, 16, v57
	v_mul_f32_e32 v62, 0x45800000, v42
	v_cndmask_b32_e32 v42, v42, v62, vcc
	v_and_b32_e32 v57, 0xffff0000, v57
	s_waitcnt vmcnt(2)
	v_lshlrev_b32_e32 v72, 16, v58
	v_and_b32_e32 v73, 0xffff0000, v58
	v_lshlrev_b32_e32 v58, 16, v59
	v_and_b32_e32 v59, 0xffff0000, v59
	v_lshlrev_b32_e32 v62, 16, v46
	v_lshlrev_b32_e32 v46, 16, v47
	v_and_b32_e32 v47, 0xffff0000, v47
	v_lshlrev_b32_e32 v64, 16, v48
	v_and_b32_e32 v65, 0xffff0000, v48
	v_lshlrev_b32_e32 v48, 16, v49
	v_and_b32_e32 v49, 0xffff0000, v49
	s_waitcnt vmcnt(1)
	v_lshlrev_b32_e32 v74, 16, v60
	v_and_b32_e32 v75, 0xffff0000, v60
	v_lshlrev_b32_e32 v60, 16, v61
	v_and_b32_e32 v61, 0xffff0000, v61
	v_pk_mul_f32 v[70:71], v[42:43], v[70:71] op_sel_hi:[0,1]
	v_pk_mul_f32 v[56:57], v[42:43], v[56:57] op_sel_hi:[0,1]
	v_pk_mul_f32 v[58:59], v[42:43], v[58:59] op_sel_hi:[0,1]
	v_pk_mul_f32 v[72:73], v[42:43], v[72:73] op_sel_hi:[0,1]
	v_lshlrev_b32_e32 v66, 16, v50
	v_and_b32_e32 v67, 0xffff0000, v50
	v_lshlrev_b32_e32 v50, 16, v51
	v_and_b32_e32 v51, 0xffff0000, v51
	v_pk_mul_f32 v[60:61], v[42:43], v[60:61] op_sel_hi:[0,1]
	v_pk_mul_f32 v[74:75], v[42:43], v[74:75] op_sel_hi:[0,1]
	v_pk_fma_f32 v[46:47], v[2:3], v[56:57], v[46:47]
	v_pk_fma_f32 v[56:57], v[0:1], v[70:71], v[62:63]
	v_pk_fma_f32 v[62:63], v[4:5], v[72:73], v[64:65]
	v_pk_fma_f32 v[48:49], v[6:7], v[58:59], v[48:49]
	v_pk_fma_f32 v[58:59], v[16:17], v[74:75], v[66:67]
	v_pk_fma_f32 v[50:51], v[18:19], v[60:61], v[50:51]
	v_pk_mul_f32 v[60:61], v[46:47], v[46:47]
	v_pk_mul_f32 v[64:65], v[56:57], v[56:57]
	v_pk_mul_f32 v[66:67], v[48:49], v[48:49]
	v_pk_mul_f32 v[70:71], v[62:63], v[62:63]
	v_pk_mov_b32 v[74:75], v[64:65], v[60:61] op_sel:[1,0]
	v_mov_b32_e32 v65, v61
	v_pk_mov_b32 v[60:61], v[70:71], v[66:67] op_sel:[1,0]
	v_mov_b32_e32 v71, v67
	v_pk_add_f32 v[60:61], v[60:61], v[70:71]
	s_waitcnt vmcnt(0)
	v_lshlrev_b32_e32 v76, 16, v54
	v_and_b32_e32 v77, 0xffff0000, v54
	v_lshlrev_b32_e32 v54, 16, v55
	v_and_b32_e32 v55, 0xffff0000, v55
	v_mul_f32_e32 v72, v58, v58
	v_pk_add_f32 v[60:61], v[60:61], v[60:61] op_sel_hi:[0,1]
	v_lshlrev_b32_e32 v68, 16, v52
	v_and_b32_e32 v69, 0xffff0000, v52
	v_lshlrev_b32_e32 v52, 16, v53
	v_and_b32_e32 v53, 0xffff0000, v53
	v_pk_fma_f32 v[66:67], v[58:59], v[58:59], v[72:73] op_sel_hi:[1,1,0]
	v_pk_add_f32 v[64:65], v[74:75], v[64:65]
	v_mul_f32_e32 v60, v50, v50
	v_pk_mul_f32 v[54:55], v[42:43], v[54:55] op_sel_hi:[0,1]
	v_pk_mul_f32 v[72:73], v[42:43], v[76:77] op_sel_hi:[0,1]
	v_pk_add_f32 v[64:65], v[64:65], v[64:65] op_sel_hi:[0,1]
	v_pk_fma_f32 v[70:71], v[50:51], v[50:51], v[60:61] op_sel_hi:[1,1,0]
	v_pk_fma_f32 v[68:69], v[20:21], v[72:73], v[68:69]
	v_pk_fma_f32 v[52:53], v[22:23], v[54:55], v[52:53]
	v_mul_f32_e32 v66, v68, v68
	v_mul_f32_e32 v70, v69, v69
	v_mul_f32_e32 v64, v52, v52
	v_mul_f32_e32 v60, v53, v53
	v_pk_add_f32 v[54:55], v[66:67], v[70:71]
	v_pk_add_f32 v[60:61], v[64:65], v[60:61]
	v_cvt_pk_bf16_f32 v66, v56, v57
	v_lshl_add_u64 v[64:65], v[44:45], 0, s[68:69]
	v_pk_add_f32 v[54:55], v[54:55], v[60:61]
	s_nop 0
	v_add_f32_e32 v42, v54, v55
	s_nop 1
	v_mov_b32_dpp v54, v42 quad_perm:[1,0,3,2] row_mask:0xf bank_mask:0xf
	s_waitcnt lgkmcnt(0)
	v_add_f32_e32 v42, v42, v54
	s_nop 1
	v_mov_b32_dpp v54, v42 quad_perm:[2,3,0,1] row_mask:0xf bank_mask:0xf
	s_waitcnt lgkmcnt(0)
	v_add_f32_e32 v42, v42, v54
	s_nop 1
	v_mov_b32_dpp v60, v42 row_half_mirror row_mask:0xf bank_mask:0xf
	v_lshl_add_u64 v[54:55], v[44:45], 0, s[62:63]
	s_waitcnt lgkmcnt(0)
	v_add_f32_e32 v42, v42, v60
	s_nop 1
	v_mov_b32_dpp v67, v42 row_mirror row_mask:0xf bank_mask:0xf
	v_lshl_add_u64 v[60:61], v[44:45], 0, s[64:65]
	v_lshl_add_u64 v[44:45], v[44:45], 0, s[70:71]
	s_waitcnt lgkmcnt(0)
	v_add_f32_e32 v42, v42, v67
	v_mov_b32_e32 v70, v42
	s_nop 1
	v_permlane16_swap_b32 v42, v70
	v_cvt_pk_bf16_f32 v67, v46, v47
	s_waitcnt lgkmcnt(0)
	v_add_f32_e32 v42, v42, v70
	v_mov_b32_e32 v208, v66
	v_mov_b32_e32 v209, v67
	s_nop 1
	v_mov_b32_e32 v66, v42
	s_nop 1
	v_permlane32_swap_b32 v42, v66
	v_cvt_pk_bf16_f32 v54, v62, v63
	v_cvt_pk_bf16_f32 v55, v48, v49
	s_waitcnt lgkmcnt(0)
	v_add_f32_e32 v42, v42, v66
	v_mov_b32_e32 v210, v54
	v_mov_b32_e32 v211, v55
	s_nop 1
	v_cvt_pk_bf16_f32 v54, v58, v59
	v_fmamk_f32 v42, v42, 0x3a800000, v146
	v_cvt_pk_bf16_f32 v55, v50, v51
	v_cmp_gt_f32_e32 vcc, s97, v42
	v_mov_b32_e32 v212, v54
	v_mov_b32_e32 v213, v55
	s_nop 1
	v_mul_f32_e32 v54, 0x4b800000, v42
	s_nop 0
	v_cndmask_b32_e32 v42, v42, v54, vcc
	v_rsq_f32_e32 v42, v42
	v_cvt_pk_bf16_f32 v54, v68, v69
	v_cvt_pk_bf16_f32 v55, v52, v53
	s_nop 0
	v_and_b32_e32 v232, 1, v152
	v_cmp_eq_u32_e64 s[98:99], 1, v232
	v_mul_u32_u24_e32 v230, 0x1f8, v232
	v_mov_b32_e32 v231, 0
	v_lshl_add_u64 v[228:229], v[44:45], 0, v[230:231]
	v_cndmask_b32_e64 v216, v210, v208, s[98:99]
	v_cndmask_b32_e64 v217, v211, v209, s[98:99]
	s_nop 1
	v_mov_b32_dpp v218, v216 quad_perm:[1,0,3,2] row_mask:0xf bank_mask:0xf
	v_mov_b32_dpp v219, v217 quad_perm:[1,0,3,2] row_mask:0xf bank_mask:0xf
	v_cndmask_b32_e64 v220, v208, v218, s[98:99]
	v_cndmask_b32_e64 v221, v209, v219, s[98:99]
	v_cndmask_b32_e64 v222, v218, v210, s[98:99]
	v_cndmask_b32_e64 v223, v219, v211, s[98:99]
	global_store_dwordx4 v[228:229], v[220:223], off offset:-1536 sc0 sc1
	s_nop 1
	v_cndmask_b32_e64 v216, v54, v212, s[98:99]
	v_cndmask_b32_e64 v217, v55, v213, s[98:99]
	s_nop 1
	v_mov_b32_dpp v218, v216 quad_perm:[1,0,3,2] row_mask:0xf bank_mask:0xf
	v_mov_b32_dpp v219, v217 quad_perm:[1,0,3,2] row_mask:0xf bank_mask:0xf
	v_cndmask_b32_e64 v224, v212, v218, s[98:99]
	v_cndmask_b32_e64 v225, v213, v219, s[98:99]
	v_cndmask_b32_e64 v226, v218, v54, s[98:99]
	v_cndmask_b32_e64 v227, v219, v55, s[98:99]
	global_store_dwordx4 v[228:229], v[224:227], off offset:-512 sc0 sc1
	s_nop 1
	s_mov_b32 s99, 0
	s_nop 1
	v_mul_f32_e32 v44, 0x45800000, v42
	v_cndmask_b32_e32 v42, v42, v44, vcc
	v_pk_mul_f32 v[54:55], v[56:57], v[42:43] op_sel_hi:[1,0]
	v_pk_mul_f32 v[46:47], v[46:47], v[42:43] op_sel_hi:[1,0]
	v_pk_mul_f32 v[54:55], v[24:25], v[54:55]
	v_pk_mul_f32 v[46:47], v[26:27], v[46:47]
	v_cvt_pk_bf16_f32 v54, v54, v55
	v_pk_mul_f32 v[48:49], v[48:49], v[42:43] op_sel_hi:[1,0]
	v_cvt_pk_bf16_f32 v55, v46, v47
	v_pk_mul_f32 v[46:47], v[62:63], v[42:43] op_sel_hi:[1,0]
	v_lshl_add_u64 v[44:45], v[36:37], 0, s[6:7]
	v_pk_mul_f32 v[46:47], v[8:9], v[46:47]
	v_mov_b32_e32 v208, v54
	v_mov_b32_e32 v209, v55
	s_nop 1
	v_pk_mul_f32 v[48:49], v[10:11], v[48:49]
	v_cvt_pk_bf16_f32 v46, v46, v47
	s_and_b64 vcc, exec, s[0:1]
	v_cvt_pk_bf16_f32 v47, v48, v49
	v_lshl_add_u64 v[48:49], v[44:45], 0, s[72:73]
	v_mov_b32_e32 v210, v46
	v_mov_b32_e32 v211, v47
	s_nop 1
	v_pk_mul_f32 v[46:47], v[58:59], v[42:43] op_sel_hi:[1,0]
	v_pk_mul_f32 v[48:49], v[50:51], v[42:43] op_sel_hi:[1,0]
	v_pk_mul_f32 v[46:47], v[12:13], v[46:47]
	v_pk_mul_f32 v[48:49], v[14:15], v[48:49]
	v_cvt_pk_bf16_f32 v46, v46, v47
	s_mov_b64 s[6:7], -1
	v_cvt_pk_bf16_f32 v47, v48, v49
	v_lshl_add_u64 v[48:49], v[44:45], 0, s[74:75]
	v_mov_b32_e32 v212, v46
	v_mov_b32_e32 v213, v47
	s_nop 1
	v_pk_mul_f32 v[46:47], v[68:69], v[42:43] op_sel_hi:[1,0]
	v_pk_mul_f32 v[48:49], v[52:53], v[42:43] op_sel_hi:[1,0]
	v_pk_mul_f32 v[46:47], v[28:29], v[46:47]
	v_pk_mul_f32 v[48:49], v[30:31], v[48:49]
	v_cvt_pk_bf16_f32 v46, v46, v47
	v_lshl_add_u64 v[44:45], v[44:45], 0, s[78:79]
	v_cvt_pk_bf16_f32 v47, v48, v49
	s_nop 0
	v_and_b32_e32 v232, 1, v152
	v_cmp_eq_u32_e64 s[98:99], 1, v232
	v_mul_u32_u24_e32 v230, 0x1f8, v232
	v_mov_b32_e32 v231, 0
	v_lshl_add_u64 v[228:229], v[44:45], 0, v[230:231]
	v_cndmask_b32_e64 v216, v210, v208, s[98:99]
	v_cndmask_b32_e64 v217, v211, v209, s[98:99]
	s_nop 1
	v_mov_b32_dpp v218, v216 quad_perm:[1,0,3,2] row_mask:0xf bank_mask:0xf
	v_mov_b32_dpp v219, v217 quad_perm:[1,0,3,2] row_mask:0xf bank_mask:0xf
	v_cndmask_b32_e64 v220, v208, v218, s[98:99]
	v_cndmask_b32_e64 v221, v209, v219, s[98:99]
	v_cndmask_b32_e64 v222, v218, v210, s[98:99]
	v_cndmask_b32_e64 v223, v219, v211, s[98:99]
	global_store_dwordx4 v[228:229], v[220:223], off offset:-1536 sc0 sc1
	s_nop 1
	v_cndmask_b32_e64 v216, v46, v212, s[98:99]
	v_cndmask_b32_e64 v217, v47, v213, s[98:99]
	s_nop 1
	v_mov_b32_dpp v218, v216 quad_perm:[1,0,3,2] row_mask:0xf bank_mask:0xf
	v_mov_b32_dpp v219, v217 quad_perm:[1,0,3,2] row_mask:0xf bank_mask:0xf
	v_cndmask_b32_e64 v224, v212, v218, s[98:99]
	v_cndmask_b32_e64 v225, v213, v219, s[98:99]
	v_cndmask_b32_e64 v226, v218, v46, s[98:99]
	v_cndmask_b32_e64 v227, v219, v47, s[98:99]
	global_store_dwordx4 v[228:229], v[224:227], off offset:-512 sc0 sc1
	s_nop 1
	s_mov_b32 s99, 0
	s_nop 1
	s_cbranch_vccnz .LBB0_1441
	s_add_i32 s56, s80, 0xffffbf83
	s_mov_b64 s[6:7], 0
	s_mov_b64 s[0:1], s[56:57]

.LBB0_1964:
	s_or_b64 exec, exec, s[10:11]
	s_lshl_b64 s[0:1], s[0:1], 12
	s_add_u32 s0, s6, s0
	s_addc_u32 s1, s7, s1
	v_lshl_add_u64 v[44:45], v[32:33], 3, s[0:1]
	s_lshl_b64 s[0:1], s[14:15], 11
	v_lshl_add_u64 v[54:55], v[38:39], 0, s[0:1]
	global_load_dwordx2 v[46:47], v[44:45], off offset:2048
	global_load_dwordx2 v[48:49], v[44:45], off offset:2560
	global_load_dwordx2 v[50:51], v[44:45], off offset:3072
	global_load_dwordx2 v[52:53], v[44:45], off offset:3584
	global_load_dwordx2 v[56:57], v[54:55], off
	global_load_dwordx2 v[58:59], v[54:55], off offset:512
	global_load_dwordx2 v[60:61], v[54:55], off offset:1024
	s_nop 0
	global_load_dwordx2 v[54:55], v[54:55], off offset:1536
	s_waitcnt vmcnt(8)
	s_nop 1
	v_mov_b32_dpp v62, v42 quad_perm:[1,0,3,2] row_mask:0xf bank_mask:0xf
	s_waitcnt lgkmcnt(0)
	v_add_f32_e32 v42, v42, v62
	s_nop 1
	v_mov_b32_dpp v62, v42 quad_perm:[2,3,0,1] row_mask:0xf bank_mask:0xf
	s_waitcnt lgkmcnt(0)
	v_add_f32_e32 v42, v42, v62
	s_nop 1
	v_mov_b32_dpp v62, v42 row_half_mirror row_mask:0xf bank_mask:0xf
	s_waitcnt lgkmcnt(0)
	v_add_f32_e32 v42, v42, v62
	s_nop 1
	v_mov_b32_dpp v62, v42 row_mirror row_mask:0xf bank_mask:0xf
	s_waitcnt lgkmcnt(0)
	v_add_f32_e32 v42, v42, v62
	v_mov_b32_e32 v62, v42
	s_nop 1
	v_permlane16_swap_b32 v42, v62
	s_waitcnt lgkmcnt(0)
	v_add_f32_e32 v42, v42, v62
	v_mov_b32_e32 v62, v42
	s_nop 1
	v_permlane32_swap_b32 v42, v62
	s_waitcnt lgkmcnt(0)
	v_add_f32_e32 v42, v42, v62
	v_fmamk_f32 v42, v42, 0x3a800000, v90
	v_mul_f32_e32 v62, 0x4b800000, v42
	v_cmp_gt_f32_e32 vcc, s91, v42
	s_waitcnt vmcnt(7)
	v_and_b32_e32 v63, 0xffff0000, v46
	v_cndmask_b32_e32 v42, v42, v62, vcc
	v_rsq_f32_e32 v42, v42
	s_waitcnt vmcnt(3)
	v_lshlrev_b32_e32 v70, 16, v56
	v_and_b32_e32 v71, 0xffff0000, v56
	v_lshlrev_b32_e32 v56, 16, v57
	v_mul_f32_e32 v62, 0x45800000, v42
	v_cndmask_b32_e32 v42, v42, v62, vcc
	v_and_b32_e32 v57, 0xffff0000, v57
	s_waitcnt vmcnt(2)
	v_lshlrev_b32_e32 v72, 16, v58
	v_and_b32_e32 v73, 0xffff0000, v58
	v_lshlrev_b32_e32 v58, 16, v59
	v_and_b32_e32 v59, 0xffff0000, v59
	v_lshlrev_b32_e32 v62, 16, v46
	v_lshlrev_b32_e32 v46, 16, v47
	v_and_b32_e32 v47, 0xffff0000, v47
	v_lshlrev_b32_e32 v64, 16, v48
	v_and_b32_e32 v65, 0xffff0000, v48
	v_lshlrev_b32_e32 v48, 16, v49
	v_and_b32_e32 v49, 0xffff0000, v49
	s_waitcnt vmcnt(1)
	v_lshlrev_b32_e32 v74, 16, v60
	v_and_b32_e32 v75, 0xffff0000, v60
	v_lshlrev_b32_e32 v60, 16, v61
	v_and_b32_e32 v61, 0xffff0000, v61
	v_pk_mul_f32 v[70:71], v[42:43], v[70:71] op_sel_hi:[0,1]
	v_pk_mul_f32 v[56:57], v[42:43], v[56:57] op_sel_hi:[0,1]
	v_pk_mul_f32 v[58:59], v[42:43], v[58:59] op_sel_hi:[0,1]
	v_pk_mul_f32 v[72:73], v[42:43], v[72:73] op_sel_hi:[0,1]
	v_lshlrev_b32_e32 v66, 16, v50
	v_and_b32_e32 v67, 0xffff0000, v50
	v_lshlrev_b32_e32 v50, 16, v51
	v_and_b32_e32 v51, 0xffff0000, v51
	v_pk_mul_f32 v[60:61], v[42:43], v[60:61] op_sel_hi:[0,1]
	v_pk_mul_f32 v[74:75], v[42:43], v[74:75] op_sel_hi:[0,1]
	v_pk_fma_f32 v[46:47], v[2:3], v[56:57], v[46:47]
	v_pk_fma_f32 v[56:57], v[0:1], v[70:71], v[62:63]
	v_pk_fma_f32 v[62:63], v[8:9], v[72:73], v[64:65]
	v_pk_fma_f32 v[48:49], v[10:11], v[58:59], v[48:49]
	v_pk_fma_f32 v[58:59], v[12:13], v[74:75], v[66:67]
	v_pk_fma_f32 v[50:51], v[14:15], v[60:61], v[50:51]
	v_pk_mul_f32 v[60:61], v[46:47], v[46:47]
	v_pk_mul_f32 v[64:65], v[56:57], v[56:57]
	v_pk_mul_f32 v[66:67], v[48:49], v[48:49]
	v_pk_mul_f32 v[70:71], v[62:63], v[62:63]
	v_pk_mov_b32 v[74:75], v[64:65], v[60:61] op_sel:[1,0]
	v_mov_b32_e32 v65, v61
	v_pk_mov_b32 v[60:61], v[70:71], v[66:67] op_sel:[1,0]
	v_mov_b32_e32 v71, v67
	v_pk_add_f32 v[60:61], v[60:61], v[70:71]
	s_waitcnt vmcnt(0)
	v_lshlrev_b32_e32 v76, 16, v54
	v_and_b32_e32 v77, 0xffff0000, v54
	v_lshlrev_b32_e32 v54, 16, v55
	v_and_b32_e32 v55, 0xffff0000, v55
	v_mul_f32_e32 v72, v58, v58
	v_pk_add_f32 v[60:61], v[60:61], v[60:61] op_sel_hi:[0,1]
	v_lshlrev_b32_e32 v68, 16, v52
	v_and_b32_e32 v69, 0xffff0000, v52
	v_lshlrev_b32_e32 v52, 16, v53
	v_and_b32_e32 v53, 0xffff0000, v53
	v_pk_fma_f32 v[66:67], v[58:59], v[58:59], v[72:73] op_sel_hi:[1,1,0]
	v_pk_add_f32 v[64:65], v[74:75], v[64:65]
	v_mul_f32_e32 v60, v50, v50
	v_pk_mul_f32 v[54:55], v[42:43], v[54:55] op_sel_hi:[0,1]
	v_pk_mul_f32 v[72:73], v[42:43], v[76:77] op_sel_hi:[0,1]
	v_pk_add_f32 v[64:65], v[64:65], v[64:65] op_sel_hi:[0,1]
	v_pk_fma_f32 v[70:71], v[50:51], v[50:51], v[60:61] op_sel_hi:[1,1,0]
	v_pk_fma_f32 v[68:69], v[24:25], v[72:73], v[68:69]
	v_pk_fma_f32 v[52:53], v[26:27], v[54:55], v[52:53]
	v_mul_f32_e32 v66, v68, v68
	v_mul_f32_e32 v70, v69, v69
	v_mul_f32_e32 v64, v52, v52
	v_mul_f32_e32 v60, v53, v53
	v_pk_add_f32 v[54:55], v[66:67], v[70:71]
	v_pk_add_f32 v[60:61], v[64:65], v[60:61]
	v_cvt_pk_bf16_f32 v66, v56, v57
	v_lshl_add_u64 v[64:65], v[44:45], 0, s[54:55]
	v_pk_add_f32 v[54:55], v[54:55], v[60:61]
	s_nop 0
	v_add_f32_e32 v42, v54, v55
	s_nop 1
	v_mov_b32_dpp v54, v42 quad_perm:[1,0,3,2] row_mask:0xf bank_mask:0xf
	s_waitcnt lgkmcnt(0)
	v_add_f32_e32 v42, v42, v54
	s_nop 1
	v_mov_b32_dpp v54, v42 quad_perm:[2,3,0,1] row_mask:0xf bank_mask:0xf
	s_waitcnt lgkmcnt(0)
	v_add_f32_e32 v42, v42, v54
	s_nop 1
	v_mov_b32_dpp v60, v42 row_half_mirror row_mask:0xf bank_mask:0xf
	v_lshl_add_u64 v[54:55], v[44:45], 0, s[40:41]
	s_waitcnt lgkmcnt(0)
	v_add_f32_e32 v42, v42, v60
	s_nop 1
	v_mov_b32_dpp v67, v42 row_mirror row_mask:0xf bank_mask:0xf
	v_lshl_add_u64 v[60:61], v[44:45], 0, s[52:53]
	v_lshl_add_u64 v[44:45], v[44:45], 0, s[56:57]
	s_waitcnt lgkmcnt(0)
	v_add_f32_e32 v42, v42, v67
	v_mov_b32_e32 v70, v42
	s_nop 1
	v_permlane16_swap_b32 v42, v70
	v_cvt_pk_bf16_f32 v67, v46, v47
	s_waitcnt lgkmcnt(0)
	v_add_f32_e32 v42, v42, v70
	v_mov_b32_e32 v208, v66
	v_mov_b32_e32 v209, v67
	s_nop 1
	v_mov_b32_e32 v66, v42
	s_nop 1
	v_permlane32_swap_b32 v42, v66
	v_cvt_pk_bf16_f32 v54, v62, v63
	v_cvt_pk_bf16_f32 v55, v48, v49
	s_waitcnt lgkmcnt(0)
	v_add_f32_e32 v42, v42, v66
	v_mov_b32_e32 v210, v54
	v_mov_b32_e32 v211, v55
	s_nop 1
	v_cvt_pk_bf16_f32 v54, v58, v59
	v_fmamk_f32 v42, v42, 0x3a800000, v90
	v_cvt_pk_bf16_f32 v55, v50, v51
	v_cmp_gt_f32_e32 vcc, s91, v42
	v_mov_b32_e32 v212, v54
	v_mov_b32_e32 v213, v55
	s_nop 1
	v_mul_f32_e32 v54, 0x4b800000, v42
	s_nop 0
	v_cndmask_b32_e32 v42, v42, v54, vcc
	v_rsq_f32_e32 v42, v42
	v_cvt_pk_bf16_f32 v54, v68, v69
	v_cvt_pk_bf16_f32 v55, v52, v53
	s_nop 0
	v_and_b32_e32 v232, 1, v152
	v_cmp_eq_u32_e64 s[98:99], 1, v232
	v_mul_u32_u24_e32 v230, 0x1f8, v232
	v_mov_b32_e32 v231, 0
	v_lshl_add_u64 v[228:229], v[44:45], 0, v[230:231]
	v_cndmask_b32_e64 v216, v210, v208, s[98:99]
	v_cndmask_b32_e64 v217, v211, v209, s[98:99]
	s_nop 1
	v_mov_b32_dpp v218, v216 quad_perm:[1,0,3,2] row_mask:0xf bank_mask:0xf
	v_mov_b32_dpp v219, v217 quad_perm:[1,0,3,2] row_mask:0xf bank_mask:0xf
	v_cndmask_b32_e64 v220, v208, v218, s[98:99]
	v_cndmask_b32_e64 v221, v209, v219, s[98:99]
	v_cndmask_b32_e64 v222, v218, v210, s[98:99]
	v_cndmask_b32_e64 v223, v219, v211, s[98:99]
	global_store_dwordx4 v[228:229], v[220:223], off offset:-1536 sc0 sc1
	s_nop 1
	v_cndmask_b32_e64 v216, v54, v212, s[98:99]
	v_cndmask_b32_e64 v217, v55, v213, s[98:99]
	s_nop 1
	v_mov_b32_dpp v218, v216 quad_perm:[1,0,3,2] row_mask:0xf bank_mask:0xf
	v_mov_b32_dpp v219, v217 quad_perm:[1,0,3,2] row_mask:0xf bank_mask:0xf
	v_cndmask_b32_e64 v224, v212, v218, s[98:99]
	v_cndmask_b32_e64 v225, v213, v219, s[98:99]
	v_cndmask_b32_e64 v226, v218, v54, s[98:99]
	v_cndmask_b32_e64 v227, v219, v55, s[98:99]
	global_store_dwordx4 v[228:229], v[224:227], off offset:-512 sc0 sc1
	s_nop 1
	s_mov_b32 s99, 0
	s_nop 1
	v_mul_f32_e32 v44, 0x45800000, v42
	v_cndmask_b32_e32 v42, v42, v44, vcc
	v_pk_mul_f32 v[54:55], v[56:57], v[42:43] op_sel_hi:[1,0]
	v_pk_mul_f32 v[46:47], v[46:47], v[42:43] op_sel_hi:[1,0]
	v_pk_mul_f32 v[54:55], v[4:5], v[54:55]
	v_pk_mul_f32 v[46:47], v[6:7], v[46:47]
	v_cvt_pk_bf16_f32 v54, v54, v55
	v_pk_mul_f32 v[48:49], v[48:49], v[42:43] op_sel_hi:[1,0]
	v_cvt_pk_bf16_f32 v55, v46, v47
	v_pk_mul_f32 v[46:47], v[62:63], v[42:43] op_sel_hi:[1,0]
	v_lshl_add_u64 v[44:45], v[36:37], 0, s[0:1]
	v_pk_mul_f32 v[46:47], v[16:17], v[46:47]
	v_mov_b32_e32 v208, v54
	v_mov_b32_e32 v209, v55
	s_nop 1
	v_pk_mul_f32 v[48:49], v[18:19], v[48:49]
	v_cvt_pk_bf16_f32 v46, v46, v47
	s_nop 0
	v_cvt_pk_bf16_f32 v47, v48, v49
	v_lshl_add_u64 v[48:49], v[44:45], 0, s[58:59]
	v_mov_b32_e32 v210, v46
	v_mov_b32_e32 v211, v47
	s_nop 1
	v_pk_mul_f32 v[46:47], v[58:59], v[42:43] op_sel_hi:[1,0]
	v_pk_mul_f32 v[48:49], v[50:51], v[42:43] op_sel_hi:[1,0]
	v_pk_mul_f32 v[46:47], v[20:21], v[46:47]
	v_pk_mul_f32 v[48:49], v[22:23], v[48:49]
	v_cvt_pk_bf16_f32 v46, v46, v47
	s_nop 0
	v_cvt_pk_bf16_f32 v47, v48, v49
	v_lshl_add_u64 v[48:49], v[44:45], 0, s[60:61]
	v_mov_b32_e32 v212, v46
	v_mov_b32_e32 v213, v47
	s_nop 1
	v_pk_mul_f32 v[46:47], v[68:69], v[42:43] op_sel_hi:[1,0]
	v_pk_mul_f32 v[48:49], v[52:53], v[42:43] op_sel_hi:[1,0]
	v_pk_mul_f32 v[46:47], v[28:29], v[46:47]
	v_pk_mul_f32 v[48:49], v[30:31], v[48:49]
	v_cvt_pk_bf16_f32 v46, v46, v47
	v_lshl_add_u64 v[44:45], v[44:45], 0, s[62:63]
	v_cvt_pk_bf16_f32 v47, v48, v49
	s_nop 0
	v_and_b32_e32 v232, 1, v152
	v_cmp_eq_u32_e64 s[98:99], 1, v232
	v_mul_u32_u24_e32 v230, 0x1f8, v232
	v_mov_b32_e32 v231, 0
	v_lshl_add_u64 v[228:229], v[44:45], 0, v[230:231]
	v_cndmask_b32_e64 v216, v210, v208, s[98:99]
	v_cndmask_b32_e64 v217, v211, v209, s[98:99]
	s_nop 1
	v_mov_b32_dpp v218, v216 quad_perm:[1,0,3,2] row_mask:0xf bank_mask:0xf
	v_mov_b32_dpp v219, v217 quad_perm:[1,0,3,2] row_mask:0xf bank_mask:0xf
	v_cndmask_b32_e64 v220, v208, v218, s[98:99]
	v_cndmask_b32_e64 v221, v209, v219, s[98:99]
	v_cndmask_b32_e64 v222, v218, v210, s[98:99]
	v_cndmask_b32_e64 v223, v219, v211, s[98:99]
	global_store_dwordx4 v[228:229], v[220:223], off offset:-1536 sc0 sc1
	s_nop 1
	v_cndmask_b32_e64 v216, v46, v212, s[98:99]
	v_cndmask_b32_e64 v217, v47, v213, s[98:99]
	s_nop 1
	v_mov_b32_dpp v218, v216 quad_perm:[1,0,3,2] row_mask:0xf bank_mask:0xf
	v_mov_b32_dpp v219, v217 quad_perm:[1,0,3,2] row_mask:0xf bank_mask:0xf
	v_cndmask_b32_e64 v224, v212, v218, s[98:99]
	v_cndmask_b32_e64 v225, v213, v219, s[98:99]
	v_cndmask_b32_e64 v226, v218, v46, s[98:99]
	v_cndmask_b32_e64 v227, v219, v47, s[98:99]
	global_store_dwordx4 v[228:229], v[224:227], off offset:-512 sc0 sc1
	s_nop 1
	s_mov_b32 s99, 0
	s_nop 1

.LBB0_2008:
	global_load_dwordx2 v[68:69], v[50:51], off offset:2048
	global_load_dwordx2 v[78:79], v[52:53], off offset:2048
	global_load_dwordx2 v[80:81], v[54:55], off offset:2048
	global_load_dwordx2 v[82:83], v[56:57], off offset:2048
	global_load_dwordx2 v[84:85], v[50:51], off offset:2560
	global_load_dwordx2 v[86:87], v[52:53], off offset:2560
	global_load_dwordx2 v[88:89], v[54:55], off offset:2560
	global_load_dwordx2 v[92:93], v[56:57], off offset:2560
	global_load_dwordx2 v[76:77], v[50:51], off offset:3072
	global_load_dwordx2 v[72:73], v[52:53], off offset:3072
	global_load_dwordx2 v[70:71], v[54:55], off offset:3072
	global_load_dwordx2 v[74:75], v[56:57], off offset:3072
	global_load_dwordx2 v[64:65], v[50:51], off offset:3584
	global_load_dwordx2 v[62:63], v[52:53], off offset:3584
	global_load_dwordx2 v[60:61], v[54:55], off offset:3584
	global_load_dwordx2 v[66:67], v[56:57], off offset:3584
	s_lshl_b64 s[6:7], s[6:7], 12
	s_add_u32 s6, s10, s6
	s_addc_u32 s7, s11, s7
	v_lshl_add_u64 v[50:51], v[32:33], 3, s[6:7]
	global_load_dwordx2 v[58:59], v[50:51], off offset:2048
	global_load_dwordx2 v[56:57], v[50:51], off offset:2560
	global_load_dwordx2 v[54:55], v[50:51], off offset:3072
	global_load_dwordx2 v[52:53], v[50:51], off offset:3584
	s_mov_b64 s[6:7], 0x3800800
	s_add_u32 s66, s66, 0x1000
	s_addc_u32 s67, s67, 0
	s_add_i32 s12, s12, 2
	s_add_u32 s0, s0, 2
	s_addc_u32 s1, s1, 0
	s_add_i32 s3, s3, 2
	s_cmpk_lg_i32 s66, 0x2000
	s_waitcnt vmcnt(19)
	v_lshlrev_b32_e32 v94, 16, v68
	v_and_b32_e32 v95, 0xffff0000, v68
	v_lshlrev_b32_e32 v68, 16, v69
	v_and_b32_e32 v69, 0xffff0000, v69
	s_waitcnt vmcnt(18)
	v_lshlrev_b32_e32 v96, 16, v78
	v_and_b32_e32 v97, 0xffff0000, v78
	v_lshlrev_b32_e32 v78, 16, v79
	v_and_b32_e32 v79, 0xffff0000, v79
	s_waitcnt vmcnt(11)
	v_lshlrev_b32_e32 v110, 16, v76
	v_and_b32_e32 v111, 0xffff0000, v76
	v_lshlrev_b32_e32 v76, 16, v77
	v_and_b32_e32 v77, 0xffff0000, v77
	s_waitcnt vmcnt(10)
	v_lshlrev_b32_e32 v112, 16, v72
	v_and_b32_e32 v113, 0xffff0000, v72
	v_pk_add_f32 v[76:77], v[76:77], 0 op_sel_hi:[1,0]
	v_lshlrev_b32_e32 v72, 16, v73
	v_and_b32_e32 v73, 0xffff0000, v73
	s_waitcnt vmcnt(9)
	v_lshlrev_b32_e32 v114, 16, v70
	v_and_b32_e32 v115, 0xffff0000, v70
	v_pk_add_f32 v[72:73], v[76:77], v[72:73]
	v_lshlrev_b32_e32 v70, 16, v71
	v_and_b32_e32 v71, 0xffff0000, v71
	v_lshlrev_b32_e32 v102, 16, v84
	v_and_b32_e32 v103, 0xffff0000, v84
	v_lshlrev_b32_e32 v84, 16, v85
	v_and_b32_e32 v85, 0xffff0000, v85
	v_pk_add_f32 v[94:95], v[94:95], 0 op_sel_hi:[1,0]
	v_pk_add_f32 v[68:69], v[68:69], 0 op_sel_hi:[1,0]
	v_pk_add_f32 v[70:71], v[72:73], v[70:71]
	s_waitcnt vmcnt(8)
	v_lshlrev_b32_e32 v72, 16, v75
	v_and_b32_e32 v73, 0xffff0000, v75
	v_lshlrev_b32_e32 v98, 16, v80
	v_and_b32_e32 v99, 0xffff0000, v80
	v_lshlrev_b32_e32 v80, 16, v81
	v_and_b32_e32 v81, 0xffff0000, v81
	v_lshlrev_b32_e32 v104, 16, v86
	v_and_b32_e32 v105, 0xffff0000, v86
	v_lshlrev_b32_e32 v86, 16, v87
	v_and_b32_e32 v87, 0xffff0000, v87
	v_pk_add_f32 v[102:103], v[102:103], 0 op_sel_hi:[1,0]
	v_pk_add_f32 v[84:85], v[84:85], 0 op_sel_hi:[1,0]
	v_pk_add_f32 v[110:111], v[110:111], 0 op_sel_hi:[1,0]
	v_pk_add_f32 v[94:95], v[94:95], v[96:97]
	v_pk_add_f32 v[68:69], v[68:69], v[78:79]
	v_pk_add_f32 v[72:73], v[70:71], v[72:73]
	s_waitcnt vmcnt(7)
	v_lshlrev_b32_e32 v70, 16, v64
	v_and_b32_e32 v71, 0xffff0000, v64
	v_lshlrev_b32_e32 v64, 16, v65
	v_and_b32_e32 v65, 0xffff0000, v65
	v_lshlrev_b32_e32 v100, 16, v82
	v_and_b32_e32 v101, 0xffff0000, v82
	v_lshlrev_b32_e32 v82, 16, v83
	v_and_b32_e32 v83, 0xffff0000, v83
	v_lshlrev_b32_e32 v106, 16, v88
	v_and_b32_e32 v107, 0xffff0000, v88
	v_lshlrev_b32_e32 v88, 16, v89
	v_and_b32_e32 v89, 0xffff0000, v89
	v_lshlrev_b32_e32 v116, 16, v74
	v_and_b32_e32 v117, 0xffff0000, v74
	v_pk_add_f32 v[78:79], v[102:103], v[104:105]
	v_pk_add_f32 v[84:85], v[84:85], v[86:87]
	v_pk_add_f32 v[86:87], v[110:111], v[112:113]
	v_pk_add_f32 v[94:95], v[94:95], v[98:99]
	v_pk_add_f32 v[68:69], v[68:69], v[80:81]
	v_pk_add_f32 v[70:71], v[70:71], 0 op_sel_hi:[1,0]
	s_waitcnt vmcnt(6)
	v_lshlrev_b32_e32 v74, 16, v62
	v_and_b32_e32 v75, 0xffff0000, v62
	v_pk_add_f32 v[64:65], v[64:65], 0 op_sel_hi:[1,0]
	v_lshlrev_b32_e32 v62, 16, v63
	v_and_b32_e32 v63, 0xffff0000, v63
	v_lshlrev_b32_e32 v108, 16, v92
	v_and_b32_e32 v109, 0xffff0000, v92
	v_lshlrev_b32_e32 v92, 16, v93
	v_and_b32_e32 v93, 0xffff0000, v93
	v_pk_add_f32 v[78:79], v[78:79], v[106:107]
	v_pk_add_f32 v[80:81], v[84:85], v[88:89]
	v_pk_add_f32 v[84:85], v[86:87], v[114:115]
	v_pk_add_f32 v[86:87], v[94:95], v[100:101]
	v_pk_add_f32 v[82:83], v[68:69], v[82:83]
	v_pk_add_f32 v[70:71], v[70:71], v[74:75]
	s_waitcnt vmcnt(5)
	v_lshlrev_b32_e32 v74, 16, v60
	v_and_b32_e32 v75, 0xffff0000, v60
	v_pk_add_f32 v[62:63], v[64:65], v[62:63]
	v_lshlrev_b32_e32 v60, 16, v61
	v_and_b32_e32 v61, 0xffff0000, v61
	v_pk_add_f32 v[78:79], v[78:79], v[108:109]
	v_pk_add_f32 v[80:81], v[80:81], v[92:93]
	v_pk_add_f32 v[60:61], v[62:63], v[60:61]
	s_waitcnt vmcnt(4)
	v_lshlrev_b32_e32 v62, 16, v67
	v_and_b32_e32 v63, 0xffff0000, v67
	v_mov_b32_e32 v64, v87
	v_mov_b32_e32 v65, v83
	v_pk_add_f32 v[68:69], v[84:85], v[116:117]
	v_pk_add_f32 v[70:71], v[70:71], v[74:75]
	v_lshlrev_b32_e32 v74, 16, v66
	v_and_b32_e32 v75, 0xffff0000, v66
	v_pk_add_f32 v[60:61], v[60:61], v[62:63]
	v_mov_b32_e32 v62, v86
	v_mov_b32_e32 v63, v82
	v_pk_mul_f32 v[64:65], v[64:65], v[64:65]
	v_mov_b32_e32 v66, v79
	v_mov_b32_e32 v67, v81
	v_pk_fma_f32 v[62:63], v[62:63], v[62:63], v[64:65]
	v_mov_b32_e32 v64, v78
	v_mov_b32_e32 v65, v80
	v_pk_mul_f32 v[66:67], v[66:67], v[66:67]
	v_mul_f32_e32 v42, v69, v69
	v_pk_add_f32 v[70:71], v[70:71], v[74:75]
	v_pk_fma_f32 v[64:65], v[64:65], v[64:65], v[66:67]
	v_pk_fma_f32 v[66:67], v[68:69], v[68:69], v[42:43] op_sel_hi:[1,1,0]
	v_mul_f32_e32 v42, v73, v73
	v_pk_add_f32 v[62:63], v[62:63], v[62:63] op_sel:[0,1] op_sel_hi:[1,0]
	v_pk_add_f32 v[64:65], v[64:65], v[64:65] op_sel:[0,1] op_sel_hi:[1,0]
	v_pk_fma_f32 v[74:75], v[72:73], v[72:73], v[42:43] op_sel_hi:[1,1,0]
	v_pk_mul_f32 v[76:77], v[70:71], v[70:71]
	v_pk_mul_f32 v[84:85], v[60:61], v[60:61]
	v_mov_b32_e32 v63, v76
	v_mov_b32_e32 v65, v77
	v_mov_b32_e32 v67, v84
	v_mov_b32_e32 v75, v85
	v_pk_add_f32 v[62:63], v[62:63], v[64:65]
	v_pk_add_f32 v[64:65], v[66:67], v[74:75]
	s_waitcnt vmcnt(1)
	v_lshlrev_b32_e32 v66, 16, v54
	v_pk_add_f32 v[62:63], v[62:63], v[64:65]
	v_lshlrev_b32_e32 v64, 16, v56
	v_add_f32_e32 v42, v62, v63
	s_nop 1
	v_mov_b32_dpp v62, v42 quad_perm:[1,0,3,2] row_mask:0xf bank_mask:0xf
	s_waitcnt vmcnt(0)
	v_lshlrev_b32_e32 v74, 16, v52
	s_waitcnt lgkmcnt(0)
	v_add_f32_e32 v42, v42, v62
	s_nop 1
	v_mov_b32_dpp v62, v42 quad_perm:[2,3,0,1] row_mask:0xf bank_mask:0xf
	s_waitcnt lgkmcnt(0)
	v_add_f32_e32 v42, v42, v62
	s_nop 1
	v_mov_b32_dpp v63, v42 row_half_mirror row_mask:0xf bank_mask:0xf
	v_lshlrev_b32_e32 v62, 16, v58
	s_waitcnt lgkmcnt(0)
	v_add_f32_e32 v42, v42, v63
	s_nop 1
	v_mov_b32_dpp v65, v42 row_mirror row_mask:0xf bank_mask:0xf
	v_and_b32_e32 v63, 0xffff0000, v58
	v_lshlrev_b32_e32 v58, 16, v59
	v_and_b32_e32 v59, 0xffff0000, v59
	s_waitcnt lgkmcnt(0)
	v_add_f32_e32 v42, v42, v65
	v_mov_b32_e32 v67, v42
	s_nop 1
	v_permlane16_swap_b32 v42, v67
	v_and_b32_e32 v65, 0xffff0000, v56
	v_lshlrev_b32_e32 v56, 16, v57
	v_and_b32_e32 v57, 0xffff0000, v57
	s_waitcnt lgkmcnt(0)
	v_add_f32_e32 v42, v42, v67
	v_mov_b32_e32 v75, v42
	s_nop 1
	v_permlane32_swap_b32 v42, v75
	v_and_b32_e32 v67, 0xffff0000, v54
	v_lshlrev_b32_e32 v54, 16, v55
	v_and_b32_e32 v55, 0xffff0000, v55
	s_waitcnt lgkmcnt(0)
	v_add_f32_e32 v42, v42, v75
	v_fmamk_f32 v42, v42, 0x3a800000, v90
	v_mul_f32_e32 v75, 0x4b800000, v42
	v_cmp_gt_f32_e32 vcc, s91, v42
	s_nop 1
	v_cndmask_b32_e32 v42, v42, v75, vcc
	v_rsq_f32_e32 v42, v42
	v_and_b32_e32 v75, 0xffff0000, v52
	v_lshlrev_b32_e32 v52, 16, v53
	v_and_b32_e32 v53, 0xffff0000, v53
	v_mul_f32_e32 v76, 0x45800000, v42
	v_cndmask_b32_e32 v42, v42, v76, vcc
	v_pk_mul_f32 v[76:77], v[86:87], v[42:43] op_sel_hi:[1,0]
	v_pk_mul_f32 v[82:83], v[82:83], v[42:43] op_sel_hi:[1,0]
	v_pk_fma_f32 v[62:63], v[0:1], v[76:77], v[62:63]
	v_pk_fma_f32 v[58:59], v[2:3], v[82:83], v[58:59]
	v_pk_mul_f32 v[80:81], v[80:81], v[42:43] op_sel_hi:[1,0]
	v_pk_mul_f32 v[78:79], v[78:79], v[42:43] op_sel_hi:[1,0]
	v_pk_mul_f32 v[68:69], v[68:69], v[42:43] op_sel_hi:[1,0]
	v_pk_mul_f32 v[76:77], v[58:59], v[58:59]
	v_pk_mul_f32 v[82:83], v[62:63], v[62:63]
	v_pk_fma_f32 v[64:65], v[8:9], v[78:79], v[64:65]
	v_pk_fma_f32 v[56:57], v[10:11], v[80:81], v[56:57]
	v_pk_fma_f32 v[66:67], v[12:13], v[68:69], v[66:67]
	v_pk_mov_b32 v[84:85], v[82:83], v[76:77] op_sel:[1,0]
	v_mov_b32_e32 v83, v77
	v_pk_mul_f32 v[78:79], v[56:57], v[56:57]
	v_pk_mul_f32 v[80:81], v[64:65], v[64:65]
	v_pk_mul_f32 v[72:73], v[72:73], v[42:43] op_sel_hi:[1,0]
	v_mul_f32_e32 v68, v66, v66
	v_pk_add_f32 v[76:77], v[84:85], v[82:83]
	v_pk_mov_b32 v[82:83], v[80:81], v[78:79] op_sel:[1,0]
	v_mov_b32_e32 v81, v79
	v_pk_fma_f32 v[54:55], v[14:15], v[72:73], v[54:55]
	v_pk_fma_f32 v[68:69], v[66:67], v[66:67], v[68:69] op_sel_hi:[1,1,0]
	v_pk_add_f32 v[78:79], v[82:83], v[80:81]
	v_mul_f32_e32 v68, v54, v54
	v_pk_mul_f32 v[60:61], v[60:61], v[42:43] op_sel_hi:[1,0]
	v_pk_mul_f32 v[70:71], v[70:71], v[42:43] op_sel_hi:[1,0]
	v_pk_add_f32 v[76:77], v[76:77], v[76:77] op_sel_hi:[0,1]
	v_pk_add_f32 v[78:79], v[78:79], v[78:79] op_sel_hi:[0,1]
	v_pk_fma_f32 v[72:73], v[54:55], v[54:55], v[68:69] op_sel_hi:[1,1,0]
	v_pk_fma_f32 v[70:71], v[24:25], v[70:71], v[74:75]
	v_pk_fma_f32 v[52:53], v[26:27], v[60:61], v[52:53]
	v_mul_f32_e32 v68, v70, v70
	v_mul_f32_e32 v72, v71, v71
	v_mul_f32_e32 v76, v52, v52
	v_mul_f32_e32 v78, v53, v53
	v_pk_add_f32 v[60:61], v[68:69], v[72:73]
	v_pk_add_f32 v[68:69], v[76:77], v[78:79]
	v_cvt_pk_bf16_f32 v74, v62, v63
	v_lshl_add_u64 v[72:73], v[50:51], 0, s[54:55]
	v_pk_add_f32 v[60:61], v[60:61], v[68:69]
	s_nop 0
	v_add_f32_e32 v42, v60, v61
	s_nop 1
	v_mov_b32_dpp v60, v42 quad_perm:[1,0,3,2] row_mask:0xf bank_mask:0xf
	s_waitcnt lgkmcnt(0)
	v_add_f32_e32 v42, v42, v60
	s_nop 1
	v_mov_b32_dpp v60, v42 quad_perm:[2,3,0,1] row_mask:0xf bank_mask:0xf
	s_waitcnt lgkmcnt(0)
	v_add_f32_e32 v42, v42, v60
	s_nop 1
	v_mov_b32_dpp v68, v42 row_half_mirror row_mask:0xf bank_mask:0xf
	v_lshl_add_u64 v[60:61], v[50:51], 0, s[40:41]
	s_waitcnt lgkmcnt(0)
	v_add_f32_e32 v42, v42, v68
	s_nop 1
	v_mov_b32_dpp v75, v42 row_mirror row_mask:0xf bank_mask:0xf
	v_lshl_add_u64 v[68:69], v[50:51], 0, s[52:53]
	v_lshl_add_u64 v[50:51], v[50:51], 0, s[56:57]
	s_waitcnt lgkmcnt(0)
	v_add_f32_e32 v42, v42, v75
	v_mov_b32_e32 v76, v42
	s_nop 1
	v_permlane16_swap_b32 v42, v76
	v_cvt_pk_bf16_f32 v75, v58, v59
	s_waitcnt lgkmcnt(0)
	v_add_f32_e32 v42, v42, v76
	v_mov_b32_e32 v208, v74
	v_mov_b32_e32 v209, v75
	s_nop 1
	v_mov_b32_e32 v74, v42
	s_nop 1
	v_permlane32_swap_b32 v42, v74
	v_cvt_pk_bf16_f32 v60, v64, v65
	v_cvt_pk_bf16_f32 v61, v56, v57
	s_waitcnt lgkmcnt(0)
	v_add_f32_e32 v42, v42, v74
	v_mov_b32_e32 v210, v60
	v_mov_b32_e32 v211, v61
	s_nop 1
	v_cvt_pk_bf16_f32 v60, v66, v67
	v_fmamk_f32 v42, v42, 0x3a800000, v90
	v_cvt_pk_bf16_f32 v61, v54, v55
	v_cmp_gt_f32_e32 vcc, s91, v42
	v_mov_b32_e32 v212, v60
	v_mov_b32_e32 v213, v61
	s_nop 1
	v_mul_f32_e32 v60, 0x4b800000, v42
	s_nop 0
	v_cndmask_b32_e32 v42, v42, v60, vcc
	v_rsq_f32_e32 v42, v42
	v_cvt_pk_bf16_f32 v60, v70, v71
	v_cvt_pk_bf16_f32 v61, v52, v53
	s_nop 0
	v_and_b32_e32 v232, 1, v152
	v_cmp_eq_u32_e64 s[98:99], 1, v232
	v_mul_u32_u24_e32 v230, 0x1f8, v232
	v_mov_b32_e32 v231, 0
	v_lshl_add_u64 v[228:229], v[50:51], 0, v[230:231]
	v_cndmask_b32_e64 v216, v210, v208, s[98:99]
	v_cndmask_b32_e64 v217, v211, v209, s[98:99]
	s_nop 1
	v_mov_b32_dpp v218, v216 quad_perm:[1,0,3,2] row_mask:0xf bank_mask:0xf
	v_mov_b32_dpp v219, v217 quad_perm:[1,0,3,2] row_mask:0xf bank_mask:0xf
	v_cndmask_b32_e64 v220, v208, v218, s[98:99]
	v_cndmask_b32_e64 v221, v209, v219, s[98:99]
	v_cndmask_b32_e64 v222, v218, v210, s[98:99]
	v_cndmask_b32_e64 v223, v219, v211, s[98:99]
	global_store_dwordx4 v[228:229], v[220:223], off offset:-1536 sc0 sc1
	s_nop 1
	v_cndmask_b32_e64 v216, v60, v212, s[98:99]
	v_cndmask_b32_e64 v217, v61, v213, s[98:99]
	s_nop 1
	v_mov_b32_dpp v218, v216 quad_perm:[1,0,3,2] row_mask:0xf bank_mask:0xf
	v_mov_b32_dpp v219, v217 quad_perm:[1,0,3,2] row_mask:0xf bank_mask:0xf
	v_cndmask_b32_e64 v224, v212, v218, s[98:99]
	v_cndmask_b32_e64 v225, v213, v219, s[98:99]
	v_cndmask_b32_e64 v226, v218, v60, s[98:99]
	v_cndmask_b32_e64 v227, v219, v61, s[98:99]
	global_store_dwordx4 v[228:229], v[224:227], off offset:-512 sc0 sc1
	s_nop 1
	s_mov_b32 s99, 0
	s_nop 1
	v_mul_f32_e32 v50, 0x45800000, v42
	v_cndmask_b32_e32 v42, v42, v50, vcc
	v_pk_mul_f32 v[60:61], v[62:63], v[42:43] op_sel_hi:[1,0]
	v_lshl_add_u64 v[50:51], v[48:49], 0, s[6:7]
	v_pk_mul_f32 v[58:59], v[58:59], v[42:43] op_sel_hi:[1,0]
	v_pk_mul_f32 v[60:61], v[4:5], v[60:61]
	v_pk_mul_f32 v[58:59], v[6:7], v[58:59]
	v_cvt_pk_bf16_f32 v60, v60, v61
	v_pk_mul_f32 v[56:57], v[56:57], v[42:43] op_sel_hi:[1,0]
	v_cvt_pk_bf16_f32 v61, v58, v59
	s_mov_b64 s[6:7], 0x3800a00
	v_mov_b32_e32 v208, v60
	v_mov_b32_e32 v209, v61
	s_nop 1
	v_pk_mul_f32 v[50:51], v[64:65], v[42:43] op_sel_hi:[1,0]
	v_pk_mul_f32 v[56:57], v[18:19], v[56:57]
	v_pk_mul_f32 v[50:51], v[16:17], v[50:51]
	v_pk_mul_f32 v[54:55], v[54:55], v[42:43] op_sel_hi:[1,0]
	v_cvt_pk_bf16_f32 v50, v50, v51
	v_cvt_pk_bf16_f32 v51, v56, v57
	v_lshl_add_u64 v[56:57], v[48:49], 0, s[6:7]
	v_mov_b32_e32 v210, v50
	v_mov_b32_e32 v211, v51
	s_nop 1
	v_pk_mul_f32 v[50:51], v[66:67], v[42:43] op_sel_hi:[1,0]
	v_pk_mul_f32 v[54:55], v[22:23], v[54:55]
	v_pk_mul_f32 v[50:51], v[20:21], v[50:51]
	s_mov_b64 s[6:7], 0x3800c00
	v_cvt_pk_bf16_f32 v50, v50, v51
	v_cvt_pk_bf16_f32 v51, v54, v55
	v_lshl_add_u64 v[54:55], v[48:49], 0, s[6:7]
	v_mov_b32_e32 v212, v50
	v_mov_b32_e32 v213, v51
	s_nop 1
	v_pk_mul_f32 v[50:51], v[70:71], v[42:43] op_sel_hi:[1,0]
	v_pk_mul_f32 v[52:53], v[52:53], v[42:43] op_sel_hi:[1,0]
	v_pk_mul_f32 v[50:51], v[28:29], v[50:51]
	s_mov_b64 s[6:7], 0x3800e00
	v_pk_mul_f32 v[52:53], v[30:31], v[52:53]
	v_cvt_pk_bf16_f32 v50, v50, v51
	v_lshl_add_u64 v[48:49], v[48:49], 0, s[6:7]
	v_cvt_pk_bf16_f32 v51, v52, v53
	s_nop 0
	v_and_b32_e32 v232, 1, v152
	v_cmp_eq_u32_e64 s[98:99], 1, v232
	v_mul_u32_u24_e32 v230, 0x1f8, v232
	v_mov_b32_e32 v231, 0
	v_lshl_add_u64 v[228:229], v[48:49], 0, v[230:231]
	v_cndmask_b32_e64 v216, v210, v208, s[98:99]
	v_cndmask_b32_e64 v217, v211, v209, s[98:99]
	s_nop 1
	v_mov_b32_dpp v218, v216 quad_perm:[1,0,3,2] row_mask:0xf bank_mask:0xf
	v_mov_b32_dpp v219, v217 quad_perm:[1,0,3,2] row_mask:0xf bank_mask:0xf
	v_cndmask_b32_e64 v220, v208, v218, s[98:99]
	v_cndmask_b32_e64 v221, v209, v219, s[98:99]
	v_cndmask_b32_e64 v222, v218, v210, s[98:99]
	v_cndmask_b32_e64 v223, v219, v211, s[98:99]
	global_store_dwordx4 v[228:229], v[220:223], off offset:-1536 sc0 sc1
	s_nop 1
	v_cndmask_b32_e64 v216, v50, v212, s[98:99]
	v_cndmask_b32_e64 v217, v51, v213, s[98:99]
	s_nop 1
	v_mov_b32_dpp v218, v216 quad_perm:[1,0,3,2] row_mask:0xf bank_mask:0xf
	v_mov_b32_dpp v219, v217 quad_perm:[1,0,3,2] row_mask:0xf bank_mask:0xf
	v_cndmask_b32_e64 v224, v212, v218, s[98:99]
	v_cndmask_b32_e64 v225, v213, v219, s[98:99]
	v_cndmask_b32_e64 v226, v218, v50, s[98:99]
	v_cndmask_b32_e64 v227, v219, v51, s[98:99]
	global_store_dwordx4 v[228:229], v[224:227], off offset:-512 sc0 sc1
	s_nop 1
	s_mov_b32 s99, 0
	s_nop 1
	s_cbranch_scc0 .LBB0_2023

.LBB0_2016:
	v_lshl_add_u64 v[48:49], v[46:47], 0, s[66:67]
	s_mov_b32 s14, 0xda00000
	v_add_co_u32_e32 v50, vcc, s14, v48
	s_mov_b32 s14, 0xdb80000
	s_nop 0
	v_addc_co_u32_e32 v51, vcc, 0, v49, vcc
	v_add_co_u32_e32 v52, vcc, s14, v48
	s_mov_b32 s14, 0xdd00000
	s_nop 0
	v_addc_co_u32_e32 v53, vcc, 0, v49, vcc
	global_load_dwordx2 v[66:67], v[50:51], off
	global_load_dwordx2 v[76:77], v[52:53], off
	v_add_co_u32_e32 v54, vcc, s14, v48
	s_mov_b32 s14, 0xde80000
	s_nop 0
	v_addc_co_u32_e32 v55, vcc, 0, v49, vcc
	global_load_dwordx2 v[78:79], v[54:55], off
	v_add_co_u32_e32 v56, vcc, s14, v48
	s_lshl_b64 s[6:7], s[6:7], 12
	s_nop 0
	v_addc_co_u32_e32 v57, vcc, 0, v49, vcc
	global_load_dwordx2 v[88:89], v[56:57], off
	global_load_dwordx2 v[92:93], v[50:51], off offset:512
	global_load_dwordx2 v[94:95], v[52:53], off offset:512
	global_load_dwordx2 v[96:97], v[54:55], off offset:512
	global_load_dwordx2 v[98:99], v[56:57], off offset:512
	global_load_dwordx2 v[86:87], v[50:51], off offset:1024
	global_load_dwordx2 v[82:83], v[52:53], off offset:1024
	global_load_dwordx2 v[80:81], v[54:55], off offset:1024
	global_load_dwordx2 v[84:85], v[56:57], off offset:1024
	global_load_dwordx2 v[72:73], v[50:51], off offset:1536
	global_load_dwordx2 v[70:71], v[52:53], off offset:1536
	global_load_dwordx2 v[68:69], v[54:55], off offset:1536
	global_load_dwordx2 v[74:75], v[56:57], off offset:1536
	s_add_u32 s6, s10, s6
	s_addc_u32 s7, s11, s7
	v_lshl_add_u64 v[48:49], v[32:33], 3, s[6:7]
	global_load_dwordx2 v[64:65], v[48:49], off offset:2048
	global_load_dwordx2 v[62:63], v[48:49], off offset:2560
	global_load_dwordx2 v[60:61], v[48:49], off offset:3072
	global_load_dwordx2 v[58:59], v[48:49], off offset:3584
	s_mov_b64 s[6:7], 0x3800000
	s_add_i32 s17, s17, 1
	s_cmpk_lt_u32 s17, 0x4080
	s_mov_b64 s[10:11], -1
	s_waitcnt vmcnt(19)
	v_lshlrev_b32_e32 v100, 16, v66
	v_and_b32_e32 v101, 0xffff0000, v66
	v_lshlrev_b32_e32 v66, 16, v67
	v_and_b32_e32 v67, 0xffff0000, v67
	s_waitcnt vmcnt(18)
	v_lshlrev_b32_e32 v102, 16, v76
	v_and_b32_e32 v103, 0xffff0000, v76
	v_lshlrev_b32_e32 v76, 16, v77
	v_and_b32_e32 v77, 0xffff0000, v77
	v_pk_add_f32 v[66:67], v[66:67], 0 op_sel_hi:[1,0]
	s_waitcnt vmcnt(17)
	v_lshlrev_b32_e32 v104, 16, v78
	v_and_b32_e32 v105, 0xffff0000, v78
	v_lshlrev_b32_e32 v78, 16, v79
	v_and_b32_e32 v79, 0xffff0000, v79
	s_waitcnt vmcnt(15)
	v_lshlrev_b32_e32 v108, 16, v92
	v_and_b32_e32 v109, 0xffff0000, v92
	v_lshlrev_b32_e32 v92, 16, v93
	v_and_b32_e32 v93, 0xffff0000, v93
	v_pk_add_f32 v[66:67], v[66:67], v[76:77]
	v_lshlrev_b32_e32 v106, 16, v88
	v_and_b32_e32 v107, 0xffff0000, v88
	v_lshlrev_b32_e32 v88, 16, v89
	v_and_b32_e32 v89, 0xffff0000, v89
	s_waitcnt vmcnt(14)
	v_lshlrev_b32_e32 v110, 16, v94
	v_and_b32_e32 v111, 0xffff0000, v94
	v_lshlrev_b32_e32 v94, 16, v95
	v_and_b32_e32 v95, 0xffff0000, v95
	v_pk_add_f32 v[92:93], v[92:93], 0 op_sel_hi:[1,0]
	v_pk_add_f32 v[66:67], v[66:67], v[78:79]
	v_pk_add_f32 v[100:101], v[100:101], 0 op_sel_hi:[1,0]
	v_pk_add_f32 v[92:93], v[92:93], v[94:95]
	v_pk_add_f32 v[78:79], v[66:67], v[88:89]
	s_waitcnt vmcnt(13)
	v_lshlrev_b32_e32 v88, 16, v97
	v_and_b32_e32 v89, 0xffff0000, v97
	v_pk_add_f32 v[108:109], v[108:109], 0 op_sel_hi:[1,0]
	v_pk_add_f32 v[100:101], v[100:101], v[102:103]
	v_pk_add_f32 v[88:89], v[92:93], v[88:89]
	s_waitcnt vmcnt(12)
	v_lshlrev_b32_e32 v92, 16, v99
	v_and_b32_e32 v93, 0xffff0000, v99
	v_lshlrev_b32_e32 v112, 16, v96
	v_and_b32_e32 v113, 0xffff0000, v96
	v_pk_add_f32 v[76:77], v[108:109], v[110:111]
	v_pk_add_f32 v[94:95], v[100:101], v[104:105]
	v_pk_add_f32 v[92:93], v[88:89], v[92:93]
	s_waitcnt vmcnt(11)
	v_lshlrev_b32_e32 v88, 16, v86
	v_and_b32_e32 v89, 0xffff0000, v86
	v_lshlrev_b32_e32 v86, 16, v87
	v_and_b32_e32 v87, 0xffff0000, v87
	v_pk_add_f32 v[100:101], v[76:77], v[112:113]
	v_pk_add_f32 v[76:77], v[94:95], v[106:107]
	v_pk_add_f32 v[88:89], v[88:89], 0 op_sel_hi:[1,0]
	s_waitcnt vmcnt(10)
	v_lshlrev_b32_e32 v94, 16, v82
	v_and_b32_e32 v95, 0xffff0000, v82
	v_pk_add_f32 v[86:87], v[86:87], 0 op_sel_hi:[1,0]
	v_lshlrev_b32_e32 v82, 16, v83
	v_and_b32_e32 v83, 0xffff0000, v83
	v_pk_add_f32 v[88:89], v[88:89], v[94:95]
	s_waitcnt vmcnt(9)
	v_lshlrev_b32_e32 v94, 16, v80
	v_and_b32_e32 v95, 0xffff0000, v80
	v_pk_add_f32 v[82:83], v[86:87], v[82:83]
	v_lshlrev_b32_e32 v80, 16, v81
	v_and_b32_e32 v81, 0xffff0000, v81
	v_pk_add_f32 v[80:81], v[82:83], v[80:81]
	s_waitcnt vmcnt(8)
	v_lshlrev_b32_e32 v82, 16, v85
	v_and_b32_e32 v83, 0xffff0000, v85
	v_pk_add_f32 v[82:83], v[80:81], v[82:83]
	s_waitcnt vmcnt(7)
	v_lshlrev_b32_e32 v80, 16, v72
	v_and_b32_e32 v81, 0xffff0000, v72
	v_lshlrev_b32_e32 v72, 16, v73
	v_and_b32_e32 v73, 0xffff0000, v73
	v_pk_add_f32 v[88:89], v[88:89], v[94:95]
	v_lshlrev_b32_e32 v94, 16, v84
	v_and_b32_e32 v95, 0xffff0000, v84
	v_pk_add_f32 v[80:81], v[80:81], 0 op_sel_hi:[1,0]
	s_waitcnt vmcnt(6)
	v_lshlrev_b32_e32 v84, 16, v70
	v_and_b32_e32 v85, 0xffff0000, v70
	v_pk_add_f32 v[72:73], v[72:73], 0 op_sel_hi:[1,0]
	v_lshlrev_b32_e32 v70, 16, v71
	v_and_b32_e32 v71, 0xffff0000, v71
	v_lshlrev_b32_e32 v114, 16, v98
	v_and_b32_e32 v115, 0xffff0000, v98
	v_pk_add_f32 v[80:81], v[80:81], v[84:85]
	s_waitcnt vmcnt(5)
	v_lshlrev_b32_e32 v84, 16, v68
	v_and_b32_e32 v85, 0xffff0000, v68
	v_pk_add_f32 v[70:71], v[72:73], v[70:71]
	v_lshlrev_b32_e32 v68, 16, v69
	v_and_b32_e32 v69, 0xffff0000, v69
	v_pk_add_f32 v[66:67], v[100:101], v[114:115]
	v_pk_add_f32 v[68:69], v[70:71], v[68:69]
	s_waitcnt vmcnt(4)
	v_lshlrev_b32_e32 v70, 16, v75
	v_and_b32_e32 v71, 0xffff0000, v75
	v_mov_b32_e32 v72, v77
	v_mov_b32_e32 v73, v79
	v_pk_add_f32 v[88:89], v[88:89], v[94:95]
	v_pk_add_f32 v[80:81], v[80:81], v[84:85]
	v_lshlrev_b32_e32 v84, 16, v74
	v_and_b32_e32 v85, 0xffff0000, v74
	v_pk_add_f32 v[68:69], v[68:69], v[70:71]
	v_mov_b32_e32 v70, v76
	v_mov_b32_e32 v71, v78
	v_pk_mul_f32 v[72:73], v[72:73], v[72:73]
	v_mov_b32_e32 v74, v67
	v_mov_b32_e32 v75, v93
	v_pk_fma_f32 v[70:71], v[70:71], v[70:71], v[72:73]
	v_mov_b32_e32 v72, v66
	v_mov_b32_e32 v73, v92
	v_pk_mul_f32 v[74:75], v[74:75], v[74:75]
	v_mul_f32_e32 v42, v89, v89
	v_pk_add_f32 v[80:81], v[80:81], v[84:85]
	v_pk_fma_f32 v[72:73], v[72:73], v[72:73], v[74:75]
	v_pk_fma_f32 v[74:75], v[88:89], v[88:89], v[42:43] op_sel_hi:[1,1,0]
	v_mul_f32_e32 v42, v83, v83
	v_pk_add_f32 v[70:71], v[70:71], v[70:71] op_sel:[0,1] op_sel_hi:[1,0]
	v_pk_add_f32 v[72:73], v[72:73], v[72:73] op_sel:[0,1] op_sel_hi:[1,0]
	v_pk_fma_f32 v[84:85], v[82:83], v[82:83], v[42:43] op_sel_hi:[1,1,0]
	v_pk_mul_f32 v[86:87], v[80:81], v[80:81]
	v_pk_mul_f32 v[94:95], v[68:69], v[68:69]
	v_mov_b32_e32 v71, v86
	v_mov_b32_e32 v73, v87
	v_mov_b32_e32 v75, v94
	v_mov_b32_e32 v85, v95
	v_pk_add_f32 v[70:71], v[70:71], v[72:73]
	v_pk_add_f32 v[72:73], v[74:75], v[84:85]
	s_waitcnt vmcnt(1)
	v_lshlrev_b32_e32 v74, 16, v60
	v_pk_add_f32 v[70:71], v[70:71], v[72:73]
	v_lshlrev_b32_e32 v72, 16, v62
	v_add_f32_e32 v42, v70, v71
	s_nop 1
	v_mov_b32_dpp v70, v42 quad_perm:[1,0,3,2] row_mask:0xf bank_mask:0xf
	s_waitcnt vmcnt(0)
	v_lshlrev_b32_e32 v84, 16, v58
	s_waitcnt lgkmcnt(0)
	v_add_f32_e32 v42, v42, v70
	s_nop 1
	v_mov_b32_dpp v70, v42 quad_perm:[2,3,0,1] row_mask:0xf bank_mask:0xf
	s_waitcnt lgkmcnt(0)
	v_add_f32_e32 v42, v42, v70
	s_nop 1
	v_mov_b32_dpp v71, v42 row_half_mirror row_mask:0xf bank_mask:0xf
	v_lshlrev_b32_e32 v70, 16, v64
	s_waitcnt lgkmcnt(0)
	v_add_f32_e32 v42, v42, v71
	s_nop 1
	v_mov_b32_dpp v73, v42 row_mirror row_mask:0xf bank_mask:0xf
	v_and_b32_e32 v71, 0xffff0000, v64
	v_lshlrev_b32_e32 v64, 16, v65
	v_and_b32_e32 v65, 0xffff0000, v65
	s_waitcnt lgkmcnt(0)
	v_add_f32_e32 v42, v42, v73
	v_mov_b32_e32 v75, v42
	s_nop 1
	v_permlane16_swap_b32 v42, v75
	v_and_b32_e32 v73, 0xffff0000, v62
	v_lshlrev_b32_e32 v62, 16, v63
	v_and_b32_e32 v63, 0xffff0000, v63
	s_waitcnt lgkmcnt(0)
	v_add_f32_e32 v42, v42, v75
	v_mov_b32_e32 v85, v42
	s_nop 1
	v_permlane32_swap_b32 v42, v85
	v_and_b32_e32 v75, 0xffff0000, v60
	v_lshlrev_b32_e32 v60, 16, v61
	v_and_b32_e32 v61, 0xffff0000, v61
	s_waitcnt lgkmcnt(0)
	v_add_f32_e32 v42, v42, v85
	v_fmamk_f32 v42, v42, 0x3a800000, v90
	v_mul_f32_e32 v85, 0x4b800000, v42
	v_cmp_gt_f32_e32 vcc, s91, v42
	s_nop 1
	v_cndmask_b32_e32 v42, v42, v85, vcc
	v_rsq_f32_e32 v42, v42
	v_and_b32_e32 v85, 0xffff0000, v58
	v_lshlrev_b32_e32 v58, 16, v59
	v_and_b32_e32 v59, 0xffff0000, v59
	v_mul_f32_e32 v86, 0x45800000, v42
	v_cndmask_b32_e32 v42, v42, v86, vcc
	v_pk_mul_f32 v[76:77], v[76:77], v[42:43] op_sel_hi:[1,0]
	v_pk_mul_f32 v[78:79], v[78:79], v[42:43] op_sel_hi:[1,0]
	v_pk_fma_f32 v[70:71], v[0:1], v[76:77], v[70:71]
	v_pk_fma_f32 v[64:65], v[2:3], v[78:79], v[64:65]
	v_pk_mul_f32 v[78:79], v[70:71], v[70:71]
	v_pk_mul_f32 v[76:77], v[64:65], v[64:65]
	v_pk_mul_f32 v[66:67], v[66:67], v[42:43] op_sel_hi:[1,0]
	v_pk_mov_b32 v[86:87], v[78:79], v[76:77] op_sel:[1,0]
	v_mov_b32_e32 v79, v77
	v_pk_add_f32 v[76:77], v[86:87], v[78:79]
	v_pk_mul_f32 v[78:79], v[92:93], v[42:43] op_sel_hi:[1,0]
	v_pk_fma_f32 v[66:67], v[8:9], v[66:67], v[72:73]
	v_pk_fma_f32 v[62:63], v[10:11], v[78:79], v[62:63]
	v_pk_mul_f32 v[78:79], v[66:67], v[66:67]
	v_pk_mul_f32 v[72:73], v[62:63], v[62:63]
	v_pk_mul_f32 v[68:69], v[68:69], v[42:43] op_sel_hi:[1,0]
	v_pk_mov_b32 v[86:87], v[78:79], v[72:73] op_sel:[1,0]
	v_mov_b32_e32 v79, v73
	v_pk_add_f32 v[72:73], v[86:87], v[78:79]
	v_pk_mul_f32 v[78:79], v[82:83], v[42:43] op_sel_hi:[1,0]
	v_pk_mul_f32 v[82:83], v[88:89], v[42:43] op_sel_hi:[1,0]
	v_pk_add_f32 v[72:73], v[72:73], v[72:73] op_sel_hi:[0,1]
	v_pk_fma_f32 v[74:75], v[12:13], v[82:83], v[74:75]
	v_pk_fma_f32 v[60:61], v[14:15], v[78:79], v[60:61]
	v_mul_f32_e32 v72, v74, v74
	v_pk_fma_f32 v[78:79], v[74:75], v[74:75], v[72:73] op_sel_hi:[1,1,0]
	v_mul_f32_e32 v72, v60, v60
	v_pk_mul_f32 v[80:81], v[80:81], v[42:43] op_sel_hi:[1,0]
	v_pk_add_f32 v[76:77], v[76:77], v[76:77] op_sel_hi:[0,1]
	v_pk_fma_f32 v[82:83], v[60:61], v[60:61], v[72:73] op_sel_hi:[1,1,0]
	v_pk_fma_f32 v[80:81], v[24:25], v[80:81], v[84:85]
	v_pk_fma_f32 v[58:59], v[26:27], v[68:69], v[58:59]
	v_mul_f32_e32 v78, v80, v80
	v_mul_f32_e32 v82, v81, v81
	v_mul_f32_e32 v76, v58, v58
	v_mul_f32_e32 v72, v59, v59
	v_pk_add_f32 v[68:69], v[78:79], v[82:83]
	v_pk_add_f32 v[72:73], v[76:77], v[72:73]
	v_cvt_pk_bf16_f32 v78, v70, v71
	v_lshl_add_u64 v[76:77], v[48:49], 0, s[54:55]
	v_pk_add_f32 v[68:69], v[68:69], v[72:73]
	s_nop 0
	v_add_f32_e32 v42, v68, v69
	s_nop 1
	v_mov_b32_dpp v68, v42 quad_perm:[1,0,3,2] row_mask:0xf bank_mask:0xf
	s_waitcnt lgkmcnt(0)
	v_add_f32_e32 v42, v42, v68
	s_nop 1
	v_mov_b32_dpp v68, v42 quad_perm:[2,3,0,1] row_mask:0xf bank_mask:0xf
	s_waitcnt lgkmcnt(0)
	v_add_f32_e32 v42, v42, v68
	s_nop 1
	v_mov_b32_dpp v72, v42 row_half_mirror row_mask:0xf bank_mask:0xf
	v_lshl_add_u64 v[68:69], v[48:49], 0, s[40:41]
	s_waitcnt lgkmcnt(0)
	v_add_f32_e32 v42, v42, v72
	s_nop 1
	v_mov_b32_dpp v79, v42 row_mirror row_mask:0xf bank_mask:0xf
	v_lshl_add_u64 v[72:73], v[48:49], 0, s[52:53]
	v_lshl_add_u64 v[48:49], v[48:49], 0, s[56:57]
	s_waitcnt lgkmcnt(0)
	v_add_f32_e32 v42, v42, v79
	v_mov_b32_e32 v82, v42
	s_nop 1
	v_permlane16_swap_b32 v42, v82
	v_cvt_pk_bf16_f32 v79, v64, v65
	s_waitcnt lgkmcnt(0)
	v_add_f32_e32 v42, v42, v82
	v_mov_b32_e32 v208, v78
	v_mov_b32_e32 v209, v79
	s_nop 1
	v_mov_b32_e32 v78, v42
	s_nop 1
	v_permlane32_swap_b32 v42, v78
	v_cvt_pk_bf16_f32 v68, v66, v67
	v_cvt_pk_bf16_f32 v69, v62, v63
	s_waitcnt lgkmcnt(0)
	v_add_f32_e32 v42, v42, v78
	v_mov_b32_e32 v210, v68
	v_mov_b32_e32 v211, v69
	s_nop 1
	v_cvt_pk_bf16_f32 v68, v74, v75
	v_fmamk_f32 v42, v42, 0x3a800000, v90
	v_cvt_pk_bf16_f32 v69, v60, v61
	v_cmp_gt_f32_e32 vcc, s91, v42
	v_mov_b32_e32 v212, v68
	v_mov_b32_e32 v213, v69
	s_nop 1
	v_mul_f32_e32 v68, 0x4b800000, v42
	s_nop 0
	v_cndmask_b32_e32 v42, v42, v68, vcc
	v_rsq_f32_e32 v42, v42
	v_cvt_pk_bf16_f32 v68, v80, v81
	v_cvt_pk_bf16_f32 v69, v58, v59
	s_nop 0
	v_and_b32_e32 v232, 1, v152
	v_cmp_eq_u32_e64 s[98:99], 1, v232
	v_mul_u32_u24_e32 v230, 0x1f8, v232
	v_mov_b32_e32 v231, 0
	v_lshl_add_u64 v[228:229], v[48:49], 0, v[230:231]
	v_cndmask_b32_e64 v216, v210, v208, s[98:99]
	v_cndmask_b32_e64 v217, v211, v209, s[98:99]
	s_nop 1
	v_mov_b32_dpp v218, v216 quad_perm:[1,0,3,2] row_mask:0xf bank_mask:0xf
	v_mov_b32_dpp v219, v217 quad_perm:[1,0,3,2] row_mask:0xf bank_mask:0xf
	v_cndmask_b32_e64 v220, v208, v218, s[98:99]
	v_cndmask_b32_e64 v221, v209, v219, s[98:99]
	v_cndmask_b32_e64 v222, v218, v210, s[98:99]
	v_cndmask_b32_e64 v223, v219, v211, s[98:99]
	global_store_dwordx4 v[228:229], v[220:223], off offset:-1536 sc0 sc1
	s_nop 1
	v_cndmask_b32_e64 v216, v68, v212, s[98:99]
	v_cndmask_b32_e64 v217, v69, v213, s[98:99]
	s_nop 1
	v_mov_b32_dpp v218, v216 quad_perm:[1,0,3,2] row_mask:0xf bank_mask:0xf
	v_mov_b32_dpp v219, v217 quad_perm:[1,0,3,2] row_mask:0xf bank_mask:0xf
	v_cndmask_b32_e64 v224, v212, v218, s[98:99]
	v_cndmask_b32_e64 v225, v213, v219, s[98:99]
	v_cndmask_b32_e64 v226, v218, v68, s[98:99]
	v_cndmask_b32_e64 v227, v219, v69, s[98:99]
	global_store_dwordx4 v[228:229], v[224:227], off offset:-512 sc0 sc1
	s_nop 1
	s_mov_b32 s99, 0
	s_nop 1
	v_mul_f32_e32 v48, 0x45800000, v42
	v_cndmask_b32_e32 v42, v42, v48, vcc
	v_pk_mul_f32 v[70:71], v[70:71], v[42:43] op_sel_hi:[1,0]
	v_pk_mul_f32 v[64:65], v[64:65], v[42:43] op_sel_hi:[1,0]
	v_pk_mul_f32 v[70:71], v[4:5], v[70:71]
	v_pk_mul_f32 v[64:65], v[6:7], v[64:65]
	v_lshl_add_u64 v[48:49], v[44:45], 0, s[66:67]
	v_cvt_pk_bf16_f32 v70, v70, v71
	v_cvt_pk_bf16_f32 v71, v64, v65
	v_pk_mul_f32 v[64:65], v[66:67], v[42:43] op_sel_hi:[1,0]
	v_pk_mul_f32 v[62:63], v[62:63], v[42:43] op_sel_hi:[1,0]
	v_lshl_add_u64 v[68:69], v[48:49], 0, s[6:7]
	v_pk_mul_f32 v[62:63], v[18:19], v[62:63]
	v_pk_mul_f32 v[64:65], v[16:17], v[64:65]
	s_mov_b64 s[6:7], 0x3800200
	v_mov_b32_e32 v208, v70
	v_mov_b32_e32 v209, v71
	s_nop 1
	v_cvt_pk_bf16_f32 v64, v64, v65
	v_cvt_pk_bf16_f32 v65, v62, v63
	v_lshl_add_u64 v[62:63], v[48:49], 0, s[6:7]
	v_mov_b32_e32 v210, v64
	v_mov_b32_e32 v211, v65
	s_nop 1
	v_pk_mul_f32 v[62:63], v[74:75], v[42:43] op_sel_hi:[1,0]
	v_pk_mul_f32 v[60:61], v[60:61], v[42:43] op_sel_hi:[1,0]
	v_pk_mul_f32 v[62:63], v[20:21], v[62:63]
	v_pk_mul_f32 v[60:61], v[22:23], v[60:61]
	s_mov_b64 s[6:7], 0x3800400
	v_cvt_pk_bf16_f32 v62, v62, v63
	v_cvt_pk_bf16_f32 v63, v60, v61
	v_lshl_add_u64 v[60:61], v[48:49], 0, s[6:7]
	v_mov_b32_e32 v212, v62
	v_mov_b32_e32 v213, v63
	s_nop 1
	v_pk_mul_f32 v[60:61], v[80:81], v[42:43] op_sel_hi:[1,0]
	v_pk_mul_f32 v[58:59], v[58:59], v[42:43] op_sel_hi:[1,0]
	v_pk_mul_f32 v[60:61], v[28:29], v[60:61]
	v_pk_mul_f32 v[58:59], v[30:31], v[58:59]
	s_mov_b64 s[6:7], 0x3800600
	v_cvt_pk_bf16_f32 v60, v60, v61
	v_cvt_pk_bf16_f32 v61, v58, v59
	v_lshl_add_u64 v[58:59], v[48:49], 0, s[6:7]
	v_and_b32_e32 v232, 1, v152
	v_cmp_eq_u32_e64 s[98:99], 1, v232
	v_mul_u32_u24_e32 v230, 0x1f8, v232
	v_mov_b32_e32 v231, 0
	v_lshl_add_u64 v[228:229], v[58:59], 0, v[230:231]
	v_cndmask_b32_e64 v216, v210, v208, s[98:99]
	v_cndmask_b32_e64 v217, v211, v209, s[98:99]
	s_nop 1
	v_mov_b32_dpp v218, v216 quad_perm:[1,0,3,2] row_mask:0xf bank_mask:0xf
	v_mov_b32_dpp v219, v217 quad_perm:[1,0,3,2] row_mask:0xf bank_mask:0xf
	v_cndmask_b32_e64 v220, v208, v218, s[98:99]
	v_cndmask_b32_e64 v221, v209, v219, s[98:99]
	v_cndmask_b32_e64 v222, v218, v210, s[98:99]
	v_cndmask_b32_e64 v223, v219, v211, s[98:99]
	global_store_dwordx4 v[228:229], v[220:223], off offset:-1536 sc0 sc1
	s_nop 1
	v_cndmask_b32_e64 v216, v60, v212, s[98:99]
	v_cndmask_b32_e64 v217, v61, v213, s[98:99]
	s_nop 1
	v_mov_b32_dpp v218, v216 quad_perm:[1,0,3,2] row_mask:0xf bank_mask:0xf
	v_mov_b32_dpp v219, v217 quad_perm:[1,0,3,2] row_mask:0xf bank_mask:0xf
	v_cndmask_b32_e64 v224, v212, v218, s[98:99]
	v_cndmask_b32_e64 v225, v213, v219, s[98:99]
	v_cndmask_b32_e64 v226, v218, v60, s[98:99]
	v_cndmask_b32_e64 v227, v219, v61, s[98:99]
	global_store_dwordx4 v[228:229], v[224:227], off offset:-512 sc0 sc1
	s_nop 1
	s_mov_b32 s99, 0
	s_nop 1
	s_cbranch_scc1 .LBB0_2018
	s_add_u32 s6, s16, s0
	s_addc_u32 s7, 0, s1
	s_add_u32 s6, s6, 1
	s_addc_u32 s7, s7, 0
	s_mov_b64 s[10:11], 0

.LBB0_2034:
	s_or_b64 exec, exec, s[38:39]
	s_lshl_b64 s[0:1], s[0:1], 12
	s_add_u32 s0, s10, s0
	s_addc_u32 s1, s11, s1
	v_lshl_add_u64 v[44:45], v[32:33], 3, s[0:1]
	s_lshl_b64 s[0:1], s[64:65], 11
	v_lshl_add_u64 v[54:55], v[38:39], 0, s[0:1]
	global_load_dwordx2 v[46:47], v[44:45], off offset:2048
	global_load_dwordx2 v[48:49], v[44:45], off offset:2560
	global_load_dwordx2 v[50:51], v[44:45], off offset:3072
	global_load_dwordx2 v[52:53], v[44:45], off offset:3584
	global_load_dwordx2 v[56:57], v[54:55], off
	global_load_dwordx2 v[58:59], v[54:55], off offset:512
	global_load_dwordx2 v[60:61], v[54:55], off offset:1024
	s_nop 0
	global_load_dwordx2 v[54:55], v[54:55], off offset:1536
	s_waitcnt vmcnt(8)
	s_nop 1
	v_mov_b32_dpp v62, v42 quad_perm:[1,0,3,2] row_mask:0xf bank_mask:0xf
	s_mov_b64 s[10:11], -1
	s_waitcnt lgkmcnt(0)
	v_add_f32_e32 v42, v42, v62
	s_nop 1
	v_mov_b32_dpp v62, v42 quad_perm:[2,3,0,1] row_mask:0xf bank_mask:0xf
	s_waitcnt lgkmcnt(0)
	v_add_f32_e32 v42, v42, v62
	s_nop 1
	v_mov_b32_dpp v62, v42 row_half_mirror row_mask:0xf bank_mask:0xf
	s_waitcnt lgkmcnt(0)
	v_add_f32_e32 v42, v42, v62
	s_nop 1
	v_mov_b32_dpp v62, v42 row_mirror row_mask:0xf bank_mask:0xf
	s_waitcnt lgkmcnt(0)
	v_add_f32_e32 v42, v42, v62
	v_mov_b32_e32 v62, v42
	s_nop 1
	v_permlane16_swap_b32 v42, v62
	s_waitcnt lgkmcnt(0)
	v_add_f32_e32 v42, v42, v62
	v_mov_b32_e32 v62, v42
	s_nop 1
	v_permlane32_swap_b32 v42, v62
	s_waitcnt lgkmcnt(0)
	v_add_f32_e32 v42, v42, v62
	v_fmamk_f32 v42, v42, 0x3a800000, v90
	v_mul_f32_e32 v62, 0x4b800000, v42
	v_cmp_gt_f32_e32 vcc, s91, v42
	s_waitcnt vmcnt(7)
	v_and_b32_e32 v63, 0xffff0000, v46
	v_cndmask_b32_e32 v42, v42, v62, vcc
	v_rsq_f32_e32 v42, v42
	s_waitcnt vmcnt(3)
	v_lshlrev_b32_e32 v70, 16, v56
	v_and_b32_e32 v71, 0xffff0000, v56
	v_lshlrev_b32_e32 v56, 16, v57
	v_mul_f32_e32 v62, 0x45800000, v42
	v_cndmask_b32_e32 v42, v42, v62, vcc
	v_and_b32_e32 v57, 0xffff0000, v57
	s_waitcnt vmcnt(2)
	v_lshlrev_b32_e32 v72, 16, v58
	v_and_b32_e32 v73, 0xffff0000, v58
	v_lshlrev_b32_e32 v58, 16, v59
	v_and_b32_e32 v59, 0xffff0000, v59
	v_lshlrev_b32_e32 v62, 16, v46
	v_lshlrev_b32_e32 v46, 16, v47
	v_and_b32_e32 v47, 0xffff0000, v47
	v_lshlrev_b32_e32 v64, 16, v48
	v_and_b32_e32 v65, 0xffff0000, v48
	v_lshlrev_b32_e32 v48, 16, v49
	v_and_b32_e32 v49, 0xffff0000, v49
	s_waitcnt vmcnt(1)
	v_lshlrev_b32_e32 v74, 16, v60
	v_and_b32_e32 v75, 0xffff0000, v60
	v_lshlrev_b32_e32 v60, 16, v61
	v_and_b32_e32 v61, 0xffff0000, v61
	v_pk_mul_f32 v[70:71], v[42:43], v[70:71] op_sel_hi:[0,1]
	v_pk_mul_f32 v[56:57], v[42:43], v[56:57] op_sel_hi:[0,1]
	v_pk_mul_f32 v[58:59], v[42:43], v[58:59] op_sel_hi:[0,1]
	v_pk_mul_f32 v[72:73], v[42:43], v[72:73] op_sel_hi:[0,1]
	v_lshlrev_b32_e32 v66, 16, v50
	v_and_b32_e32 v67, 0xffff0000, v50
	v_lshlrev_b32_e32 v50, 16, v51
	v_and_b32_e32 v51, 0xffff0000, v51
	v_pk_mul_f32 v[60:61], v[42:43], v[60:61] op_sel_hi:[0,1]
	v_pk_mul_f32 v[74:75], v[42:43], v[74:75] op_sel_hi:[0,1]
	v_pk_fma_f32 v[46:47], v[2:3], v[56:57], v[46:47]
	v_pk_fma_f32 v[56:57], v[0:1], v[70:71], v[62:63]
	v_pk_fma_f32 v[62:63], v[8:9], v[72:73], v[64:65]
	v_pk_fma_f32 v[48:49], v[10:11], v[58:59], v[48:49]
	v_pk_fma_f32 v[58:59], v[12:13], v[74:75], v[66:67]
	v_pk_fma_f32 v[50:51], v[14:15], v[60:61], v[50:51]
	v_pk_mul_f32 v[60:61], v[46:47], v[46:47]
	v_pk_mul_f32 v[64:65], v[56:57], v[56:57]
	v_pk_mul_f32 v[66:67], v[48:49], v[48:49]
	v_pk_mul_f32 v[70:71], v[62:63], v[62:63]
	v_pk_mov_b32 v[74:75], v[64:65], v[60:61] op_sel:[1,0]
	v_mov_b32_e32 v65, v61
	v_pk_mov_b32 v[60:61], v[70:71], v[66:67] op_sel:[1,0]
	v_mov_b32_e32 v71, v67
	v_pk_add_f32 v[60:61], v[60:61], v[70:71]
	s_waitcnt vmcnt(0)
	v_lshlrev_b32_e32 v76, 16, v54
	v_and_b32_e32 v77, 0xffff0000, v54
	v_lshlrev_b32_e32 v54, 16, v55
	v_and_b32_e32 v55, 0xffff0000, v55
	v_mul_f32_e32 v72, v58, v58
	v_pk_add_f32 v[60:61], v[60:61], v[60:61] op_sel_hi:[0,1]
	v_lshlrev_b32_e32 v68, 16, v52
	v_and_b32_e32 v69, 0xffff0000, v52
	v_lshlrev_b32_e32 v52, 16, v53
	v_and_b32_e32 v53, 0xffff0000, v53
	v_pk_fma_f32 v[66:67], v[58:59], v[58:59], v[72:73] op_sel_hi:[1,1,0]
	v_pk_add_f32 v[64:65], v[74:75], v[64:65]
	v_mul_f32_e32 v60, v50, v50
	v_pk_mul_f32 v[54:55], v[42:43], v[54:55] op_sel_hi:[0,1]
	v_pk_mul_f32 v[72:73], v[42:43], v[76:77] op_sel_hi:[0,1]
	v_pk_add_f32 v[64:65], v[64:65], v[64:65] op_sel_hi:[0,1]
	v_pk_fma_f32 v[70:71], v[50:51], v[50:51], v[60:61] op_sel_hi:[1,1,0]
	v_pk_fma_f32 v[68:69], v[24:25], v[72:73], v[68:69]
	v_pk_fma_f32 v[52:53], v[26:27], v[54:55], v[52:53]
	v_mul_f32_e32 v66, v68, v68
	v_mul_f32_e32 v70, v69, v69
	v_mul_f32_e32 v64, v52, v52
	v_mul_f32_e32 v60, v53, v53
	v_pk_add_f32 v[54:55], v[66:67], v[70:71]
	v_pk_add_f32 v[60:61], v[64:65], v[60:61]
	v_cvt_pk_bf16_f32 v66, v56, v57
	v_lshl_add_u64 v[64:65], v[44:45], 0, s[54:55]
	v_pk_add_f32 v[54:55], v[54:55], v[60:61]
	s_nop 0
	v_add_f32_e32 v42, v54, v55
	s_nop 1
	v_mov_b32_dpp v54, v42 quad_perm:[1,0,3,2] row_mask:0xf bank_mask:0xf
	s_waitcnt lgkmcnt(0)
	v_add_f32_e32 v42, v42, v54
	s_nop 1
	v_mov_b32_dpp v54, v42 quad_perm:[2,3,0,1] row_mask:0xf bank_mask:0xf
	s_waitcnt lgkmcnt(0)
	v_add_f32_e32 v42, v42, v54
	s_nop 1
	v_mov_b32_dpp v60, v42 row_half_mirror row_mask:0xf bank_mask:0xf
	v_lshl_add_u64 v[54:55], v[44:45], 0, s[40:41]
	s_waitcnt lgkmcnt(0)
	v_add_f32_e32 v42, v42, v60
	s_nop 1
	v_mov_b32_dpp v67, v42 row_mirror row_mask:0xf bank_mask:0xf
	v_lshl_add_u64 v[60:61], v[44:45], 0, s[52:53]
	v_lshl_add_u64 v[44:45], v[44:45], 0, s[56:57]
	s_waitcnt lgkmcnt(0)
	v_add_f32_e32 v42, v42, v67
	v_mov_b32_e32 v70, v42
	s_nop 1
	v_permlane16_swap_b32 v42, v70
	v_cvt_pk_bf16_f32 v67, v46, v47
	s_waitcnt lgkmcnt(0)
	v_add_f32_e32 v42, v42, v70
	v_mov_b32_e32 v208, v66
	v_mov_b32_e32 v209, v67
	s_nop 1
	v_mov_b32_e32 v66, v42
	s_nop 1
	v_permlane32_swap_b32 v42, v66
	v_cvt_pk_bf16_f32 v54, v62, v63
	v_cvt_pk_bf16_f32 v55, v48, v49
	s_waitcnt lgkmcnt(0)
	v_add_f32_e32 v42, v42, v66
	v_mov_b32_e32 v210, v54
	v_mov_b32_e32 v211, v55
	s_nop 1
	v_cvt_pk_bf16_f32 v54, v58, v59
	v_fmamk_f32 v42, v42, 0x3a800000, v90
	v_cvt_pk_bf16_f32 v55, v50, v51
	v_cmp_gt_f32_e32 vcc, s91, v42
	v_mov_b32_e32 v212, v54
	v_mov_b32_e32 v213, v55
	s_nop 1
	v_mul_f32_e32 v54, 0x4b800000, v42
	s_nop 0
	v_cndmask_b32_e32 v42, v42, v54, vcc
	v_rsq_f32_e32 v42, v42
	v_cvt_pk_bf16_f32 v54, v68, v69
	v_cvt_pk_bf16_f32 v55, v52, v53
	s_nop 0
	v_and_b32_e32 v232, 1, v152
	v_cmp_eq_u32_e64 s[98:99], 1, v232
	v_mul_u32_u24_e32 v230, 0x1f8, v232
	v_mov_b32_e32 v231, 0
	v_lshl_add_u64 v[228:229], v[44:45], 0, v[230:231]
	v_cndmask_b32_e64 v216, v210, v208, s[98:99]
	v_cndmask_b32_e64 v217, v211, v209, s[98:99]
	s_nop 1
	v_mov_b32_dpp v218, v216 quad_perm:[1,0,3,2] row_mask:0xf bank_mask:0xf
	v_mov_b32_dpp v219, v217 quad_perm:[1,0,3,2] row_mask:0xf bank_mask:0xf
	v_cndmask_b32_e64 v220, v208, v218, s[98:99]
	v_cndmask_b32_e64 v221, v209, v219, s[98:99]
	v_cndmask_b32_e64 v222, v218, v210, s[98:99]
	v_cndmask_b32_e64 v223, v219, v211, s[98:99]
	global_store_dwordx4 v[228:229], v[220:223], off offset:-1536 sc0 sc1
	s_nop 1
	v_cndmask_b32_e64 v216, v54, v212, s[98:99]
	v_cndmask_b32_e64 v217, v55, v213, s[98:99]
	s_nop 1
	v_mov_b32_dpp v218, v216 quad_perm:[1,0,3,2] row_mask:0xf bank_mask:0xf
	v_mov_b32_dpp v219, v217 quad_perm:[1,0,3,2] row_mask:0xf bank_mask:0xf
	v_cndmask_b32_e64 v224, v212, v218, s[98:99]
	v_cndmask_b32_e64 v225, v213, v219, s[98:99]
	v_cndmask_b32_e64 v226, v218, v54, s[98:99]
	v_cndmask_b32_e64 v227, v219, v55, s[98:99]
	global_store_dwordx4 v[228:229], v[224:227], off offset:-512 sc0 sc1
	s_nop 1
	s_mov_b32 s99, 0
	s_nop 1
	v_mul_f32_e32 v44, 0x45800000, v42
	v_cndmask_b32_e32 v42, v42, v44, vcc
	v_pk_mul_f32 v[54:55], v[56:57], v[42:43] op_sel_hi:[1,0]
	v_pk_mul_f32 v[46:47], v[46:47], v[42:43] op_sel_hi:[1,0]
	v_pk_mul_f32 v[54:55], v[4:5], v[54:55]
	v_pk_mul_f32 v[46:47], v[6:7], v[46:47]
	v_cvt_pk_bf16_f32 v54, v54, v55
	v_pk_mul_f32 v[48:49], v[48:49], v[42:43] op_sel_hi:[1,0]
	v_cvt_pk_bf16_f32 v55, v46, v47
	v_pk_mul_f32 v[46:47], v[62:63], v[42:43] op_sel_hi:[1,0]
	v_lshl_add_u64 v[44:45], v[36:37], 0, s[0:1]
	v_pk_mul_f32 v[46:47], v[16:17], v[46:47]
	v_mov_b32_e32 v208, v54
	v_mov_b32_e32 v209, v55
	s_nop 1
	v_pk_mul_f32 v[48:49], v[18:19], v[48:49]
	v_cvt_pk_bf16_f32 v46, v46, v47
	s_andn2_b64 vcc, exec, s[6:7]
	v_cvt_pk_bf16_f32 v47, v48, v49
	v_lshl_add_u64 v[48:49], v[44:45], 0, s[58:59]
	v_mov_b32_e32 v210, v46
	v_mov_b32_e32 v211, v47
	s_nop 1
	v_pk_mul_f32 v[46:47], v[58:59], v[42:43] op_sel_hi:[1,0]
	v_pk_mul_f32 v[48:49], v[50:51], v[42:43] op_sel_hi:[1,0]
	v_pk_mul_f32 v[46:47], v[20:21], v[46:47]
	v_pk_mul_f32 v[48:49], v[22:23], v[48:49]
	v_cvt_pk_bf16_f32 v46, v46, v47
	s_nop 0
	v_cvt_pk_bf16_f32 v47, v48, v49
	v_lshl_add_u64 v[48:49], v[44:45], 0, s[60:61]
	v_mov_b32_e32 v212, v46
	v_mov_b32_e32 v213, v47
	s_nop 1
	v_pk_mul_f32 v[46:47], v[68:69], v[42:43] op_sel_hi:[1,0]
	v_pk_mul_f32 v[48:49], v[52:53], v[42:43] op_sel_hi:[1,0]
	v_pk_mul_f32 v[46:47], v[28:29], v[46:47]
	v_pk_mul_f32 v[48:49], v[30:31], v[48:49]
	v_cvt_pk_bf16_f32 v46, v46, v47
	v_lshl_add_u64 v[44:45], v[44:45], 0, s[62:63]
	v_cvt_pk_bf16_f32 v47, v48, v49
	v_cndmask_b32_e64 v42, 0, 1, s[6:7]
	v_and_b32_e32 v232, 1, v152
	v_cmp_eq_u32_e64 s[98:99], 1, v232
	v_mul_u32_u24_e32 v230, 0x1f8, v232
	v_mov_b32_e32 v231, 0
	v_lshl_add_u64 v[228:229], v[44:45], 0, v[230:231]
	v_cndmask_b32_e64 v216, v210, v208, s[98:99]
	v_cndmask_b32_e64 v217, v211, v209, s[98:99]
	s_nop 1
	v_mov_b32_dpp v218, v216 quad_perm:[1,0,3,2] row_mask:0xf bank_mask:0xf
	v_mov_b32_dpp v219, v217 quad_perm:[1,0,3,2] row_mask:0xf bank_mask:0xf
	v_cndmask_b32_e64 v220, v208, v218, s[98:99]
	v_cndmask_b32_e64 v221, v209, v219, s[98:99]
	v_cndmask_b32_e64 v222, v218, v210, s[98:99]
	v_cndmask_b32_e64 v223, v219, v211, s[98:99]
	global_store_dwordx4 v[228:229], v[220:223], off offset:-1536 sc0 sc1
	s_nop 1
	v_cndmask_b32_e64 v216, v46, v212, s[98:99]
	v_cndmask_b32_e64 v217, v47, v213, s[98:99]
	s_nop 1
	v_mov_b32_dpp v218, v216 quad_perm:[1,0,3,2] row_mask:0xf bank_mask:0xf
	v_mov_b32_dpp v219, v217 quad_perm:[1,0,3,2] row_mask:0xf bank_mask:0xf
	v_cndmask_b32_e64 v224, v212, v218, s[98:99]
	v_cndmask_b32_e64 v225, v213, v219, s[98:99]
	v_cndmask_b32_e64 v226, v218, v46, s[98:99]
	v_cndmask_b32_e64 v227, v219, v47, s[98:99]
	global_store_dwordx4 v[228:229], v[224:227], off offset:-512 sc0 sc1
	s_nop 1
	s_mov_b32 s99, 0
	s_nop 1
	v_cmp_ne_u32_e64 s[0:1], 1, v42
	s_cbranch_vccnz .LBB0_2036
	s_add_i32 s14, s64, 0xffffbf81
	s_mov_b64 s[10:11], 0
	s_mov_b64 s[6:7], s[14:15]

.LBB0_2043:
	s_or_b64 exec, exec, s[38:39]
	s_lshl_b64 s[6:7], s[6:7], 12
	s_add_u32 s6, s10, s6
	s_addc_u32 s7, s11, s7
	v_lshl_add_u64 v[44:45], v[32:33], 3, s[6:7]
	s_lshl_b64 s[6:7], s[14:15], 11
	v_lshl_add_u64 v[54:55], v[38:39], 0, s[6:7]
	global_load_dwordx2 v[46:47], v[44:45], off offset:2048
	global_load_dwordx2 v[48:49], v[44:45], off offset:2560
	global_load_dwordx2 v[50:51], v[44:45], off offset:3072
	global_load_dwordx2 v[52:53], v[44:45], off offset:3584
	global_load_dwordx2 v[56:57], v[54:55], off
	global_load_dwordx2 v[58:59], v[54:55], off offset:512
	global_load_dwordx2 v[60:61], v[54:55], off offset:1024
	s_nop 0
	global_load_dwordx2 v[54:55], v[54:55], off offset:1536
	s_waitcnt vmcnt(8)
	s_nop 1
	v_mov_b32_dpp v62, v42 quad_perm:[1,0,3,2] row_mask:0xf bank_mask:0xf
	s_mov_b64 s[10:11], -1
	s_waitcnt lgkmcnt(0)
	v_add_f32_e32 v42, v42, v62
	s_nop 1
	v_mov_b32_dpp v62, v42 quad_perm:[2,3,0,1] row_mask:0xf bank_mask:0xf
	s_waitcnt lgkmcnt(0)
	v_add_f32_e32 v42, v42, v62
	s_nop 1
	v_mov_b32_dpp v62, v42 row_half_mirror row_mask:0xf bank_mask:0xf
	s_waitcnt lgkmcnt(0)
	v_add_f32_e32 v42, v42, v62
	s_nop 1
	v_mov_b32_dpp v62, v42 row_mirror row_mask:0xf bank_mask:0xf
	s_waitcnt lgkmcnt(0)
	v_add_f32_e32 v42, v42, v62
	v_mov_b32_e32 v62, v42
	s_nop 1
	v_permlane16_swap_b32 v42, v62
	s_waitcnt lgkmcnt(0)
	v_add_f32_e32 v42, v42, v62
	v_mov_b32_e32 v62, v42
	s_nop 1
	v_permlane32_swap_b32 v42, v62
	s_waitcnt lgkmcnt(0)
	v_add_f32_e32 v42, v42, v62
	v_fmamk_f32 v42, v42, 0x3a800000, v90
	v_mul_f32_e32 v62, 0x4b800000, v42
	v_cmp_gt_f32_e32 vcc, s91, v42
	s_waitcnt vmcnt(7)
	v_and_b32_e32 v63, 0xffff0000, v46
	v_cndmask_b32_e32 v42, v42, v62, vcc
	v_rsq_f32_e32 v42, v42
	s_waitcnt vmcnt(3)
	v_lshlrev_b32_e32 v70, 16, v56
	v_and_b32_e32 v71, 0xffff0000, v56
	v_lshlrev_b32_e32 v56, 16, v57
	v_mul_f32_e32 v62, 0x45800000, v42
	v_cndmask_b32_e32 v42, v42, v62, vcc
	v_and_b32_e32 v57, 0xffff0000, v57
	s_waitcnt vmcnt(2)
	v_lshlrev_b32_e32 v72, 16, v58
	v_and_b32_e32 v73, 0xffff0000, v58
	v_lshlrev_b32_e32 v58, 16, v59
	v_and_b32_e32 v59, 0xffff0000, v59
	v_lshlrev_b32_e32 v62, 16, v46
	v_lshlrev_b32_e32 v46, 16, v47
	v_and_b32_e32 v47, 0xffff0000, v47
	v_lshlrev_b32_e32 v64, 16, v48
	v_and_b32_e32 v65, 0xffff0000, v48
	v_lshlrev_b32_e32 v48, 16, v49
	v_and_b32_e32 v49, 0xffff0000, v49
	s_waitcnt vmcnt(1)
	v_lshlrev_b32_e32 v74, 16, v60
	v_and_b32_e32 v75, 0xffff0000, v60
	v_lshlrev_b32_e32 v60, 16, v61
	v_and_b32_e32 v61, 0xffff0000, v61
	v_pk_mul_f32 v[70:71], v[42:43], v[70:71] op_sel_hi:[0,1]
	v_pk_mul_f32 v[56:57], v[42:43], v[56:57] op_sel_hi:[0,1]
	v_pk_mul_f32 v[58:59], v[42:43], v[58:59] op_sel_hi:[0,1]
	v_pk_mul_f32 v[72:73], v[42:43], v[72:73] op_sel_hi:[0,1]
	v_lshlrev_b32_e32 v66, 16, v50
	v_and_b32_e32 v67, 0xffff0000, v50
	v_lshlrev_b32_e32 v50, 16, v51
	v_and_b32_e32 v51, 0xffff0000, v51
	v_pk_mul_f32 v[60:61], v[42:43], v[60:61] op_sel_hi:[0,1]
	v_pk_mul_f32 v[74:75], v[42:43], v[74:75] op_sel_hi:[0,1]
	v_pk_fma_f32 v[46:47], v[2:3], v[56:57], v[46:47]
	v_pk_fma_f32 v[56:57], v[0:1], v[70:71], v[62:63]
	v_pk_fma_f32 v[62:63], v[8:9], v[72:73], v[64:65]
	v_pk_fma_f32 v[48:49], v[10:11], v[58:59], v[48:49]
	v_pk_fma_f32 v[58:59], v[12:13], v[74:75], v[66:67]
	v_pk_fma_f32 v[50:51], v[14:15], v[60:61], v[50:51]
	v_pk_mul_f32 v[60:61], v[46:47], v[46:47]
	v_pk_mul_f32 v[64:65], v[56:57], v[56:57]
	v_pk_mul_f32 v[66:67], v[48:49], v[48:49]
	v_pk_mul_f32 v[70:71], v[62:63], v[62:63]
	v_pk_mov_b32 v[74:75], v[64:65], v[60:61] op_sel:[1,0]
	v_mov_b32_e32 v65, v61
	v_pk_mov_b32 v[60:61], v[70:71], v[66:67] op_sel:[1,0]
	v_mov_b32_e32 v71, v67
	v_pk_add_f32 v[60:61], v[60:61], v[70:71]
	s_waitcnt vmcnt(0)
	v_lshlrev_b32_e32 v76, 16, v54
	v_and_b32_e32 v77, 0xffff0000, v54
	v_lshlrev_b32_e32 v54, 16, v55
	v_and_b32_e32 v55, 0xffff0000, v55
	v_mul_f32_e32 v72, v58, v58
	v_pk_add_f32 v[60:61], v[60:61], v[60:61] op_sel_hi:[0,1]
	v_lshlrev_b32_e32 v68, 16, v52
	v_and_b32_e32 v69, 0xffff0000, v52
	v_lshlrev_b32_e32 v52, 16, v53
	v_and_b32_e32 v53, 0xffff0000, v53
	v_pk_fma_f32 v[66:67], v[58:59], v[58:59], v[72:73] op_sel_hi:[1,1,0]
	v_pk_add_f32 v[64:65], v[74:75], v[64:65]
	v_mul_f32_e32 v60, v50, v50
	v_pk_mul_f32 v[54:55], v[42:43], v[54:55] op_sel_hi:[0,1]
	v_pk_mul_f32 v[72:73], v[42:43], v[76:77] op_sel_hi:[0,1]
	v_pk_add_f32 v[64:65], v[64:65], v[64:65] op_sel_hi:[0,1]
	v_pk_fma_f32 v[70:71], v[50:51], v[50:51], v[60:61] op_sel_hi:[1,1,0]
	v_pk_fma_f32 v[68:69], v[24:25], v[72:73], v[68:69]
	v_pk_fma_f32 v[52:53], v[26:27], v[54:55], v[52:53]
	v_mul_f32_e32 v66, v68, v68
	v_mul_f32_e32 v70, v69, v69
	v_mul_f32_e32 v64, v52, v52
	v_mul_f32_e32 v60, v53, v53
	v_pk_add_f32 v[54:55], v[66:67], v[70:71]
	v_pk_add_f32 v[60:61], v[64:65], v[60:61]
	v_cvt_pk_bf16_f32 v66, v56, v57
	v_lshl_add_u64 v[64:65], v[44:45], 0, s[54:55]
	v_pk_add_f32 v[54:55], v[54:55], v[60:61]
	s_nop 0
	v_add_f32_e32 v42, v54, v55
	s_nop 1
	v_mov_b32_dpp v54, v42 quad_perm:[1,0,3,2] row_mask:0xf bank_mask:0xf
	s_waitcnt lgkmcnt(0)
	v_add_f32_e32 v42, v42, v54
	s_nop 1
	v_mov_b32_dpp v54, v42 quad_perm:[2,3,0,1] row_mask:0xf bank_mask:0xf
	s_waitcnt lgkmcnt(0)
	v_add_f32_e32 v42, v42, v54
	s_nop 1
	v_mov_b32_dpp v60, v42 row_half_mirror row_mask:0xf bank_mask:0xf
	v_lshl_add_u64 v[54:55], v[44:45], 0, s[40:41]
	s_waitcnt lgkmcnt(0)
	v_add_f32_e32 v42, v42, v60
	s_nop 1
	v_mov_b32_dpp v67, v42 row_mirror row_mask:0xf bank_mask:0xf
	v_lshl_add_u64 v[60:61], v[44:45], 0, s[52:53]
	v_lshl_add_u64 v[44:45], v[44:45], 0, s[56:57]
	s_waitcnt lgkmcnt(0)
	v_add_f32_e32 v42, v42, v67
	v_mov_b32_e32 v70, v42
	s_nop 1
	v_permlane16_swap_b32 v42, v70
	v_cvt_pk_bf16_f32 v67, v46, v47
	s_waitcnt lgkmcnt(0)
	v_add_f32_e32 v42, v42, v70
	v_mov_b32_e32 v208, v66
	v_mov_b32_e32 v209, v67
	s_nop 1
	v_mov_b32_e32 v66, v42
	s_nop 1
	v_permlane32_swap_b32 v42, v66
	v_cvt_pk_bf16_f32 v54, v62, v63
	v_cvt_pk_bf16_f32 v55, v48, v49
	s_waitcnt lgkmcnt(0)
	v_add_f32_e32 v42, v42, v66
	v_mov_b32_e32 v210, v54
	v_mov_b32_e32 v211, v55
	s_nop 1
	v_cvt_pk_bf16_f32 v54, v58, v59
	v_fmamk_f32 v42, v42, 0x3a800000, v90
	v_cvt_pk_bf16_f32 v55, v50, v51
	v_cmp_gt_f32_e32 vcc, s91, v42
	v_mov_b32_e32 v212, v54
	v_mov_b32_e32 v213, v55
	s_nop 1
	v_mul_f32_e32 v54, 0x4b800000, v42
	s_nop 0
	v_cndmask_b32_e32 v42, v42, v54, vcc
	v_rsq_f32_e32 v42, v42
	v_cvt_pk_bf16_f32 v54, v68, v69
	v_cvt_pk_bf16_f32 v55, v52, v53
	s_nop 0
	v_and_b32_e32 v232, 1, v152
	v_cmp_eq_u32_e64 s[98:99], 1, v232
	v_mul_u32_u24_e32 v230, 0x1f8, v232
	v_mov_b32_e32 v231, 0
	v_lshl_add_u64 v[228:229], v[44:45], 0, v[230:231]
	v_cndmask_b32_e64 v216, v210, v208, s[98:99]
	v_cndmask_b32_e64 v217, v211, v209, s[98:99]
	s_nop 1
	v_mov_b32_dpp v218, v216 quad_perm:[1,0,3,2] row_mask:0xf bank_mask:0xf
	v_mov_b32_dpp v219, v217 quad_perm:[1,0,3,2] row_mask:0xf bank_mask:0xf
	v_cndmask_b32_e64 v220, v208, v218, s[98:99]
	v_cndmask_b32_e64 v221, v209, v219, s[98:99]
	v_cndmask_b32_e64 v222, v218, v210, s[98:99]
	v_cndmask_b32_e64 v223, v219, v211, s[98:99]
	global_store_dwordx4 v[228:229], v[220:223], off offset:-1536 sc0 sc1
	s_nop 1
	v_cndmask_b32_e64 v216, v54, v212, s[98:99]
	v_cndmask_b32_e64 v217, v55, v213, s[98:99]
	s_nop 1
	v_mov_b32_dpp v218, v216 quad_perm:[1,0,3,2] row_mask:0xf bank_mask:0xf
	v_mov_b32_dpp v219, v217 quad_perm:[1,0,3,2] row_mask:0xf bank_mask:0xf
	v_cndmask_b32_e64 v224, v212, v218, s[98:99]
	v_cndmask_b32_e64 v225, v213, v219, s[98:99]
	v_cndmask_b32_e64 v226, v218, v54, s[98:99]
	v_cndmask_b32_e64 v227, v219, v55, s[98:99]
	global_store_dwordx4 v[228:229], v[224:227], off offset:-512 sc0 sc1
	s_nop 1
	s_mov_b32 s99, 0
	s_nop 1
	v_mul_f32_e32 v44, 0x45800000, v42
	v_cndmask_b32_e32 v42, v42, v44, vcc
	v_pk_mul_f32 v[54:55], v[56:57], v[42:43] op_sel_hi:[1,0]
	v_pk_mul_f32 v[46:47], v[46:47], v[42:43] op_sel_hi:[1,0]
	v_pk_mul_f32 v[54:55], v[4:5], v[54:55]
	v_pk_mul_f32 v[46:47], v[6:7], v[46:47]
	v_cvt_pk_bf16_f32 v54, v54, v55
	v_pk_mul_f32 v[48:49], v[48:49], v[42:43] op_sel_hi:[1,0]
	v_cvt_pk_bf16_f32 v55, v46, v47
	v_pk_mul_f32 v[46:47], v[62:63], v[42:43] op_sel_hi:[1,0]
	v_lshl_add_u64 v[44:45], v[36:37], 0, s[6:7]
	v_pk_mul_f32 v[46:47], v[16:17], v[46:47]
	v_mov_b32_e32 v208, v54
	v_mov_b32_e32 v209, v55
	s_nop 1
	v_pk_mul_f32 v[48:49], v[18:19], v[48:49]
	v_cvt_pk_bf16_f32 v46, v46, v47
	s_and_b64 vcc, exec, s[0:1]
	v_cvt_pk_bf16_f32 v47, v48, v49
	v_lshl_add_u64 v[48:49], v[44:45], 0, s[58:59]
	v_mov_b32_e32 v210, v46
	v_mov_b32_e32 v211, v47
	s_nop 1
	v_pk_mul_f32 v[46:47], v[58:59], v[42:43] op_sel_hi:[1,0]
	v_pk_mul_f32 v[48:49], v[50:51], v[42:43] op_sel_hi:[1,0]
	v_pk_mul_f32 v[46:47], v[20:21], v[46:47]
	v_pk_mul_f32 v[48:49], v[22:23], v[48:49]
	v_cvt_pk_bf16_f32 v46, v46, v47
	s_nop 0
	v_cvt_pk_bf16_f32 v47, v48, v49
	v_lshl_add_u64 v[48:49], v[44:45], 0, s[60:61]
	v_mov_b32_e32 v212, v46
	v_mov_b32_e32 v213, v47
	s_nop 1
	v_pk_mul_f32 v[46:47], v[68:69], v[42:43] op_sel_hi:[1,0]
	v_pk_mul_f32 v[48:49], v[52:53], v[42:43] op_sel_hi:[1,0]
	v_pk_mul_f32 v[46:47], v[28:29], v[46:47]
	v_pk_mul_f32 v[48:49], v[30:31], v[48:49]
	v_cvt_pk_bf16_f32 v46, v46, v47
	v_lshl_add_u64 v[44:45], v[44:45], 0, s[62:63]
	v_cvt_pk_bf16_f32 v47, v48, v49
	s_nop 0
	v_and_b32_e32 v232, 1, v152
	v_cmp_eq_u32_e64 s[98:99], 1, v232
	v_mul_u32_u24_e32 v230, 0x1f8, v232
	v_mov_b32_e32 v231, 0
	v_lshl_add_u64 v[228:229], v[44:45], 0, v[230:231]
	v_cndmask_b32_e64 v216, v210, v208, s[98:99]
	v_cndmask_b32_e64 v217, v211, v209, s[98:99]
	s_nop 1
	v_mov_b32_dpp v218, v216 quad_perm:[1,0,3,2] row_mask:0xf bank_mask:0xf
	v_mov_b32_dpp v219, v217 quad_perm:[1,0,3,2] row_mask:0xf bank_mask:0xf
	v_cndmask_b32_e64 v220, v208, v218, s[98:99]
	v_cndmask_b32_e64 v221, v209, v219, s[98:99]
	v_cndmask_b32_e64 v222, v218, v210, s[98:99]
	v_cndmask_b32_e64 v223, v219, v211, s[98:99]
	global_store_dwordx4 v[228:229], v[220:223], off offset:-1536 sc0 sc1
	s_nop 1
	v_cndmask_b32_e64 v216, v46, v212, s[98:99]
	v_cndmask_b32_e64 v217, v47, v213, s[98:99]
	s_nop 1
	v_mov_b32_dpp v218, v216 quad_perm:[1,0,3,2] row_mask:0xf bank_mask:0xf
	v_mov_b32_dpp v219, v217 quad_perm:[1,0,3,2] row_mask:0xf bank_mask:0xf
	v_cndmask_b32_e64 v224, v212, v218, s[98:99]
	v_cndmask_b32_e64 v225, v213, v219, s[98:99]
	v_cndmask_b32_e64 v226, v218, v46, s[98:99]
	v_cndmask_b32_e64 v227, v219, v47, s[98:99]
	global_store_dwordx4 v[228:229], v[224:227], off offset:-512 sc0 sc1
	s_nop 1
	s_mov_b32 s99, 0
	s_nop 1
	s_cbranch_vccnz .LBB0_2045
	s_add_i32 s14, s64, 0xffffbf82
	s_mov_b64 s[10:11], 0
	s_mov_b64 s[6:7], s[14:15]

.LBB0_2052:
	s_or_b64 exec, exec, s[38:39]
	s_lshl_b64 s[6:7], s[6:7], 12
	s_add_u32 s6, s10, s6
	s_addc_u32 s7, s11, s7
	v_lshl_add_u64 v[44:45], v[32:33], 3, s[6:7]
	s_lshl_b64 s[6:7], s[14:15], 11
	v_lshl_add_u64 v[54:55], v[38:39], 0, s[6:7]
	global_load_dwordx2 v[46:47], v[44:45], off offset:2048
	global_load_dwordx2 v[48:49], v[44:45], off offset:2560
	global_load_dwordx2 v[50:51], v[44:45], off offset:3072
	global_load_dwordx2 v[52:53], v[44:45], off offset:3584
	global_load_dwordx2 v[56:57], v[54:55], off
	global_load_dwordx2 v[58:59], v[54:55], off offset:512
	global_load_dwordx2 v[60:61], v[54:55], off offset:1024
	s_nop 0
	global_load_dwordx2 v[54:55], v[54:55], off offset:1536
	s_waitcnt vmcnt(8)
	s_nop 1
	v_mov_b32_dpp v62, v42 quad_perm:[1,0,3,2] row_mask:0xf bank_mask:0xf
	s_waitcnt lgkmcnt(0)
	v_add_f32_e32 v42, v42, v62
	s_nop 1
	v_mov_b32_dpp v62, v42 quad_perm:[2,3,0,1] row_mask:0xf bank_mask:0xf
	s_waitcnt lgkmcnt(0)
	v_add_f32_e32 v42, v42, v62
	s_nop 1
	v_mov_b32_dpp v62, v42 row_half_mirror row_mask:0xf bank_mask:0xf
	s_waitcnt lgkmcnt(0)
	v_add_f32_e32 v42, v42, v62
	s_nop 1
	v_mov_b32_dpp v62, v42 row_mirror row_mask:0xf bank_mask:0xf
	s_waitcnt lgkmcnt(0)
	v_add_f32_e32 v42, v42, v62
	v_mov_b32_e32 v62, v42
	s_nop 1
	v_permlane16_swap_b32 v42, v62
	s_waitcnt lgkmcnt(0)
	v_add_f32_e32 v42, v42, v62
	v_mov_b32_e32 v62, v42
	s_nop 1
	v_permlane32_swap_b32 v42, v62
	s_waitcnt lgkmcnt(0)
	v_add_f32_e32 v42, v42, v62
	v_fmamk_f32 v42, v42, 0x3a800000, v90
	v_mul_f32_e32 v62, 0x4b800000, v42
	v_cmp_gt_f32_e32 vcc, s91, v42
	s_waitcnt vmcnt(7)
	v_and_b32_e32 v63, 0xffff0000, v46
	v_cndmask_b32_e32 v42, v42, v62, vcc
	v_rsq_f32_e32 v42, v42
	s_waitcnt vmcnt(3)
	v_lshlrev_b32_e32 v70, 16, v56
	v_and_b32_e32 v71, 0xffff0000, v56
	v_lshlrev_b32_e32 v56, 16, v57
	v_mul_f32_e32 v62, 0x45800000, v42
	v_cndmask_b32_e32 v42, v42, v62, vcc
	v_and_b32_e32 v57, 0xffff0000, v57
	s_waitcnt vmcnt(2)
	v_lshlrev_b32_e32 v72, 16, v58
	v_and_b32_e32 v73, 0xffff0000, v58
	v_lshlrev_b32_e32 v58, 16, v59
	v_and_b32_e32 v59, 0xffff0000, v59
	v_lshlrev_b32_e32 v62, 16, v46
	v_lshlrev_b32_e32 v46, 16, v47
	v_and_b32_e32 v47, 0xffff0000, v47
	v_lshlrev_b32_e32 v64, 16, v48
	v_and_b32_e32 v65, 0xffff0000, v48
	v_lshlrev_b32_e32 v48, 16, v49
	v_and_b32_e32 v49, 0xffff0000, v49
	s_waitcnt vmcnt(1)
	v_lshlrev_b32_e32 v74, 16, v60
	v_and_b32_e32 v75, 0xffff0000, v60
	v_lshlrev_b32_e32 v60, 16, v61
	v_and_b32_e32 v61, 0xffff0000, v61
	v_pk_mul_f32 v[70:71], v[42:43], v[70:71] op_sel_hi:[0,1]
	v_pk_mul_f32 v[56:57], v[42:43], v[56:57] op_sel_hi:[0,1]
	v_pk_mul_f32 v[58:59], v[42:43], v[58:59] op_sel_hi:[0,1]
	v_pk_mul_f32 v[72:73], v[42:43], v[72:73] op_sel_hi:[0,1]
	v_lshlrev_b32_e32 v66, 16, v50
	v_and_b32_e32 v67, 0xffff0000, v50
	v_lshlrev_b32_e32 v50, 16, v51
	v_and_b32_e32 v51, 0xffff0000, v51
	v_pk_mul_f32 v[60:61], v[42:43], v[60:61] op_sel_hi:[0,1]
	v_pk_mul_f32 v[74:75], v[42:43], v[74:75] op_sel_hi:[0,1]
	v_pk_fma_f32 v[46:47], v[2:3], v[56:57], v[46:47]
	v_pk_fma_f32 v[56:57], v[0:1], v[70:71], v[62:63]
	v_pk_fma_f32 v[62:63], v[8:9], v[72:73], v[64:65]
	v_pk_fma_f32 v[48:49], v[10:11], v[58:59], v[48:49]
	v_pk_fma_f32 v[58:59], v[12:13], v[74:75], v[66:67]
	v_pk_fma_f32 v[50:51], v[14:15], v[60:61], v[50:51]
	v_pk_mul_f32 v[60:61], v[46:47], v[46:47]
	v_pk_mul_f32 v[64:65], v[56:57], v[56:57]
	v_pk_mul_f32 v[66:67], v[48:49], v[48:49]
	v_pk_mul_f32 v[70:71], v[62:63], v[62:63]
	v_pk_mov_b32 v[74:75], v[64:65], v[60:61] op_sel:[1,0]
	v_mov_b32_e32 v65, v61
	v_pk_mov_b32 v[60:61], v[70:71], v[66:67] op_sel:[1,0]
	v_mov_b32_e32 v71, v67
	v_pk_add_f32 v[60:61], v[60:61], v[70:71]
	s_waitcnt vmcnt(0)
	v_lshlrev_b32_e32 v76, 16, v54
	v_and_b32_e32 v77, 0xffff0000, v54
	v_lshlrev_b32_e32 v54, 16, v55
	v_and_b32_e32 v55, 0xffff0000, v55
	v_mul_f32_e32 v72, v58, v58
	v_pk_add_f32 v[60:61], v[60:61], v[60:61] op_sel_hi:[0,1]
	v_lshlrev_b32_e32 v68, 16, v52
	v_and_b32_e32 v69, 0xffff0000, v52
	v_lshlrev_b32_e32 v52, 16, v53
	v_and_b32_e32 v53, 0xffff0000, v53
	v_pk_fma_f32 v[66:67], v[58:59], v[58:59], v[72:73] op_sel_hi:[1,1,0]
	v_pk_add_f32 v[64:65], v[74:75], v[64:65]
	v_mul_f32_e32 v60, v50, v50
	v_pk_mul_f32 v[54:55], v[42:43], v[54:55] op_sel_hi:[0,1]
	v_pk_mul_f32 v[72:73], v[42:43], v[76:77] op_sel_hi:[0,1]
	v_pk_add_f32 v[64:65], v[64:65], v[64:65] op_sel_hi:[0,1]
	v_pk_fma_f32 v[70:71], v[50:51], v[50:51], v[60:61] op_sel_hi:[1,1,0]
	v_pk_fma_f32 v[68:69], v[24:25], v[72:73], v[68:69]
	v_pk_fma_f32 v[52:53], v[26:27], v[54:55], v[52:53]
	v_mul_f32_e32 v66, v68, v68
	v_mul_f32_e32 v70, v69, v69
	v_mul_f32_e32 v64, v52, v52
	v_mul_f32_e32 v60, v53, v53
	v_pk_add_f32 v[54:55], v[66:67], v[70:71]
	v_pk_add_f32 v[60:61], v[64:65], v[60:61]
	v_cvt_pk_bf16_f32 v66, v56, v57
	v_lshl_add_u64 v[64:65], v[44:45], 0, s[54:55]
	v_pk_add_f32 v[54:55], v[54:55], v[60:61]
	s_nop 0
	v_add_f32_e32 v42, v54, v55
	s_nop 1
	v_mov_b32_dpp v54, v42 quad_perm:[1,0,3,2] row_mask:0xf bank_mask:0xf
	s_waitcnt lgkmcnt(0)
	v_add_f32_e32 v42, v42, v54
	s_nop 1
	v_mov_b32_dpp v54, v42 quad_perm:[2,3,0,1] row_mask:0xf bank_mask:0xf
	s_waitcnt lgkmcnt(0)
	v_add_f32_e32 v42, v42, v54
	s_nop 1
	v_mov_b32_dpp v60, v42 row_half_mirror row_mask:0xf bank_mask:0xf
	v_lshl_add_u64 v[54:55], v[44:45], 0, s[40:41]
	s_waitcnt lgkmcnt(0)
	v_add_f32_e32 v42, v42, v60
	s_nop 1
	v_mov_b32_dpp v67, v42 row_mirror row_mask:0xf bank_mask:0xf
	v_lshl_add_u64 v[60:61], v[44:45], 0, s[52:53]
	v_lshl_add_u64 v[44:45], v[44:45], 0, s[56:57]
	s_waitcnt lgkmcnt(0)
	v_add_f32_e32 v42, v42, v67
	v_mov_b32_e32 v70, v42
	s_nop 1
	v_permlane16_swap_b32 v42, v70
	v_cvt_pk_bf16_f32 v67, v46, v47
	s_waitcnt lgkmcnt(0)
	v_add_f32_e32 v42, v42, v70
	v_mov_b32_e32 v208, v66
	v_mov_b32_e32 v209, v67
	s_nop 1
	v_mov_b32_e32 v66, v42
	s_nop 1
	v_permlane32_swap_b32 v42, v66
	v_cvt_pk_bf16_f32 v54, v62, v63
	v_cvt_pk_bf16_f32 v55, v48, v49
	s_waitcnt lgkmcnt(0)
	v_add_f32_e32 v42, v42, v66
	v_mov_b32_e32 v210, v54
	v_mov_b32_e32 v211, v55
	s_nop 1
	v_cvt_pk_bf16_f32 v54, v58, v59
	v_fmamk_f32 v42, v42, 0x3a800000, v90
	v_cvt_pk_bf16_f32 v55, v50, v51
	v_cmp_gt_f32_e32 vcc, s91, v42
	v_mov_b32_e32 v212, v54
	v_mov_b32_e32 v213, v55
	s_nop 1
	v_mul_f32_e32 v54, 0x4b800000, v42
	s_nop 0
	v_cndmask_b32_e32 v42, v42, v54, vcc
	v_rsq_f32_e32 v42, v42
	v_cvt_pk_bf16_f32 v54, v68, v69
	v_cvt_pk_bf16_f32 v55, v52, v53
	s_nop 0
	v_and_b32_e32 v232, 1, v152
	v_cmp_eq_u32_e64 s[98:99], 1, v232
	v_mul_u32_u24_e32 v230, 0x1f8, v232
	v_mov_b32_e32 v231, 0
	v_lshl_add_u64 v[228:229], v[44:45], 0, v[230:231]
	v_cndmask_b32_e64 v216, v210, v208, s[98:99]
	v_cndmask_b32_e64 v217, v211, v209, s[98:99]
	s_nop 1
	v_mov_b32_dpp v218, v216 quad_perm:[1,0,3,2] row_mask:0xf bank_mask:0xf
	v_mov_b32_dpp v219, v217 quad_perm:[1,0,3,2] row_mask:0xf bank_mask:0xf
	v_cndmask_b32_e64 v220, v208, v218, s[98:99]
	v_cndmask_b32_e64 v221, v209, v219, s[98:99]
	v_cndmask_b32_e64 v222, v218, v210, s[98:99]
	v_cndmask_b32_e64 v223, v219, v211, s[98:99]
	global_store_dwordx4 v[228:229], v[220:223], off offset:-1536 sc0 sc1
	s_nop 1
	v_cndmask_b32_e64 v216, v54, v212, s[98:99]
	v_cndmask_b32_e64 v217, v55, v213, s[98:99]
	s_nop 1
	v_mov_b32_dpp v218, v216 quad_perm:[1,0,3,2] row_mask:0xf bank_mask:0xf
	v_mov_b32_dpp v219, v217 quad_perm:[1,0,3,2] row_mask:0xf bank_mask:0xf
	v_cndmask_b32_e64 v224, v212, v218, s[98:99]
	v_cndmask_b32_e64 v225, v213, v219, s[98:99]
	v_cndmask_b32_e64 v226, v218, v54, s[98:99]
	v_cndmask_b32_e64 v227, v219, v55, s[98:99]
	global_store_dwordx4 v[228:229], v[224:227], off offset:-512 sc0 sc1
	s_nop 1
	s_mov_b32 s99, 0
	s_nop 1
	v_mul_f32_e32 v44, 0x45800000, v42
	v_cndmask_b32_e32 v42, v42, v44, vcc
	v_pk_mul_f32 v[54:55], v[56:57], v[42:43] op_sel_hi:[1,0]
	v_pk_mul_f32 v[46:47], v[46:47], v[42:43] op_sel_hi:[1,0]
	v_pk_mul_f32 v[54:55], v[4:5], v[54:55]
	v_pk_mul_f32 v[46:47], v[6:7], v[46:47]
	v_cvt_pk_bf16_f32 v54, v54, v55
	v_pk_mul_f32 v[48:49], v[48:49], v[42:43] op_sel_hi:[1,0]
	v_cvt_pk_bf16_f32 v55, v46, v47
	v_pk_mul_f32 v[46:47], v[62:63], v[42:43] op_sel_hi:[1,0]
	v_lshl_add_u64 v[44:45], v[36:37], 0, s[6:7]
	v_pk_mul_f32 v[46:47], v[16:17], v[46:47]
	v_mov_b32_e32 v208, v54
	v_mov_b32_e32 v209, v55
	s_nop 1
	v_pk_mul_f32 v[48:49], v[18:19], v[48:49]
	v_cvt_pk_bf16_f32 v46, v46, v47
	s_and_b64 vcc, exec, s[0:1]
	v_cvt_pk_bf16_f32 v47, v48, v49
	v_lshl_add_u64 v[48:49], v[44:45], 0, s[58:59]
	v_mov_b32_e32 v210, v46
	v_mov_b32_e32 v211, v47
	s_nop 1
	v_pk_mul_f32 v[46:47], v[58:59], v[42:43] op_sel_hi:[1,0]
	v_pk_mul_f32 v[48:49], v[50:51], v[42:43] op_sel_hi:[1,0]
	v_pk_mul_f32 v[46:47], v[20:21], v[46:47]
	v_pk_mul_f32 v[48:49], v[22:23], v[48:49]
	v_cvt_pk_bf16_f32 v46, v46, v47
	s_mov_b64 s[6:7], -1
	v_cvt_pk_bf16_f32 v47, v48, v49
	v_lshl_add_u64 v[48:49], v[44:45], 0, s[60:61]
	v_mov_b32_e32 v212, v46
	v_mov_b32_e32 v213, v47
	s_nop 1
	v_pk_mul_f32 v[46:47], v[68:69], v[42:43] op_sel_hi:[1,0]
	v_pk_mul_f32 v[48:49], v[52:53], v[42:43] op_sel_hi:[1,0]
	v_pk_mul_f32 v[46:47], v[28:29], v[46:47]
	v_pk_mul_f32 v[48:49], v[30:31], v[48:49]
	v_cvt_pk_bf16_f32 v46, v46, v47
	v_lshl_add_u64 v[44:45], v[44:45], 0, s[62:63]
	v_cvt_pk_bf16_f32 v47, v48, v49
	s_nop 0
	v_and_b32_e32 v232, 1, v152
	v_cmp_eq_u32_e64 s[98:99], 1, v232
	v_mul_u32_u24_e32 v230, 0x1f8, v232
	v_mov_b32_e32 v231, 0
	v_lshl_add_u64 v[228:229], v[44:45], 0, v[230:231]
	v_cndmask_b32_e64 v216, v210, v208, s[98:99]
	v_cndmask_b32_e64 v217, v211, v209, s[98:99]
	s_nop 1
	v_mov_b32_dpp v218, v216 quad_perm:[1,0,3,2] row_mask:0xf bank_mask:0xf
	v_mov_b32_dpp v219, v217 quad_perm:[1,0,3,2] row_mask:0xf bank_mask:0xf
	v_cndmask_b32_e64 v220, v208, v218, s[98:99]
	v_cndmask_b32_e64 v221, v209, v219, s[98:99]
	v_cndmask_b32_e64 v222, v218, v210, s[98:99]
	v_cndmask_b32_e64 v223, v219, v211, s[98:99]
	global_store_dwordx4 v[228:229], v[220:223], off offset:-1536 sc0 sc1
	s_nop 1
	v_cndmask_b32_e64 v216, v46, v212, s[98:99]
	v_cndmask_b32_e64 v217, v47, v213, s[98:99]
	s_nop 1
	v_mov_b32_dpp v218, v216 quad_perm:[1,0,3,2] row_mask:0xf bank_mask:0xf
	v_mov_b32_dpp v219, v217 quad_perm:[1,0,3,2] row_mask:0xf bank_mask:0xf
	v_cndmask_b32_e64 v224, v212, v218, s[98:99]
	v_cndmask_b32_e64 v225, v213, v219, s[98:99]
	v_cndmask_b32_e64 v226, v218, v46, s[98:99]
	v_cndmask_b32_e64 v227, v219, v47, s[98:99]
	global_store_dwordx4 v[228:229], v[224:227], off offset:-512 sc0 sc1
	s_nop 1
	s_mov_b32 s99, 0
	s_nop 1
	s_cbranch_vccnz .LBB0_2054
	s_add_i32 s14, s64, 0xffffbf83
	s_mov_b64 s[6:7], 0
	s_mov_b64 s[0:1], s[14:15]
